# P7: stream w_down 2nd half through caches in epilogues of rounds 8-9 + hand-written idle-round w_down quantiser (in-register Hadamard, 3-deep loads)
# speedup vs baseline: 1.0091x; 1.0091x over previous
.LBB0_914:
	v_lshl_or_b32 v50, s12, 8, v161
	v_lshl_add_u32 v154, s64, 8, v1
	v_ashrrev_i32_e32 v51, 31, v50
	v_ashrrev_i32_e32 v155, 31, v154
	v_lshl_add_u64 v[50:51], v[50:51], 2, s[28:29]
	v_lshl_add_u64 v[176:177], v[154:155], 2, s[8:9]
	global_load_dwordx4 v[168:171], v[50:51], off offset:512
	global_load_dwordx4 v[62:65], v[50:51], off
	global_load_dwordx4 v[172:175], v[50:51], off offset:528
	s_nop 0
	global_load_dwordx4 v[50:53], v[50:51], off offset:16
	v_cvt_f32_i32_e32 v185, v134
	global_load_dword v180, v[176:177], off
	v_cvt_f32_i32_e32 v184, v130
	v_cvt_f32_i32_e32 v187, v135
	v_cvt_f32_i32_e32 v186, v131
	v_cvt_f32_i32_e32 v189, v136
	v_cvt_f32_i32_e32 v188, v132
	v_cvt_f32_i32_e32 v192, v122
	v_cvt_f32_i32_e32 v197, v128
	global_load_dword v164, v[176:177], off offset:64
	global_load_dword v162, v[176:177], off offset:128
	global_load_dword v160, v[176:177], off offset:192
	global_load_dword v158, v[176:177], off offset:512
	global_load_dword v136, v[176:177], off offset:576
	global_load_dword v128, v[176:177], off offset:640
	global_load_dword v122, v[176:177], off offset:704
	v_cvt_f32_i32_e32 v191, v137
	v_cvt_f32_i32_e32 v190, v133
	v_cvt_f32_i32_e32 v193, v126
	v_cvt_f32_i32_e32 v195, v127
	v_cvt_f32_i32_e32 v196, v124
	v_cvt_f32_i32_e32 v194, v123
	v_lshl_or_b32 v182, s12, 7, v161
	v_ashrrev_i32_e32 v183, 31, v182
	v_mov_b64_e32 v[156:157], s[10:11]
	v_mad_i64_i32 v[198:199], s[12:13], v154, s79, v[156:157]
	v_cvt_f32_i32_e32 v119, v119
	v_cvt_f32_i32_e32 v121, v121
	v_cvt_f32_i32_e32 v111, v111
	v_cvt_f32_i32_e32 v113, v113
	v_cvt_f32_i32_e32 v103, v103
	v_cvt_f32_i32_e32 v105, v105
	v_cvt_f32_i32_e32 v95, v95
	v_cvt_f32_i32_e32 v97, v97
	v_cvt_f32_i32_e32 v87, v87
	v_cvt_f32_i32_e32 v89, v89
	v_cvt_f32_i32_e32 v79, v79
	v_cvt_f32_i32_e32 v81, v81
	v_cvt_f32_i32_e32 v71, v71
	v_cvt_f32_i32_e32 v73, v73
	v_cvt_f32_i32_e32 v59, v59
	v_cvt_f32_i32_e32 v61, v61
	v_add_u32_e32 v123, 0x80, v154
	v_cvt_f32_i32_e32 v47, v47
	v_cvt_f32_i32_e32 v49, v49
	v_cvt_f32_i32_e32 v39, v39
	v_cvt_f32_i32_e32 v41, v41
	v_cvt_f32_i32_e32 v31, v31
	v_cvt_f32_i32_e32 v33, v33
	v_cvt_f32_i32_e32 v23, v23
	v_cvt_f32_i32_e32 v25, v25
	v_cvt_f32_i32_e32 v15, v15
	v_cvt_f32_i32_e32 v17, v17
	v_cvt_f32_i32_e32 v7, v7
	v_cvt_f32_i32_e32 v9, v9
	s_andn2_b64 vcc, exec, s[6:7]
	s_mov_b64 s[6:7], -1
	s_waitcnt vmcnt(0)
	s_sub_i32 s98, s73, 9
	s_cmp_gt_u32 s98, 1
	s_cbranch_scc1 .Lpf7_done
	s_lshl_b32 s98, s98, 8
	s_add_i32 s98, s98, s62
	s_lshl_b32 s98, s98, 3
	s_add_i32 s98, s98, s92
	s_mul_i32 s98, s98, 3
	v_lshlrev_b32_e32 v232, 7, v178
	s_cmpk_lt_u32 s98, 0x2b00
	s_cbranch_scc0 .Lpf7_done
	s_lshl_b32 s99, s98, 14
	s_add_u32 s99, s99, 0x2000
	s_add_u32 s100, s48, s99
	s_addc_u32 s101, s49, 0
	global_load_dword v233, v232, s[100:101]
	s_add_i32 s98, s98, 1
	s_cmpk_lt_u32 s98, 0x2b00
	s_cbranch_scc0 .Lpf7_done
	s_lshl_b32 s99, s98, 14
	s_add_u32 s99, s99, 0x2000
	s_add_u32 s100, s48, s99
	s_addc_u32 s101, s49, 0
	global_load_dword v234, v232, s[100:101]
	s_add_i32 s98, s98, 1
	s_cmpk_lt_u32 s98, 0x2b00
	s_cbranch_scc0 .Lpf7_done
	s_lshl_b32 s99, s98, 14
	s_add_u32 s99, s99, 0x2000
	s_add_u32 s100, s48, s99
	s_addc_u32 s101, s49, 0
	global_load_dword v235, v232, s[100:101]
	s_add_i32 s98, s98, 1
.Lpf7_done:
	v_mov_b32_e32 v134, v168
	v_mov_b32_e32 v135, v62
	v_mov_b32_e32 v62, v169
	v_mov_b32_e32 v132, v170
	v_mov_b32_e32 v133, v64
	v_mov_b32_e32 v64, v171
	v_pk_mul_f32 v[168:169], v[134:135], v[180:181] op_sel_hi:[1,0]
	v_pk_mul_f32 v[170:171], v[62:63], v[180:181] op_sel_hi:[1,0]
	v_mov_b32_e32 v130, v172
	v_mov_b32_e32 v131, v50
	v_mov_b32_e32 v50, v173
	v_pk_mul_f32 v[172:173], v[132:133], v[180:181] op_sel_hi:[1,0]
	v_pk_mul_f32 v[168:169], v[168:169], v[184:185]
	v_pk_mul_f32 v[170:171], v[170:171], v[186:187]
	v_mov_b32_e32 v127, v52
	v_pk_mul_f32 v[176:177], v[64:65], v[180:181] op_sel_hi:[1,0]
	v_pk_mul_f32 v[200:201], v[130:131], v[180:181] op_sel_hi:[1,0]
	v_pk_mul_f32 v[172:173], v[172:173], v[188:189]
	v_mul_f32_e32 v52, 0xbfb8aa3b, v169
	v_mul_f32_e32 v124, 0xbfb8aa3b, v171
	v_pk_mul_f32 v[176:177], v[176:177], v[190:191]
	v_pk_mul_f32 v[184:185], v[200:201], v[192:193]
	v_mul_f32_e32 v137, 0xbfb8aa3b, v173
	v_exp_f32_e32 v52, v52
	v_exp_f32_e32 v124, v124
	v_mul_f32_e32 v155, 0xbfb8aa3b, v177
	v_mul_f32_e32 v167, 0xbfb8aa3b, v185
	v_exp_f32_e32 v137, v137
	v_exp_f32_e32 v155, v155
	v_exp_f32_e32 v167, v167
	v_add_f32_e32 v52, 1.0, v52
	v_add_f32_e32 v124, 1.0, v124
	v_add_f32_e32 v137, 1.0, v137
	v_rcp_f32_e32 v52, v52
	v_rcp_f32_e32 v124, v124
	v_add_f32_e32 v155, 1.0, v155
	v_add_f32_e32 v167, 1.0, v167
	v_rcp_f32_e32 v137, v137
	v_rcp_f32_e32 v155, v155
	v_rcp_f32_e32 v167, v167
	v_mul_f32_e32 v169, v169, v52
	v_mul_f32_e32 v52, v171, v124
	v_mul_f32_e32 v137, v173, v137
	v_mul_f32_e32 v173, v170, v52
	v_cvt_f32_i32_e32 v171, v129
	v_cvt_f32_i32_e32 v170, v125
	v_mov_b32_e32 v126, v174
	v_mul_f32_e32 v124, v177, v155
	v_mul_f32_e32 v155, v185, v167
	v_pk_mul_f32 v[202:203], v[50:51], v[180:181] op_sel_hi:[1,0]
	v_pk_mul_f32 v[204:205], v[126:127], v[180:181] op_sel_hi:[1,0]
	v_mul_f32_e32 v181, v184, v155
	v_mov_b32_e32 v52, v175
	v_mul_f32_e32 v176, v176, v124
	v_pk_mul_f32 v[124:125], v[52:53], v[180:181] op_sel_hi:[1,0]
	v_pk_mul_f32 v[186:187], v[202:203], v[194:195]
	v_pk_mul_f32 v[188:189], v[204:205], v[196:197]
	v_pk_mul_f32 v[124:125], v[124:125], v[170:171]
	v_mul_f32_e32 v174, 0xbfb8aa3b, v187
	v_mul_f32_e32 v179, 0xbfb8aa3b, v189
	v_mul_f32_e32 v170, 0xbfb8aa3b, v125
	v_exp_f32_e32 v174, v174
	v_exp_f32_e32 v129, v179
	v_exp_f32_e32 v170, v170
	v_mul_f32_e32 v167, v168, v169
	v_add_f32_e32 v174, 1.0, v174
	v_add_f32_e32 v129, 1.0, v129
	v_add_f32_e32 v170, 1.0, v170
	v_rcp_f32_e32 v174, v174
	v_rcp_f32_e32 v129, v129
	v_rcp_f32_e32 v170, v170
	v_mul_f32_e32 v177, v172, v137
	v_mul_f32_e32 v171, v187, v174
	v_mul_f32_e32 v129, v189, v129
	v_mul_f32_e32 v125, v125, v170
	v_mul_f32_e32 v179, v186, v171
	v_mul_f32_e32 v180, v188, v129
	v_mul_f32_e32 v185, v124, v125
	v_add_f32_e32 v170, v167, v173
	v_fma_f32 v171, v168, v169, -v173
	v_add_f32_e32 v168, v177, v176
	v_fma_f32 v169, v172, v137, -v176
	v_add_f32_e32 v172, v181, v179
	v_fma_f32 v173, v184, v155, -v179
	v_add_f32_e32 v176, v180, v185
	v_fma_f32 v177, v188, v129, -v185
	v_lshlrev_b64 v[124:125], 1, v[182:183]
	v_pk_add_f32 v[180:181], v[170:171], v[168:169] neg_lo:[0,1] neg_hi:[0,1]
	v_pk_add_f32 v[182:183], v[172:173], v[176:177] neg_lo:[0,1] neg_hi:[0,1]
	v_pk_add_f32 v[168:169], v[170:171], v[168:169]
	v_pk_add_f32 v[184:185], v[180:181], v[182:183]
	v_pk_add_f32 v[180:181], v[180:181], v[182:183] neg_lo:[0,1] neg_hi:[0,1]
	v_mov_b32_e32 v129, v184
	v_mov_b32_e32 v137, v184
	s_nop 1
	v_permlane16_swap_b32_e32 v129, v137
	v_cndmask_b32_e64 v129, v129, v137, s[2:3]
	v_cndmask_b32_e64 v137, -v184, v184, s[2:3]
	v_add_f32_e32 v129, v137, v129
	v_mov_b32_e32 v137, v185
	v_mov_b32_e32 v155, v185
	s_nop 1
	v_permlane16_swap_b32_e32 v137, v155
	v_cndmask_b32_e64 v137, v137, v155, s[2:3]
	v_cndmask_b32_e64 v155, -v185, v185, s[2:3]
	v_add_f32_e32 v137, v155, v137
	v_mov_b32_e32 v155, v180
	v_mov_b32_e32 v167, v180
	v_mov_b32_e32 v179, v181
	v_mov_b32_e32 v182, v181
	v_permlane16_swap_b32_e32 v155, v167
	s_nop 0
	v_permlane16_swap_b32_e32 v179, v182
	v_cndmask_b32_e64 v183, v179, v182, s[2:3]
	v_cndmask_b32_e64 v182, v155, v167, s[2:3]
	v_mov_b32_e32 v155, v129
	v_mov_b32_e32 v167, v129
	s_nop 1
	v_permlane32_swap_b32_e32 v155, v167
	v_cndmask_b32_e64 v155, v155, v167, s[4:5]
	v_cndmask_b32_e64 v129, -v129, v129, s[4:5]
	v_add_f32_e32 v129, v129, v155
	v_mov_b32_e32 v155, v137
	v_mov_b32_e32 v167, v137
	s_nop 1
	v_permlane32_swap_b32_e32 v155, v167
	v_pk_add_f32 v[170:171], v[172:173], v[176:177]
	v_cndmask_b32_e64 v155, v155, v167, s[4:5]
	v_cndmask_b32_e64 v137, -v137, v137, s[4:5]
	v_pk_add_f32 v[172:173], v[168:169], v[170:171]
	v_add_f32_e32 v137, v137, v155
	v_mov_b32_e32 v155, v172
	v_mov_b32_e32 v167, v172
	s_nop 1
	v_permlane16_swap_b32_e32 v155, v167
	v_cndmask_b32_e64 v155, v155, v167, s[2:3]
	v_cndmask_b32_e64 v167, -v172, v172, s[2:3]
	v_pk_add_f32 v[168:169], v[168:169], v[170:171] neg_lo:[0,1] neg_hi:[0,1]
	v_add_f32_e32 v155, v167, v155
	v_mov_b32_e32 v167, v173
	v_mov_b32_e32 v170, v173
	s_nop 1
	v_permlane16_swap_b32_e32 v167, v170
	v_cndmask_b32_e64 v167, v167, v170, s[2:3]
	v_cndmask_b32_e64 v170, -v173, v173, s[2:3]
	v_add_f32_e32 v167, v170, v167
	v_mov_b32_e32 v170, v168
	v_mov_b32_e32 v172, v168
	v_mov_b32_e32 v171, v169
	v_mov_b32_e32 v173, v169
	v_permlane16_swap_b32_e32 v170, v172
	s_nop 0
	v_permlane16_swap_b32_e32 v171, v173
	v_cndmask_b32_e64 v171, v171, v173, s[2:3]
	v_cndmask_b32_e64 v170, v170, v172, s[2:3]
	v_cndmask_b32_e64 v169, -v169, v169, s[2:3]
	v_cndmask_b32_e64 v168, -v168, v168, s[2:3]
	v_pk_add_f32 v[168:169], v[168:169], v[170:171]
	v_mov_b32_e32 v170, v155
	v_mov_b32_e32 v171, v155
	s_nop 1
	v_permlane32_swap_b32_e32 v170, v171
	v_cndmask_b32_e64 v170, v170, v171, s[4:5]
	v_cndmask_b32_e64 v155, -v155, v155, s[4:5]
	v_add_f32_e32 v155, v155, v170
	v_mov_b32_e32 v170, v167
	v_mov_b32_e32 v171, v167
	s_nop 1
	v_permlane32_swap_b32_e32 v170, v171
	v_cndmask_b32_e64 v170, v170, v171, s[4:5]
	v_cndmask_b32_e64 v167, -v167, v167, s[4:5]
	v_add_f32_e32 v167, v167, v170
	v_mov_b32_e32 v170, v168
	v_mov_b32_e32 v172, v168
	v_mov_b32_e32 v171, v169
	v_mov_b32_e32 v173, v169
	v_permlane32_swap_b32_e32 v170, v172
	s_nop 0
	v_permlane32_swap_b32_e32 v171, v173
	v_cndmask_b32_e64 v181, -v181, v181, s[2:3]
	v_cndmask_b32_e64 v180, -v180, v180, s[2:3]
	v_cndmask_b32_e64 v171, v171, v173, s[4:5]
	v_cndmask_b32_e64 v170, v170, v172, s[4:5]
	v_cndmask_b32_e64 v169, -v169, v169, s[4:5]
	v_cndmask_b32_e64 v168, -v168, v168, s[4:5]
	v_pk_add_f32 v[180:181], v[180:181], v[182:183]
	v_pk_add_f32 v[168:169], v[168:169], v[170:171]
	v_mov_b32_e32 v172, v180
	v_pk_mul_f32 v[170:171], v[168:169], s[38:39] op_sel_hi:[1,0]
	v_mov_b32_e32 v168, v180
	v_mov_b32_e32 v169, v181
	v_mov_b32_e32 v173, v181
	v_permlane32_swap_b32_e32 v168, v172
	s_nop 0
	v_permlane32_swap_b32_e32 v169, v173
	v_cndmask_b32_e64 v169, v169, v173, s[4:5]
	v_cndmask_b32_e64 v168, v168, v172, s[4:5]
	v_cndmask_b32_e64 v173, -v181, v181, s[4:5]
	v_cndmask_b32_e64 v172, -v180, v180, s[4:5]
	v_pk_add_f32 v[168:169], v[172:173], v[168:169]
	v_cvt_f32_i32_e32 v177, v118
	v_cvt_f32_i32_e32 v176, v114
	v_mul_f32_e32 v129, 0x3e3504f3, v129
	v_mul_f32_e32 v137, 0x3e3504f3, v137
	v_mul_f32_e32 v155, 0x3e3504f3, v155
	v_mul_f32_e32 v167, 0x3e3504f3, v167
	v_pk_mul_f32 v[172:173], v[168:169], s[38:39] op_sel_hi:[1,0]
	v_lshl_add_u64 v[174:175], v[198:199], 0, v[124:125]
	v_cvt_pk_bf16_f32 v168, v155, v167
	v_cvt_pk_bf16_f32 v169, v129, v137
	v_cvt_pk_bf16_f32 v170, v170, v171
	v_cvt_pk_bf16_f32 v171, v172, v173
	global_store_dwordx4 v[174:175], v[168:171], off nt
	v_cvt_f32_i32_e32 v118, v115
	v_or_b32_e32 v129, 16, v154
	v_pk_mul_f32 v[168:169], v[134:135], v[164:165] op_sel_hi:[1,0]
	v_cvt_f32_i32_e32 v171, v120
	v_pk_mul_f32 v[168:169], v[168:169], v[176:177]
	v_cvt_f32_i32_e32 v170, v116
	v_mul_f32_e32 v114, 0xbfb8aa3b, v169
	v_exp_f32_e32 v114, v114
	v_pk_mul_f32 v[172:173], v[132:133], v[164:165] op_sel_hi:[1,0]
	v_cvt_f32_i32_e32 v120, v117
	v_pk_mul_f32 v[170:171], v[172:173], v[170:171]
	v_add_f32_e32 v114, 1.0, v114
	v_rcp_f32_e32 v137, v114
	v_pk_mul_f32 v[114:115], v[62:63], v[164:165] op_sel_hi:[1,0]
	v_mul_f32_e32 v116, 0xbfb8aa3b, v171
	v_pk_mul_f32 v[114:115], v[114:115], v[118:119]
	v_exp_f32_e32 v116, v116
	v_mul_f32_e32 v118, 0xbfb8aa3b, v115
	v_exp_f32_e32 v155, v118
	v_mad_i64_i32 v[118:119], s[12:13], v129, s79, v[156:157]
	v_mul_f32_e32 v129, v169, v137
	v_add_f32_e32 v137, 1.0, v155
	v_rcp_f32_e32 v137, v137
	v_add_f32_e32 v116, 1.0, v116
	v_rcp_f32_e32 v167, v116
	v_cvt_f32_i32_e32 v116, v106
	v_mul_f32_e32 v115, v115, v137
	v_mul_f32_e32 v137, v114, v115
	v_pk_mul_f32 v[114:115], v[64:65], v[164:165] op_sel_hi:[1,0]
	v_mul_f32_e32 v155, v168, v129
	v_pk_mul_f32 v[114:115], v[114:115], v[120:121]
	s_nop 0
	v_mul_f32_e32 v117, 0xbfb8aa3b, v115
	v_exp_f32_e32 v120, v117
	v_cvt_f32_i32_e32 v117, v110
	v_add_f32_e32 v106, 1.0, v120
	v_pk_mul_f32 v[120:121], v[130:131], v[164:165] op_sel_hi:[1,0]
	v_rcp_f32_e32 v106, v106
	v_pk_mul_f32 v[116:117], v[120:121], v[116:117]
	v_mul_f32_e32 v120, v171, v167
	v_mul_f32_e32 v110, 0xbfb8aa3b, v117
	v_exp_f32_e32 v110, v110
	v_mul_f32_e32 v106, v115, v106
	v_mul_f32_e32 v167, v114, v106
	v_mul_f32_e32 v121, v170, v120
	v_add_f32_e32 v110, 1.0, v110
	v_rcp_f32_e32 v115, v110
	v_cvt_f32_i32_e32 v110, v107
	v_pk_mul_f32 v[106:107], v[50:51], v[164:165] op_sel_hi:[1,0]
	v_mul_f32_e32 v117, v117, v115
	v_pk_mul_f32 v[106:107], v[106:107], v[110:111]
	v_cvt_f32_i32_e32 v111, v112
	v_mul_f32_e32 v110, 0xbfb8aa3b, v107
	v_exp_f32_e32 v114, v110
	v_cvt_f32_i32_e32 v110, v108
	v_cvt_f32_i32_e32 v112, v109
	v_mul_f32_e32 v169, v116, v117
	v_add_f32_e32 v108, 1.0, v114
	v_pk_mul_f32 v[114:115], v[126:127], v[164:165] op_sel_hi:[1,0]
	v_rcp_f32_e32 v171, v108
	v_pk_mul_f32 v[110:111], v[114:115], v[110:111]
	v_mul_f32_e32 v107, v107, v171
	v_mul_f32_e32 v108, 0xbfb8aa3b, v111
	v_exp_f32_e32 v114, v108
	v_pk_mul_f32 v[108:109], v[52:53], v[164:165] op_sel_hi:[1,0]
	v_mul_f32_e32 v115, v106, v107
	v_pk_mul_f32 v[108:109], v[108:109], v[112:113]
	v_add_f32_e32 v113, 1.0, v114
	v_mul_f32_e32 v112, 0xbfb8aa3b, v109
	v_exp_f32_e32 v112, v112
	v_rcp_f32_e32 v113, v113
	v_fma_f32 v107, v168, v129, -v137
	v_add_f32_e32 v114, v169, v115
	v_add_f32_e32 v112, 1.0, v112
	v_rcp_f32_e32 v112, v112
	v_mul_f32_e32 v111, v111, v113
	v_mul_f32_e32 v164, v110, v111
	v_fma_f32 v115, v116, v117, -v115
	v_mul_f32_e32 v106, v109, v112
	v_mul_f32_e32 v171, v108, v106
	v_add_f32_e32 v106, v155, v137
	v_add_f32_e32 v108, v121, v167
	v_fma_f32 v109, v170, v120, -v167
	v_add_f32_e32 v116, v164, v171
	v_fma_f32 v117, v110, v111, -v171
	v_pk_add_f32 v[110:111], v[106:107], v[108:109] neg_lo:[0,1] neg_hi:[0,1]
	v_pk_add_f32 v[106:107], v[106:107], v[108:109]
	v_pk_add_f32 v[108:109], v[114:115], v[116:117]
	v_lshl_add_u64 v[112:113], v[118:119], 0, v[124:125]
	v_pk_add_f32 v[118:119], v[114:115], v[116:117] neg_lo:[0,1] neg_hi:[0,1]
	v_pk_add_f32 v[114:115], v[106:107], v[108:109]
	v_pk_add_f32 v[106:107], v[106:107], v[108:109] neg_lo:[0,1] neg_hi:[0,1]
	v_mov_b32_e32 v108, v114
	v_mov_b32_e32 v109, v114
	s_nop 1
	v_permlane16_swap_b32_e32 v108, v109
	v_cndmask_b32_e64 v108, v108, v109, s[2:3]
	v_cndmask_b32_e64 v109, -v114, v114, s[2:3]
	v_add_f32_e32 v114, v109, v108
	v_mov_b32_e32 v108, v115
	v_mov_b32_e32 v109, v115
	s_nop 1
	v_permlane16_swap_b32_e32 v108, v109
	v_cndmask_b32_e64 v108, v108, v109, s[2:3]
	v_cndmask_b32_e64 v109, -v115, v115, s[2:3]
	v_add_f32_e32 v115, v109, v108
	v_mov_b32_e32 v108, v106
	v_mov_b32_e32 v116, v106
	v_mov_b32_e32 v109, v107
	v_mov_b32_e32 v117, v107
	v_permlane16_swap_b32_e32 v108, v116
	s_nop 0
	v_permlane16_swap_b32_e32 v109, v117
	v_cndmask_b32_e64 v109, v109, v117, s[2:3]
	v_cndmask_b32_e64 v108, v108, v116, s[2:3]
	v_cndmask_b32_e64 v107, -v107, v107, s[2:3]
	v_cndmask_b32_e64 v106, -v106, v106, s[2:3]
	v_pk_add_f32 v[120:121], v[110:111], v[118:119]
	v_pk_add_f32 v[106:107], v[106:107], v[108:109]
	v_mov_b32_e32 v108, v114
	v_mov_b32_e32 v109, v114
	v_pk_add_f32 v[110:111], v[110:111], v[118:119] neg_lo:[0,1] neg_hi:[0,1]
	v_mov_b32_e32 v118, v120
	v_mov_b32_e32 v119, v120
	v_permlane32_swap_b32_e32 v108, v109
	s_nop 0
	v_permlane16_swap_b32_e32 v118, v119
	v_cndmask_b32_e64 v108, v108, v109, s[4:5]
	v_cndmask_b32_e64 v109, -v114, v114, s[4:5]
	v_cndmask_b32_e64 v118, v118, v119, s[2:3]
	v_cndmask_b32_e64 v119, -v120, v120, s[2:3]
	v_add_f32_e32 v108, v109, v108
	v_add_f32_e32 v120, v119, v118
	v_mov_b32_e32 v118, v121
	v_mov_b32_e32 v119, v121
	v_mul_f32_e32 v114, 0x3e3504f3, v108
	v_mov_b32_e32 v108, v115
	v_mov_b32_e32 v109, v115
	v_permlane16_swap_b32_e32 v118, v119
	s_nop 0
	v_permlane32_swap_b32_e32 v108, v109
	v_cndmask_b32_e64 v118, v118, v119, s[2:3]
	v_cndmask_b32_e64 v119, -v121, v121, s[2:3]
	v_cndmask_b32_e64 v108, v108, v109, s[4:5]
	v_cndmask_b32_e64 v109, -v115, v115, s[4:5]
	v_add_f32_e32 v121, v119, v118
	v_mov_b32_e32 v118, v110
	v_mov_b32_e32 v129, v110
	v_mov_b32_e32 v119, v111
	v_mov_b32_e32 v137, v111
	v_add_f32_e32 v108, v109, v108
	v_permlane16_swap_b32_e32 v118, v129
	v_permlane16_swap_b32_e32 v119, v137
	v_mul_f32_e32 v115, 0x3e3504f3, v108
	v_mov_b32_e32 v108, v106
	v_mov_b32_e32 v116, v106
	v_mov_b32_e32 v109, v107
	v_mov_b32_e32 v117, v107
	v_cndmask_b32_e64 v119, v119, v137, s[2:3]
	v_cndmask_b32_e64 v118, v118, v129, s[2:3]
	v_cndmask_b32_e64 v111, -v111, v111, s[2:3]
	v_cndmask_b32_e64 v110, -v110, v110, s[2:3]
	v_permlane32_swap_b32_e32 v108, v116
	v_permlane32_swap_b32_e32 v109, v117
	v_pk_add_f32 v[110:111], v[110:111], v[118:119]
	v_mov_b32_e32 v118, v120
	v_mov_b32_e32 v119, v120
	v_cndmask_b32_e64 v109, v109, v117, s[4:5]
	v_cndmask_b32_e64 v108, v108, v116, s[4:5]
	v_cndmask_b32_e64 v107, -v107, v107, s[4:5]
	v_cndmask_b32_e64 v106, -v106, v106, s[4:5]
	v_permlane32_swap_b32_e32 v118, v119
	v_pk_add_f32 v[106:107], v[106:107], v[108:109]
	v_cndmask_b32_e64 v118, v118, v119, s[4:5]
	v_cndmask_b32_e64 v119, -v120, v120, s[4:5]
	v_pk_mul_f32 v[108:109], v[106:107], s[38:39] op_sel_hi:[1,0]
	v_mov_b32_e32 v106, v110
	v_mov_b32_e32 v116, v110
	v_mov_b32_e32 v107, v111
	v_mov_b32_e32 v117, v111
	v_add_f32_e32 v118, v119, v118
	v_mov_b32_e32 v119, v121
	v_mov_b32_e32 v120, v121
	v_permlane32_swap_b32_e32 v106, v116
	v_permlane32_swap_b32_e32 v107, v117
	v_permlane32_swap_b32_e32 v119, v120
	v_cndmask_b32_e64 v107, v107, v117, s[4:5]
	v_cndmask_b32_e64 v106, v106, v116, s[4:5]
	v_cndmask_b32_e64 v111, -v111, v111, s[4:5]
	v_cndmask_b32_e64 v110, -v110, v110, s[4:5]
	v_cndmask_b32_e64 v119, v119, v120, s[4:5]
	v_cndmask_b32_e64 v120, -v121, v121, s[4:5]
	v_pk_add_f32 v[106:107], v[110:111], v[106:107]
	v_add_f32_e32 v119, v120, v119
	v_pk_mul_f32 v[110:111], v[106:107], s[38:39] op_sel_hi:[1,0]
	v_cvt_pk_bf16_f32 v106, v114, v115
	v_cvt_f32_i32_e32 v115, v102
	v_cvt_f32_i32_e32 v114, v98
	v_mul_f32_e32 v118, 0x3e3504f3, v118
	v_mul_f32_e32 v119, 0x3e3504f3, v119
	v_cvt_pk_bf16_f32 v107, v118, v119
	v_cvt_pk_bf16_f32 v108, v108, v109
	v_cvt_pk_bf16_f32 v109, v110, v111
	global_store_dwordx4 v[112:113], v[106:109], off nt
	v_cvt_f32_i32_e32 v102, v99
	s_nop 0
	v_pk_mul_f32 v[106:107], v[134:135], v[162:163] op_sel_hi:[1,0]
	v_or_b32_e32 v108, 32, v154
	v_pk_mul_f32 v[106:107], v[106:107], v[114:115]
	s_nop 0
	v_mul_f32_e32 v98, 0xbfb8aa3b, v107
	v_exp_f32_e32 v98, v98
	s_nop 0
	v_add_f32_e32 v98, 1.0, v98
	v_rcp_f32_e32 v109, v98
	v_pk_mul_f32 v[98:99], v[62:63], v[162:163] op_sel_hi:[1,0]
	v_mul_f32_e32 v107, v107, v109
	v_pk_mul_f32 v[98:99], v[98:99], v[102:103]
	v_cvt_f32_i32_e32 v109, v104
	v_mul_f32_e32 v102, 0xbfb8aa3b, v99
	v_exp_f32_e32 v110, v102
	v_mad_i64_i32 v[102:103], s[12:13], v108, s79, v[156:157]
	v_cvt_f32_i32_e32 v104, v101
	v_add_f32_e32 v108, 1.0, v110
	v_rcp_f32_e32 v110, v108
	v_cvt_f32_i32_e32 v108, v100
	v_mul_f32_e32 v112, v106, v107
	v_mul_f32_e32 v99, v99, v110
	v_pk_mul_f32 v[110:111], v[132:133], v[162:163] op_sel_hi:[1,0]
	s_nop 0
	v_pk_mul_f32 v[108:109], v[110:111], v[108:109]
	v_mul_f32_e32 v110, v98, v99
	v_mul_f32_e32 v100, 0xbfb8aa3b, v109
	v_exp_f32_e32 v100, v100
	v_pk_mul_f32 v[98:99], v[64:65], v[162:163] op_sel_hi:[1,0]
	v_add_f32_e32 v100, 1.0, v100
	v_pk_mul_f32 v[98:99], v[98:99], v[104:105]
	v_rcp_f32_e32 v111, v100
	v_mul_f32_e32 v101, 0xbfb8aa3b, v99
	v_exp_f32_e32 v104, v101
	v_cvt_f32_i32_e32 v101, v94
	v_cvt_f32_i32_e32 v100, v90
	v_add_f32_e32 v90, 1.0, v104
	v_pk_mul_f32 v[104:105], v[130:131], v[162:163] op_sel_hi:[1,0]
	v_rcp_f32_e32 v90, v90
	v_pk_mul_f32 v[100:101], v[104:105], v[100:101]
	v_mul_f32_e32 v104, v109, v111
	v_mul_f32_e32 v94, 0xbfb8aa3b, v101
	v_exp_f32_e32 v94, v94
	v_mul_f32_e32 v90, v99, v90
	v_mul_f32_e32 v109, v98, v90
	v_mul_f32_e32 v105, v108, v104
	v_add_f32_e32 v94, 1.0, v94
	v_rcp_f32_e32 v99, v94
	v_cvt_f32_i32_e32 v94, v91
	v_pk_mul_f32 v[90:91], v[50:51], v[162:163] op_sel_hi:[1,0]
	v_mul_f32_e32 v101, v101, v99
	v_pk_mul_f32 v[90:91], v[90:91], v[94:95]
	v_cvt_f32_i32_e32 v95, v96
	v_mul_f32_e32 v94, 0xbfb8aa3b, v91
	v_exp_f32_e32 v98, v94
	v_cvt_f32_i32_e32 v94, v92
	v_cvt_f32_i32_e32 v96, v93
	v_mul_f32_e32 v111, v100, v101
	v_add_f32_e32 v92, 1.0, v98
	v_pk_mul_f32 v[98:99], v[126:127], v[162:163] op_sel_hi:[1,0]
	v_rcp_f32_e32 v113, v92
	v_pk_mul_f32 v[94:95], v[98:99], v[94:95]
	v_mul_f32_e32 v91, v91, v113
	v_mul_f32_e32 v92, 0xbfb8aa3b, v95
	v_exp_f32_e32 v98, v92
	v_pk_mul_f32 v[92:93], v[52:53], v[162:163] op_sel_hi:[1,0]
	v_mul_f32_e32 v99, v90, v91
	v_pk_mul_f32 v[92:93], v[92:93], v[96:97]
	v_add_f32_e32 v97, 1.0, v98
	v_mul_f32_e32 v96, 0xbfb8aa3b, v93
	v_exp_f32_e32 v96, v96
	v_rcp_f32_e32 v97, v97
	v_fma_f32 v91, v106, v107, -v110
	v_add_f32_e32 v98, v111, v99
	v_add_f32_e32 v96, 1.0, v96
	v_rcp_f32_e32 v96, v96
	v_mul_f32_e32 v95, v95, v97
	v_mul_f32_e32 v113, v94, v95
	v_fma_f32 v99, v100, v101, -v99
	v_mul_f32_e32 v90, v93, v96
	v_mul_f32_e32 v114, v92, v90
	v_add_f32_e32 v90, v112, v110
	v_add_f32_e32 v92, v105, v109
	v_fma_f32 v93, v108, v104, -v109
	v_add_f32_e32 v100, v113, v114
	v_fma_f32 v101, v94, v95, -v114
	v_pk_add_f32 v[94:95], v[90:91], v[92:93] neg_lo:[0,1] neg_hi:[0,1]
	v_pk_add_f32 v[90:91], v[90:91], v[92:93]
	v_pk_add_f32 v[92:93], v[98:99], v[100:101]
	v_lshl_add_u64 v[96:97], v[102:103], 0, v[124:125]
	v_pk_add_f32 v[102:103], v[98:99], v[100:101] neg_lo:[0,1] neg_hi:[0,1]
	v_pk_add_f32 v[98:99], v[90:91], v[92:93]
	v_pk_add_f32 v[90:91], v[90:91], v[92:93] neg_lo:[0,1] neg_hi:[0,1]
	v_mov_b32_e32 v92, v98
	v_mov_b32_e32 v93, v98
	s_nop 1
	v_permlane16_swap_b32_e32 v92, v93
	v_cndmask_b32_e64 v92, v92, v93, s[2:3]
	v_cndmask_b32_e64 v93, -v98, v98, s[2:3]
	v_add_f32_e32 v98, v93, v92
	v_mov_b32_e32 v92, v99
	v_mov_b32_e32 v93, v99
	s_nop 1
	v_permlane16_swap_b32_e32 v92, v93
	v_cndmask_b32_e64 v92, v92, v93, s[2:3]
	v_cndmask_b32_e64 v93, -v99, v99, s[2:3]
	v_add_f32_e32 v99, v93, v92
	v_mov_b32_e32 v92, v90
	v_mov_b32_e32 v100, v90
	v_mov_b32_e32 v93, v91
	v_mov_b32_e32 v101, v91
	v_permlane16_swap_b32_e32 v92, v100
	s_nop 0
	v_permlane16_swap_b32_e32 v93, v101
	v_cndmask_b32_e64 v93, v93, v101, s[2:3]
	v_cndmask_b32_e64 v92, v92, v100, s[2:3]
	v_cndmask_b32_e64 v91, -v91, v91, s[2:3]
	v_cndmask_b32_e64 v90, -v90, v90, s[2:3]
	v_pk_add_f32 v[104:105], v[94:95], v[102:103]
	v_pk_add_f32 v[90:91], v[90:91], v[92:93]
	v_mov_b32_e32 v92, v98
	v_mov_b32_e32 v93, v98
	v_pk_add_f32 v[94:95], v[94:95], v[102:103] neg_lo:[0,1] neg_hi:[0,1]
	v_mov_b32_e32 v102, v104
	v_mov_b32_e32 v103, v104
	v_permlane32_swap_b32_e32 v92, v93
	s_nop 0
	v_permlane16_swap_b32_e32 v102, v103
	v_cndmask_b32_e64 v92, v92, v93, s[4:5]
	v_cndmask_b32_e64 v93, -v98, v98, s[4:5]
	v_cndmask_b32_e64 v102, v102, v103, s[2:3]
	v_cndmask_b32_e64 v103, -v104, v104, s[2:3]
	v_add_f32_e32 v92, v93, v92
	v_add_f32_e32 v104, v103, v102
	v_mov_b32_e32 v102, v105
	v_mov_b32_e32 v103, v105
	v_mul_f32_e32 v98, 0x3e3504f3, v92
	v_mov_b32_e32 v92, v99
	v_mov_b32_e32 v93, v99
	v_permlane16_swap_b32_e32 v102, v103
	s_nop 0
	v_permlane32_swap_b32_e32 v92, v93
	v_cndmask_b32_e64 v102, v102, v103, s[2:3]
	v_cndmask_b32_e64 v103, -v105, v105, s[2:3]
	v_cndmask_b32_e64 v92, v92, v93, s[4:5]
	v_cndmask_b32_e64 v93, -v99, v99, s[4:5]
	v_add_f32_e32 v105, v103, v102
	v_mov_b32_e32 v102, v94
	v_mov_b32_e32 v106, v94
	v_mov_b32_e32 v103, v95
	v_mov_b32_e32 v107, v95
	v_add_f32_e32 v92, v93, v92
	v_permlane16_swap_b32_e32 v102, v106
	v_permlane16_swap_b32_e32 v103, v107
	v_mul_f32_e32 v99, 0x3e3504f3, v92
	v_mov_b32_e32 v92, v90
	v_mov_b32_e32 v100, v90
	v_mov_b32_e32 v93, v91
	v_mov_b32_e32 v101, v91
	v_cndmask_b32_e64 v103, v103, v107, s[2:3]
	v_cndmask_b32_e64 v102, v102, v106, s[2:3]
	v_cndmask_b32_e64 v95, -v95, v95, s[2:3]
	v_cndmask_b32_e64 v94, -v94, v94, s[2:3]
	v_permlane32_swap_b32_e32 v92, v100
	v_permlane32_swap_b32_e32 v93, v101
	v_pk_add_f32 v[94:95], v[94:95], v[102:103]
	v_mov_b32_e32 v102, v104
	v_mov_b32_e32 v103, v104
	v_cndmask_b32_e64 v93, v93, v101, s[4:5]
	v_cndmask_b32_e64 v92, v92, v100, s[4:5]
	v_cndmask_b32_e64 v91, -v91, v91, s[4:5]
	v_cndmask_b32_e64 v90, -v90, v90, s[4:5]
	v_permlane32_swap_b32_e32 v102, v103
	v_pk_add_f32 v[90:91], v[90:91], v[92:93]
	v_cndmask_b32_e64 v102, v102, v103, s[4:5]
	v_cndmask_b32_e64 v103, -v104, v104, s[4:5]
	v_pk_mul_f32 v[92:93], v[90:91], s[38:39] op_sel_hi:[1,0]
	v_mov_b32_e32 v90, v94
	v_mov_b32_e32 v100, v94
	v_mov_b32_e32 v91, v95
	v_mov_b32_e32 v101, v95
	v_add_f32_e32 v102, v103, v102
	v_mov_b32_e32 v103, v105
	v_mov_b32_e32 v104, v105
	v_permlane32_swap_b32_e32 v90, v100
	v_permlane32_swap_b32_e32 v91, v101
	v_permlane32_swap_b32_e32 v103, v104
	v_cndmask_b32_e64 v91, v91, v101, s[4:5]
	v_cndmask_b32_e64 v90, v90, v100, s[4:5]
	v_cndmask_b32_e64 v95, -v95, v95, s[4:5]
	v_cndmask_b32_e64 v94, -v94, v94, s[4:5]
	v_cndmask_b32_e64 v103, v103, v104, s[4:5]
	v_cndmask_b32_e64 v104, -v105, v105, s[4:5]
	v_pk_add_f32 v[90:91], v[94:95], v[90:91]
	v_add_f32_e32 v103, v104, v103
	v_pk_mul_f32 v[94:95], v[90:91], s[38:39] op_sel_hi:[1,0]
	v_cvt_pk_bf16_f32 v90, v98, v99
	v_cvt_f32_i32_e32 v99, v86
	v_cvt_f32_i32_e32 v98, v82
	v_mul_f32_e32 v102, 0x3e3504f3, v102
	v_mul_f32_e32 v103, 0x3e3504f3, v103
	v_cvt_pk_bf16_f32 v91, v102, v103
	v_cvt_pk_bf16_f32 v92, v92, v93
	v_cvt_pk_bf16_f32 v93, v94, v95
	global_store_dwordx4 v[96:97], v[90:93], off nt
	v_cvt_f32_i32_e32 v86, v83
	s_nop 0
	v_pk_mul_f32 v[90:91], v[134:135], v[160:161] op_sel_hi:[1,0]
	v_or_b32_e32 v92, 48, v154
	v_pk_mul_f32 v[90:91], v[90:91], v[98:99]
	s_nop 0
	v_mul_f32_e32 v82, 0xbfb8aa3b, v91
	v_exp_f32_e32 v82, v82
	s_nop 0
	v_add_f32_e32 v82, 1.0, v82
	v_rcp_f32_e32 v93, v82
	v_pk_mul_f32 v[82:83], v[62:63], v[160:161] op_sel_hi:[1,0]
	v_mul_f32_e32 v91, v91, v93
	v_pk_mul_f32 v[82:83], v[82:83], v[86:87]
	v_cvt_f32_i32_e32 v93, v88
	v_mul_f32_e32 v86, 0xbfb8aa3b, v83
	v_exp_f32_e32 v94, v86
	v_mad_i64_i32 v[86:87], s[12:13], v92, s79, v[156:157]
	v_cvt_f32_i32_e32 v88, v85
	v_add_f32_e32 v92, 1.0, v94
	v_rcp_f32_e32 v94, v92
	v_cvt_f32_i32_e32 v92, v84
	v_mul_f32_e32 v96, v90, v91
	v_mul_f32_e32 v83, v83, v94
	v_pk_mul_f32 v[94:95], v[132:133], v[160:161] op_sel_hi:[1,0]
	s_nop 0
	v_pk_mul_f32 v[92:93], v[94:95], v[92:93]
	v_mul_f32_e32 v94, v82, v83
	v_mul_f32_e32 v84, 0xbfb8aa3b, v93
	v_exp_f32_e32 v84, v84
	v_pk_mul_f32 v[82:83], v[64:65], v[160:161] op_sel_hi:[1,0]
	v_add_f32_e32 v84, 1.0, v84
	v_pk_mul_f32 v[82:83], v[82:83], v[88:89]
	v_rcp_f32_e32 v95, v84
	v_mul_f32_e32 v85, 0xbfb8aa3b, v83
	v_exp_f32_e32 v88, v85
	v_cvt_f32_i32_e32 v85, v78
	v_cvt_f32_i32_e32 v84, v74
	v_add_f32_e32 v74, 1.0, v88
	v_pk_mul_f32 v[88:89], v[130:131], v[160:161] op_sel_hi:[1,0]
	v_rcp_f32_e32 v74, v74
	v_pk_mul_f32 v[84:85], v[88:89], v[84:85]
	v_mul_f32_e32 v88, v93, v95
	v_mul_f32_e32 v78, 0xbfb8aa3b, v85
	v_exp_f32_e32 v78, v78
	v_mul_f32_e32 v74, v83, v74
	v_mul_f32_e32 v93, v82, v74
	v_mul_f32_e32 v89, v92, v88
	v_add_f32_e32 v78, 1.0, v78
	v_rcp_f32_e32 v83, v78
	v_cvt_f32_i32_e32 v78, v75
	v_pk_mul_f32 v[74:75], v[50:51], v[160:161] op_sel_hi:[1,0]
	v_mul_f32_e32 v85, v85, v83
	v_pk_mul_f32 v[74:75], v[74:75], v[78:79]
	v_cvt_f32_i32_e32 v79, v80
	v_mul_f32_e32 v78, 0xbfb8aa3b, v75
	v_exp_f32_e32 v82, v78
	v_cvt_f32_i32_e32 v78, v76
	v_cvt_f32_i32_e32 v80, v77
	v_mul_f32_e32 v95, v84, v85
	v_add_f32_e32 v76, 1.0, v82
	v_pk_mul_f32 v[82:83], v[126:127], v[160:161] op_sel_hi:[1,0]
	v_rcp_f32_e32 v97, v76
	v_pk_mul_f32 v[78:79], v[82:83], v[78:79]
	v_mul_f32_e32 v75, v75, v97
	v_mul_f32_e32 v76, 0xbfb8aa3b, v79
	v_exp_f32_e32 v82, v76
	v_pk_mul_f32 v[76:77], v[52:53], v[160:161] op_sel_hi:[1,0]
	v_mul_f32_e32 v83, v74, v75
	v_pk_mul_f32 v[76:77], v[76:77], v[80:81]
	v_add_f32_e32 v81, 1.0, v82
	v_mul_f32_e32 v80, 0xbfb8aa3b, v77
	v_exp_f32_e32 v80, v80
	v_rcp_f32_e32 v81, v81
	v_fma_f32 v75, v90, v91, -v94
	v_add_f32_e32 v82, v95, v83
	v_add_f32_e32 v80, 1.0, v80
	v_rcp_f32_e32 v80, v80
	v_mul_f32_e32 v79, v79, v81
	v_mul_f32_e32 v97, v78, v79
	v_fma_f32 v83, v84, v85, -v83
	v_mul_f32_e32 v74, v77, v80
	v_mul_f32_e32 v98, v76, v74
	v_add_f32_e32 v74, v96, v94
	v_add_f32_e32 v76, v89, v93
	v_fma_f32 v77, v92, v88, -v93
	v_add_f32_e32 v84, v97, v98
	v_fma_f32 v85, v78, v79, -v98
	v_pk_add_f32 v[78:79], v[74:75], v[76:77] neg_lo:[0,1] neg_hi:[0,1]
	v_pk_add_f32 v[74:75], v[74:75], v[76:77]
	v_pk_add_f32 v[76:77], v[82:83], v[84:85]
	v_lshl_add_u64 v[80:81], v[86:87], 0, v[124:125]
	v_pk_add_f32 v[86:87], v[82:83], v[84:85] neg_lo:[0,1] neg_hi:[0,1]
	v_pk_add_f32 v[82:83], v[74:75], v[76:77]
	v_pk_add_f32 v[74:75], v[74:75], v[76:77] neg_lo:[0,1] neg_hi:[0,1]
	v_mov_b32_e32 v76, v82
	v_mov_b32_e32 v77, v82
	s_nop 1
	v_permlane16_swap_b32_e32 v76, v77
	v_cndmask_b32_e64 v76, v76, v77, s[2:3]
	v_cndmask_b32_e64 v77, -v82, v82, s[2:3]
	v_add_f32_e32 v82, v77, v76
	v_mov_b32_e32 v76, v83
	v_mov_b32_e32 v77, v83
	s_nop 1
	v_permlane16_swap_b32_e32 v76, v77
	v_cndmask_b32_e64 v76, v76, v77, s[2:3]
	v_cndmask_b32_e64 v77, -v83, v83, s[2:3]
	v_add_f32_e32 v83, v77, v76
	v_mov_b32_e32 v76, v74
	v_mov_b32_e32 v84, v74
	v_mov_b32_e32 v77, v75
	v_mov_b32_e32 v85, v75
	v_permlane16_swap_b32_e32 v76, v84
	s_nop 0
	v_permlane16_swap_b32_e32 v77, v85
	v_cndmask_b32_e64 v77, v77, v85, s[2:3]
	v_cndmask_b32_e64 v76, v76, v84, s[2:3]
	v_cndmask_b32_e64 v75, -v75, v75, s[2:3]
	v_cndmask_b32_e64 v74, -v74, v74, s[2:3]
	v_pk_add_f32 v[74:75], v[74:75], v[76:77]
	v_mov_b32_e32 v76, v82
	v_mov_b32_e32 v77, v82
	v_pk_add_f32 v[88:89], v[78:79], v[86:87]
	s_nop 0
	v_permlane32_swap_b32_e32 v76, v77
	v_pk_add_f32 v[78:79], v[78:79], v[86:87] neg_lo:[0,1] neg_hi:[0,1]
	v_mov_b32_e32 v86, v88
	v_mov_b32_e32 v87, v88
	v_cndmask_b32_e64 v76, v76, v77, s[4:5]
	v_cndmask_b32_e64 v77, -v82, v82, s[4:5]
	v_permlane16_swap_b32_e32 v86, v87
	v_add_f32_e32 v76, v77, v76
	v_cndmask_b32_e64 v86, v86, v87, s[2:3]
	v_cndmask_b32_e64 v87, -v88, v88, s[2:3]
	v_mul_f32_e32 v82, 0x3e3504f3, v76
	v_mov_b32_e32 v76, v83
	v_mov_b32_e32 v77, v83
	v_add_f32_e32 v88, v87, v86
	v_mov_b32_e32 v86, v89
	v_mov_b32_e32 v87, v89
	v_permlane32_swap_b32_e32 v76, v77
	s_nop 0
	v_permlane16_swap_b32_e32 v86, v87
	v_cndmask_b32_e64 v76, v76, v77, s[4:5]
	v_cndmask_b32_e64 v77, -v83, v83, s[4:5]
	v_cndmask_b32_e64 v86, v86, v87, s[2:3]
	v_cndmask_b32_e64 v87, -v89, v89, s[2:3]
	v_add_f32_e32 v76, v77, v76
	v_add_f32_e32 v89, v87, v86
	v_mov_b32_e32 v86, v78
	v_mov_b32_e32 v90, v78
	v_mov_b32_e32 v87, v79
	v_mov_b32_e32 v91, v79
	v_mul_f32_e32 v83, 0x3e3504f3, v76
	v_mov_b32_e32 v76, v74
	v_mov_b32_e32 v84, v74
	v_mov_b32_e32 v77, v75
	v_mov_b32_e32 v85, v75
	v_permlane16_swap_b32_e32 v86, v90
	v_permlane16_swap_b32_e32 v87, v91
	v_permlane32_swap_b32_e32 v76, v84
	v_permlane32_swap_b32_e32 v77, v85
	v_cndmask_b32_e64 v87, v87, v91, s[2:3]
	v_cndmask_b32_e64 v86, v86, v90, s[2:3]
	v_cndmask_b32_e64 v79, -v79, v79, s[2:3]
	v_cndmask_b32_e64 v78, -v78, v78, s[2:3]
	v_cndmask_b32_e64 v77, v77, v85, s[4:5]
	v_cndmask_b32_e64 v76, v76, v84, s[4:5]
	v_cndmask_b32_e64 v75, -v75, v75, s[4:5]
	v_cndmask_b32_e64 v74, -v74, v74, s[4:5]
	v_pk_add_f32 v[78:79], v[78:79], v[86:87]
	v_pk_add_f32 v[74:75], v[74:75], v[76:77]
	v_mov_b32_e32 v84, v78
	v_pk_mul_f32 v[76:77], v[74:75], s[38:39] op_sel_hi:[1,0]
	v_mov_b32_e32 v74, v78
	v_mov_b32_e32 v75, v79
	v_mov_b32_e32 v85, v79
	v_permlane32_swap_b32_e32 v74, v84
	s_nop 0
	v_permlane32_swap_b32_e32 v75, v85
	v_cndmask_b32_e64 v75, v75, v85, s[4:5]
	v_cndmask_b32_e64 v74, v74, v84, s[4:5]
	v_cndmask_b32_e64 v79, -v79, v79, s[4:5]
	v_cndmask_b32_e64 v78, -v78, v78, s[4:5]
	v_pk_add_f32 v[74:75], v[78:79], v[74:75]
	v_mov_b32_e32 v86, v88
	v_pk_mul_f32 v[78:79], v[74:75], s[38:39] op_sel_hi:[1,0]
	v_cvt_pk_bf16_f32 v74, v82, v83
	v_cvt_f32_i32_e32 v83, v70
	v_cvt_f32_i32_e32 v82, v66
	v_mov_b32_e32 v87, v88
	s_nop 1
	v_permlane32_swap_b32_e32 v86, v87
	v_cvt_pk_bf16_f32 v76, v76, v77
	v_cvt_pk_bf16_f32 v77, v78, v79
	v_pk_mul_f32 v[78:79], v[134:135], v[158:159] op_sel_hi:[1,0]
	v_cndmask_b32_e64 v86, v86, v87, s[4:5]
	v_cndmask_b32_e64 v87, -v88, v88, s[4:5]
	v_pk_mul_f32 v[78:79], v[78:79], v[82:83]
	v_add_f32_e32 v86, v87, v86
	v_mov_b32_e32 v87, v89
	v_mov_b32_e32 v88, v89
	v_mul_f32_e32 v66, 0xbfb8aa3b, v79
	s_nop 0
	v_permlane32_swap_b32_e32 v87, v88
	v_exp_f32_e32 v66, v66
	v_cndmask_b32_e64 v87, v87, v88, s[4:5]
	v_cndmask_b32_e64 v88, -v89, v89, s[4:5]
	v_add_f32_e32 v87, v88, v87
	v_cvt_f32_i32_e32 v70, v67
	v_mul_f32_e32 v86, 0x3e3504f3, v86
	v_mul_f32_e32 v87, 0x3e3504f3, v87
	v_cvt_pk_bf16_f32 v75, v86, v87
	v_add_f32_e32 v66, 1.0, v66
	global_store_dwordx4 v[80:81], v[74:77], off nt
	s_nop 1
	v_rcp_f32_e32 v74, v66
	v_pk_mul_f32 v[66:67], v[62:63], v[158:159] op_sel_hi:[1,0]
	v_mul_f32_e32 v79, v79, v74
	v_pk_mul_f32 v[66:67], v[66:67], v[70:71]
	v_mul_f32_e32 v80, v78, v79
	v_mul_f32_e32 v70, 0xbfb8aa3b, v67
	v_exp_f32_e32 v75, v70
	v_mad_i64_i32 v[70:71], s[12:13], v123, s79, v[156:157]
	v_add_f32_e32 v74, 1.0, v75
	v_rcp_f32_e32 v76, v74
	v_cvt_f32_i32_e32 v75, v72
	v_cvt_f32_i32_e32 v74, v68
	v_cvt_f32_i32_e32 v72, v69
	v_mul_f32_e32 v67, v67, v76
	v_pk_mul_f32 v[76:77], v[132:133], v[158:159] op_sel_hi:[1,0]
	s_nop 0
	v_pk_mul_f32 v[74:75], v[76:77], v[74:75]
	v_mul_f32_e32 v76, v66, v67
	v_mul_f32_e32 v68, 0xbfb8aa3b, v75
	v_exp_f32_e32 v68, v68
	v_pk_mul_f32 v[66:67], v[64:65], v[158:159] op_sel_hi:[1,0]
	v_add_f32_e32 v68, 1.0, v68
	v_pk_mul_f32 v[66:67], v[66:67], v[72:73]
	v_rcp_f32_e32 v77, v68
	v_mul_f32_e32 v69, 0xbfb8aa3b, v67
	v_exp_f32_e32 v72, v69
	v_cvt_f32_i32_e32 v69, v58
	v_cvt_f32_i32_e32 v68, v54
	v_add_f32_e32 v54, 1.0, v72
	v_pk_mul_f32 v[72:73], v[130:131], v[158:159] op_sel_hi:[1,0]
	v_rcp_f32_e32 v54, v54
	v_pk_mul_f32 v[68:69], v[72:73], v[68:69]
	v_mul_f32_e32 v72, v75, v77
	v_mul_f32_e32 v58, 0xbfb8aa3b, v69
	v_exp_f32_e32 v58, v58
	v_mul_f32_e32 v54, v67, v54
	v_mul_f32_e32 v75, v66, v54
	v_mul_f32_e32 v73, v74, v72
	v_add_f32_e32 v58, 1.0, v58
	v_rcp_f32_e32 v67, v58
	v_cvt_f32_i32_e32 v58, v55
	v_pk_mul_f32 v[54:55], v[50:51], v[158:159] op_sel_hi:[1,0]
	v_mul_f32_e32 v69, v69, v67
	v_pk_mul_f32 v[54:55], v[54:55], v[58:59]
	v_cvt_f32_i32_e32 v59, v60
	v_mul_f32_e32 v58, 0xbfb8aa3b, v55
	v_exp_f32_e32 v66, v58
	v_cvt_f32_i32_e32 v58, v56
	v_cvt_f32_i32_e32 v60, v57
	v_mul_f32_e32 v77, v68, v69
	v_add_f32_e32 v56, 1.0, v66
	v_pk_mul_f32 v[66:67], v[126:127], v[158:159] op_sel_hi:[1,0]
	v_rcp_f32_e32 v81, v56
	v_pk_mul_f32 v[58:59], v[66:67], v[58:59]
	v_mul_f32_e32 v55, v55, v81
	v_mul_f32_e32 v56, 0xbfb8aa3b, v59
	v_exp_f32_e32 v66, v56
	v_pk_mul_f32 v[56:57], v[52:53], v[158:159] op_sel_hi:[1,0]
	v_mul_f32_e32 v67, v54, v55
	v_pk_mul_f32 v[56:57], v[56:57], v[60:61]
	v_add_f32_e32 v61, 1.0, v66
	v_mul_f32_e32 v60, 0xbfb8aa3b, v57
	v_exp_f32_e32 v60, v60
	v_rcp_f32_e32 v61, v61
	v_fma_f32 v55, v78, v79, -v76
	v_add_f32_e32 v66, v77, v67
	v_add_f32_e32 v60, 1.0, v60
	v_rcp_f32_e32 v60, v60
	v_mul_f32_e32 v59, v59, v61
	v_mul_f32_e32 v81, v58, v59
	v_fma_f32 v67, v68, v69, -v67
	v_mul_f32_e32 v54, v57, v60
	v_mul_f32_e32 v82, v56, v54
	v_add_f32_e32 v54, v80, v76
	v_add_f32_e32 v56, v73, v75
	v_fma_f32 v57, v74, v72, -v75
	v_add_f32_e32 v68, v81, v82
	v_fma_f32 v69, v58, v59, -v82
	v_pk_add_f32 v[58:59], v[54:55], v[56:57] neg_lo:[0,1] neg_hi:[0,1]
	v_pk_add_f32 v[54:55], v[54:55], v[56:57]
	v_pk_add_f32 v[56:57], v[66:67], v[68:69]
	v_lshl_add_u64 v[60:61], v[70:71], 0, v[124:125]
	v_pk_add_f32 v[70:71], v[66:67], v[68:69] neg_lo:[0,1] neg_hi:[0,1]
	v_pk_add_f32 v[66:67], v[54:55], v[56:57]
	v_pk_add_f32 v[54:55], v[54:55], v[56:57] neg_lo:[0,1] neg_hi:[0,1]
	v_mov_b32_e32 v56, v66
	v_mov_b32_e32 v57, v66
	s_nop 1
	v_permlane16_swap_b32_e32 v56, v57
	v_cndmask_b32_e64 v56, v56, v57, s[2:3]
	v_cndmask_b32_e64 v57, -v66, v66, s[2:3]
	v_add_f32_e32 v66, v57, v56
	v_mov_b32_e32 v56, v67
	v_mov_b32_e32 v57, v67
	s_nop 1
	v_permlane16_swap_b32_e32 v56, v57
	v_cndmask_b32_e64 v56, v56, v57, s[2:3]
	v_cndmask_b32_e64 v57, -v67, v67, s[2:3]
	v_add_f32_e32 v67, v57, v56
	v_mov_b32_e32 v56, v54
	v_mov_b32_e32 v68, v54
	v_mov_b32_e32 v57, v55
	v_mov_b32_e32 v69, v55
	v_permlane16_swap_b32_e32 v56, v68
	s_nop 0
	v_permlane16_swap_b32_e32 v57, v69
	v_cndmask_b32_e64 v57, v57, v69, s[2:3]
	v_cndmask_b32_e64 v56, v56, v68, s[2:3]
	v_cndmask_b32_e64 v55, -v55, v55, s[2:3]
	v_cndmask_b32_e64 v54, -v54, v54, s[2:3]
	v_pk_add_f32 v[72:73], v[58:59], v[70:71]
	v_pk_add_f32 v[54:55], v[54:55], v[56:57]
	v_mov_b32_e32 v56, v66
	v_mov_b32_e32 v57, v66
	v_pk_add_f32 v[58:59], v[58:59], v[70:71] neg_lo:[0,1] neg_hi:[0,1]
	v_mov_b32_e32 v70, v72
	v_mov_b32_e32 v71, v72
	v_permlane32_swap_b32_e32 v56, v57
	s_nop 0
	v_permlane16_swap_b32_e32 v70, v71
	v_cndmask_b32_e64 v56, v56, v57, s[4:5]
	v_cndmask_b32_e64 v57, -v66, v66, s[4:5]
	v_cndmask_b32_e64 v70, v70, v71, s[2:3]
	v_cndmask_b32_e64 v71, -v72, v72, s[2:3]
	v_add_f32_e32 v56, v57, v56
	v_add_f32_e32 v72, v71, v70
	v_mov_b32_e32 v70, v73
	v_mov_b32_e32 v71, v73
	v_mul_f32_e32 v66, 0x3e3504f3, v56
	v_mov_b32_e32 v56, v67
	v_mov_b32_e32 v57, v67
	v_permlane16_swap_b32_e32 v70, v71
	s_nop 0
	v_permlane32_swap_b32_e32 v56, v57
	v_cndmask_b32_e64 v70, v70, v71, s[2:3]
	v_cndmask_b32_e64 v71, -v73, v73, s[2:3]
	v_cndmask_b32_e64 v56, v56, v57, s[4:5]
	v_cndmask_b32_e64 v57, -v67, v67, s[4:5]
	v_add_f32_e32 v73, v71, v70
	v_mov_b32_e32 v70, v58
	v_mov_b32_e32 v74, v58
	v_mov_b32_e32 v71, v59
	v_mov_b32_e32 v75, v59
	v_add_f32_e32 v56, v57, v56
	v_permlane16_swap_b32_e32 v70, v74
	v_permlane16_swap_b32_e32 v71, v75
	v_mul_f32_e32 v67, 0x3e3504f3, v56
	v_mov_b32_e32 v56, v54
	v_mov_b32_e32 v68, v54
	v_mov_b32_e32 v57, v55
	v_mov_b32_e32 v69, v55
	v_cndmask_b32_e64 v71, v71, v75, s[2:3]
	v_cndmask_b32_e64 v70, v70, v74, s[2:3]
	v_cndmask_b32_e64 v59, -v59, v59, s[2:3]
	v_cndmask_b32_e64 v58, -v58, v58, s[2:3]
	v_permlane32_swap_b32_e32 v56, v68
	v_permlane32_swap_b32_e32 v57, v69
	v_pk_add_f32 v[58:59], v[58:59], v[70:71]
	v_mov_b32_e32 v70, v72
	v_mov_b32_e32 v71, v72
	v_cndmask_b32_e64 v57, v57, v69, s[4:5]
	v_cndmask_b32_e64 v56, v56, v68, s[4:5]
	v_cndmask_b32_e64 v55, -v55, v55, s[4:5]
	v_cndmask_b32_e64 v54, -v54, v54, s[4:5]
	v_permlane32_swap_b32_e32 v70, v71
	v_pk_add_f32 v[54:55], v[54:55], v[56:57]
	v_cndmask_b32_e64 v70, v70, v71, s[4:5]
	v_cndmask_b32_e64 v71, -v72, v72, s[4:5]
	v_pk_mul_f32 v[56:57], v[54:55], s[38:39] op_sel_hi:[1,0]
	v_mov_b32_e32 v54, v58
	v_mov_b32_e32 v68, v58
	v_mov_b32_e32 v55, v59
	v_mov_b32_e32 v69, v59
	v_add_f32_e32 v70, v71, v70
	v_mov_b32_e32 v71, v73
	v_mov_b32_e32 v72, v73
	v_permlane32_swap_b32_e32 v54, v68
	v_permlane32_swap_b32_e32 v55, v69
	v_permlane32_swap_b32_e32 v71, v72
	v_cndmask_b32_e64 v55, v55, v69, s[4:5]
	v_cndmask_b32_e64 v54, v54, v68, s[4:5]
	v_cndmask_b32_e64 v59, -v59, v59, s[4:5]
	v_cndmask_b32_e64 v58, -v58, v58, s[4:5]
	v_cndmask_b32_e64 v71, v71, v72, s[4:5]
	v_cndmask_b32_e64 v72, -v73, v73, s[4:5]
	v_pk_add_f32 v[54:55], v[58:59], v[54:55]
	v_add_f32_e32 v71, v72, v71
	v_pk_mul_f32 v[58:59], v[54:55], s[38:39] op_sel_hi:[1,0]
	v_cvt_pk_bf16_f32 v54, v66, v67
	v_cvt_f32_i32_e32 v67, v46
	v_cvt_f32_i32_e32 v66, v42
	v_mul_f32_e32 v70, 0x3e3504f3, v70
	v_mul_f32_e32 v71, 0x3e3504f3, v71
	v_cvt_pk_bf16_f32 v55, v70, v71
	v_cvt_pk_bf16_f32 v56, v56, v57
	v_cvt_pk_bf16_f32 v57, v58, v59
	global_store_dwordx4 v[60:61], v[54:57], off nt
	v_cvt_f32_i32_e32 v46, v43
	s_nop 0
	v_pk_mul_f32 v[54:55], v[134:135], v[136:137] op_sel_hi:[1,0]
	v_add_u32_e32 v56, 0x90, v154
	v_pk_mul_f32 v[54:55], v[54:55], v[66:67]
	s_nop 0
	v_mul_f32_e32 v42, 0xbfb8aa3b, v55
	v_exp_f32_e32 v42, v42
	s_nop 0
	v_add_f32_e32 v42, 1.0, v42
	v_rcp_f32_e32 v57, v42
	v_pk_mul_f32 v[42:43], v[62:63], v[136:137] op_sel_hi:[1,0]
	v_mul_f32_e32 v55, v55, v57
	v_pk_mul_f32 v[42:43], v[42:43], v[46:47]
	v_cvt_f32_i32_e32 v57, v48
	v_mul_f32_e32 v46, 0xbfb8aa3b, v43
	v_exp_f32_e32 v58, v46
	v_mad_i64_i32 v[46:47], s[12:13], v56, s79, v[156:157]
	v_cvt_f32_i32_e32 v48, v45
	v_add_f32_e32 v56, 1.0, v58
	v_rcp_f32_e32 v58, v56
	v_cvt_f32_i32_e32 v56, v44
	v_mul_f32_e32 v60, v54, v55
	v_mul_f32_e32 v43, v43, v58
	v_pk_mul_f32 v[58:59], v[132:133], v[136:137] op_sel_hi:[1,0]
	s_nop 0
	v_pk_mul_f32 v[56:57], v[58:59], v[56:57]
	v_mul_f32_e32 v58, v42, v43
	v_mul_f32_e32 v44, 0xbfb8aa3b, v57
	v_exp_f32_e32 v44, v44
	v_pk_mul_f32 v[42:43], v[64:65], v[136:137] op_sel_hi:[1,0]
	v_add_f32_e32 v44, 1.0, v44
	v_pk_mul_f32 v[42:43], v[42:43], v[48:49]
	v_rcp_f32_e32 v59, v44
	v_mul_f32_e32 v45, 0xbfb8aa3b, v43
	v_exp_f32_e32 v48, v45
	v_cvt_f32_i32_e32 v45, v38
	v_cvt_f32_i32_e32 v44, v34
	v_add_f32_e32 v34, 1.0, v48
	v_pk_mul_f32 v[48:49], v[130:131], v[136:137] op_sel_hi:[1,0]
	v_rcp_f32_e32 v34, v34
	v_pk_mul_f32 v[44:45], v[48:49], v[44:45]
	v_mul_f32_e32 v48, v57, v59
	v_mul_f32_e32 v38, 0xbfb8aa3b, v45
	v_exp_f32_e32 v38, v38
	v_mul_f32_e32 v34, v43, v34
	v_mul_f32_e32 v57, v42, v34
	v_mul_f32_e32 v49, v56, v48
	v_add_f32_e32 v38, 1.0, v38
	v_rcp_f32_e32 v43, v38
	v_cvt_f32_i32_e32 v38, v35
	v_pk_mul_f32 v[34:35], v[50:51], v[136:137] op_sel_hi:[1,0]
	v_mul_f32_e32 v45, v45, v43
	v_pk_mul_f32 v[34:35], v[34:35], v[38:39]
	v_cvt_f32_i32_e32 v39, v40
	v_mul_f32_e32 v38, 0xbfb8aa3b, v35
	v_exp_f32_e32 v42, v38
	v_cvt_f32_i32_e32 v38, v36
	v_cvt_f32_i32_e32 v40, v37
	v_mul_f32_e32 v59, v44, v45
	v_add_f32_e32 v36, 1.0, v42
	v_pk_mul_f32 v[42:43], v[126:127], v[136:137] op_sel_hi:[1,0]
	v_rcp_f32_e32 v61, v36
	v_pk_mul_f32 v[38:39], v[42:43], v[38:39]
	v_mul_f32_e32 v35, v35, v61
	v_mul_f32_e32 v36, 0xbfb8aa3b, v39
	v_exp_f32_e32 v42, v36
	v_pk_mul_f32 v[36:37], v[52:53], v[136:137] op_sel_hi:[1,0]
	v_mul_f32_e32 v43, v34, v35
	v_pk_mul_f32 v[36:37], v[36:37], v[40:41]
	v_add_f32_e32 v41, 1.0, v42
	v_mul_f32_e32 v40, 0xbfb8aa3b, v37
	v_exp_f32_e32 v40, v40
	v_rcp_f32_e32 v41, v41
	v_fma_f32 v35, v54, v55, -v58
	v_add_f32_e32 v42, v59, v43
	v_add_f32_e32 v40, 1.0, v40
	v_rcp_f32_e32 v40, v40
	v_mul_f32_e32 v39, v39, v41
	v_mul_f32_e32 v61, v38, v39
	v_fma_f32 v43, v44, v45, -v43
	v_mul_f32_e32 v34, v37, v40
	v_mul_f32_e32 v66, v36, v34
	v_add_f32_e32 v34, v60, v58
	v_add_f32_e32 v36, v49, v57
	v_fma_f32 v37, v56, v48, -v57
	v_add_f32_e32 v44, v61, v66
	v_fma_f32 v45, v38, v39, -v66
	v_pk_add_f32 v[38:39], v[34:35], v[36:37] neg_lo:[0,1] neg_hi:[0,1]
	v_pk_add_f32 v[34:35], v[34:35], v[36:37]
	v_pk_add_f32 v[36:37], v[42:43], v[44:45]
	v_lshl_add_u64 v[40:41], v[46:47], 0, v[124:125]
	v_pk_add_f32 v[46:47], v[42:43], v[44:45] neg_lo:[0,1] neg_hi:[0,1]
	v_pk_add_f32 v[42:43], v[34:35], v[36:37]
	v_pk_add_f32 v[34:35], v[34:35], v[36:37] neg_lo:[0,1] neg_hi:[0,1]
	v_mov_b32_e32 v36, v42
	v_mov_b32_e32 v37, v42
	s_nop 1
	v_permlane16_swap_b32_e32 v36, v37
	v_cndmask_b32_e64 v36, v36, v37, s[2:3]
	v_cndmask_b32_e64 v37, -v42, v42, s[2:3]
	v_add_f32_e32 v42, v37, v36
	v_mov_b32_e32 v36, v43
	v_mov_b32_e32 v37, v43
	s_nop 1
	v_permlane16_swap_b32_e32 v36, v37
	v_cndmask_b32_e64 v36, v36, v37, s[2:3]
	v_cndmask_b32_e64 v37, -v43, v43, s[2:3]
	v_add_f32_e32 v43, v37, v36
	v_mov_b32_e32 v36, v34
	v_mov_b32_e32 v44, v34
	v_mov_b32_e32 v37, v35
	v_mov_b32_e32 v45, v35
	v_permlane16_swap_b32_e32 v36, v44
	s_nop 0
	v_permlane16_swap_b32_e32 v37, v45
	v_cndmask_b32_e64 v37, v37, v45, s[2:3]
	v_cndmask_b32_e64 v36, v36, v44, s[2:3]
	v_cndmask_b32_e64 v35, -v35, v35, s[2:3]
	v_cndmask_b32_e64 v34, -v34, v34, s[2:3]
	v_pk_add_f32 v[48:49], v[38:39], v[46:47]
	v_pk_add_f32 v[34:35], v[34:35], v[36:37]
	v_mov_b32_e32 v36, v42
	v_mov_b32_e32 v37, v42
	v_pk_add_f32 v[38:39], v[38:39], v[46:47] neg_lo:[0,1] neg_hi:[0,1]
	v_mov_b32_e32 v46, v48
	v_mov_b32_e32 v47, v48
	v_permlane32_swap_b32_e32 v36, v37
	s_nop 0
	v_permlane16_swap_b32_e32 v46, v47
	v_cndmask_b32_e64 v36, v36, v37, s[4:5]
	v_cndmask_b32_e64 v37, -v42, v42, s[4:5]
	v_cndmask_b32_e64 v46, v46, v47, s[2:3]
	v_cndmask_b32_e64 v47, -v48, v48, s[2:3]
	v_add_f32_e32 v36, v37, v36
	v_add_f32_e32 v48, v47, v46
	v_mov_b32_e32 v46, v49
	v_mov_b32_e32 v47, v49
	v_mul_f32_e32 v42, 0x3e3504f3, v36
	v_mov_b32_e32 v36, v43
	v_mov_b32_e32 v37, v43
	v_permlane16_swap_b32_e32 v46, v47
	s_nop 0
	v_permlane32_swap_b32_e32 v36, v37
	v_cndmask_b32_e64 v46, v46, v47, s[2:3]
	v_cndmask_b32_e64 v47, -v49, v49, s[2:3]
	v_cndmask_b32_e64 v36, v36, v37, s[4:5]
	v_cndmask_b32_e64 v37, -v43, v43, s[4:5]
	v_add_f32_e32 v49, v47, v46
	v_mov_b32_e32 v46, v38
	v_mov_b32_e32 v54, v38
	v_mov_b32_e32 v47, v39
	v_mov_b32_e32 v55, v39
	v_add_f32_e32 v36, v37, v36
	v_permlane16_swap_b32_e32 v46, v54
	v_permlane16_swap_b32_e32 v47, v55
	v_mul_f32_e32 v43, 0x3e3504f3, v36
	v_mov_b32_e32 v36, v34
	v_mov_b32_e32 v44, v34
	v_mov_b32_e32 v37, v35
	v_mov_b32_e32 v45, v35
	v_cndmask_b32_e64 v47, v47, v55, s[2:3]
	v_cndmask_b32_e64 v46, v46, v54, s[2:3]
	v_cndmask_b32_e64 v39, -v39, v39, s[2:3]
	v_cndmask_b32_e64 v38, -v38, v38, s[2:3]
	v_permlane32_swap_b32_e32 v36, v44
	v_permlane32_swap_b32_e32 v37, v45
	v_pk_add_f32 v[38:39], v[38:39], v[46:47]
	v_mov_b32_e32 v46, v48
	v_mov_b32_e32 v47, v48
	v_cndmask_b32_e64 v37, v37, v45, s[4:5]
	v_cndmask_b32_e64 v36, v36, v44, s[4:5]
	v_cndmask_b32_e64 v35, -v35, v35, s[4:5]
	v_cndmask_b32_e64 v34, -v34, v34, s[4:5]
	v_permlane32_swap_b32_e32 v46, v47
	v_pk_add_f32 v[34:35], v[34:35], v[36:37]
	v_cndmask_b32_e64 v46, v46, v47, s[4:5]
	v_cndmask_b32_e64 v47, -v48, v48, s[4:5]
	v_pk_mul_f32 v[36:37], v[34:35], s[38:39] op_sel_hi:[1,0]
	v_mov_b32_e32 v34, v38
	v_mov_b32_e32 v44, v38
	v_mov_b32_e32 v35, v39
	v_mov_b32_e32 v45, v39
	v_add_f32_e32 v46, v47, v46
	v_mov_b32_e32 v47, v49
	v_mov_b32_e32 v48, v49
	v_permlane32_swap_b32_e32 v34, v44
	v_permlane32_swap_b32_e32 v35, v45
	v_permlane32_swap_b32_e32 v47, v48
	v_cndmask_b32_e64 v35, v35, v45, s[4:5]
	v_cndmask_b32_e64 v34, v34, v44, s[4:5]
	v_cndmask_b32_e64 v39, -v39, v39, s[4:5]
	v_cndmask_b32_e64 v38, -v38, v38, s[4:5]
	v_cndmask_b32_e64 v47, v47, v48, s[4:5]
	v_cndmask_b32_e64 v48, -v49, v49, s[4:5]
	v_pk_add_f32 v[34:35], v[38:39], v[34:35]
	v_add_f32_e32 v47, v48, v47
	v_pk_mul_f32 v[38:39], v[34:35], s[38:39] op_sel_hi:[1,0]
	v_cvt_pk_bf16_f32 v34, v42, v43
	v_cvt_f32_i32_e32 v43, v30
	v_cvt_f32_i32_e32 v42, v26
	v_mul_f32_e32 v46, 0x3e3504f3, v46
	v_mul_f32_e32 v47, 0x3e3504f3, v47
	v_cvt_pk_bf16_f32 v35, v46, v47
	v_cvt_pk_bf16_f32 v36, v36, v37
	v_cvt_pk_bf16_f32 v37, v38, v39
	global_store_dwordx4 v[40:41], v[34:37], off nt
	v_cvt_f32_i32_e32 v30, v27
	s_nop 0
	v_pk_mul_f32 v[34:35], v[134:135], v[128:129] op_sel_hi:[1,0]
	v_add_u32_e32 v36, 0xa0, v154
	v_pk_mul_f32 v[34:35], v[34:35], v[42:43]
	s_nop 0
	v_mul_f32_e32 v26, 0xbfb8aa3b, v35
	v_exp_f32_e32 v26, v26
	s_nop 0
	v_add_f32_e32 v26, 1.0, v26
	v_rcp_f32_e32 v37, v26
	v_pk_mul_f32 v[26:27], v[62:63], v[128:129] op_sel_hi:[1,0]
	v_mul_f32_e32 v35, v35, v37
	v_pk_mul_f32 v[26:27], v[26:27], v[30:31]
	v_cvt_f32_i32_e32 v37, v32
	v_mul_f32_e32 v30, 0xbfb8aa3b, v27
	v_exp_f32_e32 v38, v30
	v_mad_i64_i32 v[30:31], s[12:13], v36, s79, v[156:157]
	v_cvt_f32_i32_e32 v32, v29
	v_add_f32_e32 v36, 1.0, v38
	v_rcp_f32_e32 v38, v36
	v_cvt_f32_i32_e32 v36, v28
	v_mul_f32_e32 v40, v34, v35
	v_mul_f32_e32 v27, v27, v38
	v_pk_mul_f32 v[38:39], v[132:133], v[128:129] op_sel_hi:[1,0]
	s_nop 0
	v_pk_mul_f32 v[36:37], v[38:39], v[36:37]
	v_mul_f32_e32 v38, v26, v27
	v_mul_f32_e32 v28, 0xbfb8aa3b, v37
	v_exp_f32_e32 v28, v28
	v_pk_mul_f32 v[26:27], v[64:65], v[128:129] op_sel_hi:[1,0]
	v_add_f32_e32 v28, 1.0, v28
	v_pk_mul_f32 v[26:27], v[26:27], v[32:33]
	v_rcp_f32_e32 v39, v28
	v_mul_f32_e32 v29, 0xbfb8aa3b, v27
	v_exp_f32_e32 v32, v29
	v_cvt_f32_i32_e32 v29, v22
	v_cvt_f32_i32_e32 v28, v18
	v_add_f32_e32 v18, 1.0, v32
	v_pk_mul_f32 v[32:33], v[130:131], v[128:129] op_sel_hi:[1,0]
	v_rcp_f32_e32 v18, v18
	v_pk_mul_f32 v[28:29], v[32:33], v[28:29]
	v_mul_f32_e32 v32, v37, v39
	v_mul_f32_e32 v22, 0xbfb8aa3b, v29
	v_exp_f32_e32 v22, v22
	v_mul_f32_e32 v18, v27, v18
	v_mul_f32_e32 v37, v26, v18
	v_mul_f32_e32 v33, v36, v32
	v_add_f32_e32 v22, 1.0, v22
	v_rcp_f32_e32 v27, v22
	v_cvt_f32_i32_e32 v22, v19
	v_pk_mul_f32 v[18:19], v[50:51], v[128:129] op_sel_hi:[1,0]
	v_mul_f32_e32 v29, v29, v27
	v_pk_mul_f32 v[18:19], v[18:19], v[22:23]
	v_cvt_f32_i32_e32 v23, v24
	v_mul_f32_e32 v22, 0xbfb8aa3b, v19
	v_exp_f32_e32 v26, v22
	v_cvt_f32_i32_e32 v22, v20
	v_cvt_f32_i32_e32 v24, v21
	v_mul_f32_e32 v39, v28, v29
	v_add_f32_e32 v20, 1.0, v26
	v_pk_mul_f32 v[26:27], v[126:127], v[128:129] op_sel_hi:[1,0]
	v_rcp_f32_e32 v41, v20
	v_pk_mul_f32 v[22:23], v[26:27], v[22:23]
	v_mul_f32_e32 v19, v19, v41
	v_mul_f32_e32 v20, 0xbfb8aa3b, v23
	v_exp_f32_e32 v26, v20
	v_pk_mul_f32 v[20:21], v[52:53], v[128:129] op_sel_hi:[1,0]
	v_mul_f32_e32 v27, v18, v19
	v_pk_mul_f32 v[20:21], v[20:21], v[24:25]
	v_add_f32_e32 v25, 1.0, v26
	v_mul_f32_e32 v24, 0xbfb8aa3b, v21
	v_exp_f32_e32 v24, v24
	v_rcp_f32_e32 v25, v25
	v_fma_f32 v19, v34, v35, -v38
	v_add_f32_e32 v26, v39, v27
	v_add_f32_e32 v24, 1.0, v24
	v_rcp_f32_e32 v24, v24
	v_mul_f32_e32 v23, v23, v25
	v_mul_f32_e32 v41, v22, v23
	v_fma_f32 v27, v28, v29, -v27
	v_mul_f32_e32 v18, v21, v24
	v_mul_f32_e32 v42, v20, v18
	v_add_f32_e32 v18, v40, v38
	v_add_f32_e32 v20, v33, v37
	v_fma_f32 v21, v36, v32, -v37
	v_add_f32_e32 v28, v41, v42
	v_fma_f32 v29, v22, v23, -v42
	v_pk_add_f32 v[22:23], v[18:19], v[20:21] neg_lo:[0,1] neg_hi:[0,1]
	v_pk_add_f32 v[18:19], v[18:19], v[20:21]
	v_pk_add_f32 v[20:21], v[26:27], v[28:29]
	v_lshl_add_u64 v[24:25], v[30:31], 0, v[124:125]
	v_pk_add_f32 v[30:31], v[26:27], v[28:29] neg_lo:[0,1] neg_hi:[0,1]
	v_pk_add_f32 v[26:27], v[18:19], v[20:21]
	v_pk_add_f32 v[18:19], v[18:19], v[20:21] neg_lo:[0,1] neg_hi:[0,1]
	v_mov_b32_e32 v20, v26
	v_mov_b32_e32 v21, v26
	s_nop 1
	v_permlane16_swap_b32_e32 v20, v21
	v_cndmask_b32_e64 v20, v20, v21, s[2:3]
	v_cndmask_b32_e64 v21, -v26, v26, s[2:3]
	v_add_f32_e32 v26, v21, v20
	v_mov_b32_e32 v20, v27
	v_mov_b32_e32 v21, v27
	s_nop 1
	v_permlane16_swap_b32_e32 v20, v21
	v_cndmask_b32_e64 v20, v20, v21, s[2:3]
	v_cndmask_b32_e64 v21, -v27, v27, s[2:3]
	v_add_f32_e32 v27, v21, v20
	v_mov_b32_e32 v20, v18
	v_mov_b32_e32 v28, v18
	v_mov_b32_e32 v21, v19
	v_mov_b32_e32 v29, v19
	v_permlane16_swap_b32_e32 v20, v28
	s_nop 0
	v_permlane16_swap_b32_e32 v21, v29
	v_cndmask_b32_e64 v21, v21, v29, s[2:3]
	v_cndmask_b32_e64 v20, v20, v28, s[2:3]
	v_cndmask_b32_e64 v19, -v19, v19, s[2:3]
	v_cndmask_b32_e64 v18, -v18, v18, s[2:3]
	v_pk_add_f32 v[32:33], v[22:23], v[30:31]
	v_pk_add_f32 v[18:19], v[18:19], v[20:21]
	v_mov_b32_e32 v20, v26
	v_mov_b32_e32 v21, v26
	v_pk_add_f32 v[22:23], v[22:23], v[30:31] neg_lo:[0,1] neg_hi:[0,1]
	v_mov_b32_e32 v30, v32
	v_mov_b32_e32 v31, v32
	v_permlane32_swap_b32_e32 v20, v21
	s_nop 0
	v_permlane16_swap_b32_e32 v30, v31
	v_cndmask_b32_e64 v20, v20, v21, s[4:5]
	v_cndmask_b32_e64 v21, -v26, v26, s[4:5]
	v_cndmask_b32_e64 v30, v30, v31, s[2:3]
	v_cndmask_b32_e64 v31, -v32, v32, s[2:3]
	v_add_f32_e32 v20, v21, v20
	v_add_f32_e32 v32, v31, v30
	v_mov_b32_e32 v30, v33
	v_mov_b32_e32 v31, v33
	v_mul_f32_e32 v26, 0x3e3504f3, v20
	v_mov_b32_e32 v20, v27
	v_mov_b32_e32 v21, v27
	v_permlane16_swap_b32_e32 v30, v31
	s_nop 0
	v_permlane32_swap_b32_e32 v20, v21
	v_cndmask_b32_e64 v30, v30, v31, s[2:3]
	v_cndmask_b32_e64 v31, -v33, v33, s[2:3]
	v_cndmask_b32_e64 v20, v20, v21, s[4:5]
	v_cndmask_b32_e64 v21, -v27, v27, s[4:5]
	v_add_f32_e32 v33, v31, v30
	v_mov_b32_e32 v30, v22
	v_mov_b32_e32 v34, v22
	v_mov_b32_e32 v31, v23
	v_mov_b32_e32 v35, v23
	v_add_f32_e32 v20, v21, v20
	v_permlane16_swap_b32_e32 v30, v34
	v_permlane16_swap_b32_e32 v31, v35
	v_mul_f32_e32 v27, 0x3e3504f3, v20
	v_mov_b32_e32 v20, v18
	v_mov_b32_e32 v28, v18
	v_mov_b32_e32 v21, v19
	v_mov_b32_e32 v29, v19
	v_cndmask_b32_e64 v31, v31, v35, s[2:3]
	v_cndmask_b32_e64 v30, v30, v34, s[2:3]
	v_cndmask_b32_e64 v23, -v23, v23, s[2:3]
	v_cndmask_b32_e64 v22, -v22, v22, s[2:3]
	v_permlane32_swap_b32_e32 v20, v28
	v_permlane32_swap_b32_e32 v21, v29
	v_pk_add_f32 v[22:23], v[22:23], v[30:31]
	v_mov_b32_e32 v30, v32
	v_mov_b32_e32 v31, v32
	v_cndmask_b32_e64 v21, v21, v29, s[4:5]
	v_cndmask_b32_e64 v20, v20, v28, s[4:5]
	v_cndmask_b32_e64 v19, -v19, v19, s[4:5]
	v_cndmask_b32_e64 v18, -v18, v18, s[4:5]
	v_permlane32_swap_b32_e32 v30, v31
	v_pk_add_f32 v[18:19], v[18:19], v[20:21]
	v_cndmask_b32_e64 v30, v30, v31, s[4:5]
	v_cndmask_b32_e64 v31, -v32, v32, s[4:5]
	v_pk_mul_f32 v[20:21], v[18:19], s[38:39] op_sel_hi:[1,0]
	v_mov_b32_e32 v18, v22
	v_mov_b32_e32 v28, v22
	v_mov_b32_e32 v19, v23
	v_mov_b32_e32 v29, v23
	v_add_f32_e32 v30, v31, v30
	v_mov_b32_e32 v31, v33
	v_mov_b32_e32 v32, v33
	v_permlane32_swap_b32_e32 v18, v28
	v_permlane32_swap_b32_e32 v19, v29
	v_permlane32_swap_b32_e32 v31, v32
	v_cndmask_b32_e64 v19, v19, v29, s[4:5]
	v_cndmask_b32_e64 v18, v18, v28, s[4:5]
	v_cndmask_b32_e64 v23, -v23, v23, s[4:5]
	v_cndmask_b32_e64 v22, -v22, v22, s[4:5]
	v_cndmask_b32_e64 v31, v31, v32, s[4:5]
	v_cndmask_b32_e64 v32, -v33, v33, s[4:5]
	v_pk_add_f32 v[18:19], v[22:23], v[18:19]
	v_add_f32_e32 v31, v32, v31
	v_pk_mul_f32 v[22:23], v[18:19], s[38:39] op_sel_hi:[1,0]
	v_cvt_pk_bf16_f32 v18, v26, v27
	v_cvt_f32_i32_e32 v27, v14
	v_cvt_f32_i32_e32 v26, v10
	v_mul_f32_e32 v30, 0x3e3504f3, v30
	v_mul_f32_e32 v31, 0x3e3504f3, v31
	v_cvt_pk_bf16_f32 v19, v30, v31
	v_cvt_pk_bf16_f32 v20, v20, v21
	v_cvt_pk_bf16_f32 v21, v22, v23
	global_store_dwordx4 v[24:25], v[18:21], off nt
	v_cvt_f32_i32_e32 v14, v11
	s_nop 0
	v_pk_mul_f32 v[18:19], v[134:135], v[122:123] op_sel_hi:[1,0]
	v_add_u32_e32 v20, 0xb0, v154
	v_pk_mul_f32 v[18:19], v[18:19], v[26:27]
	s_nop 0
	v_mul_f32_e32 v10, 0xbfb8aa3b, v19
	v_exp_f32_e32 v10, v10
	s_nop 0
	v_add_f32_e32 v10, 1.0, v10
	v_rcp_f32_e32 v21, v10
	v_pk_mul_f32 v[10:11], v[62:63], v[122:123] op_sel_hi:[1,0]
	v_mul_f32_e32 v19, v19, v21
	v_pk_mul_f32 v[10:11], v[10:11], v[14:15]
	v_cvt_f32_i32_e32 v21, v16
	v_mul_f32_e32 v14, 0xbfb8aa3b, v11
	v_exp_f32_e32 v22, v14
	v_mad_i64_i32 v[14:15], s[12:13], v20, s79, v[156:157]
	v_cvt_f32_i32_e32 v16, v13
	v_add_f32_e32 v20, 1.0, v22
	v_rcp_f32_e32 v22, v20
	v_cvt_f32_i32_e32 v20, v12
	v_mul_f32_e32 v24, v18, v19
	v_mul_f32_e32 v11, v11, v22
	v_pk_mul_f32 v[22:23], v[132:133], v[122:123] op_sel_hi:[1,0]
	s_nop 0
	v_pk_mul_f32 v[20:21], v[22:23], v[20:21]
	v_mul_f32_e32 v22, v10, v11
	v_mul_f32_e32 v12, 0xbfb8aa3b, v21
	v_exp_f32_e32 v12, v12
	v_pk_mul_f32 v[10:11], v[64:65], v[122:123] op_sel_hi:[1,0]
	v_add_f32_e32 v12, 1.0, v12
	v_pk_mul_f32 v[10:11], v[10:11], v[16:17]
	v_rcp_f32_e32 v23, v12
	v_mul_f32_e32 v13, 0xbfb8aa3b, v11
	v_exp_f32_e32 v16, v13
	v_cvt_f32_i32_e32 v13, v6
	v_cvt_f32_i32_e32 v12, v2
	v_add_f32_e32 v2, 1.0, v16
	v_pk_mul_f32 v[16:17], v[130:131], v[122:123] op_sel_hi:[1,0]
	v_rcp_f32_e32 v2, v2
	v_pk_mul_f32 v[12:13], v[16:17], v[12:13]
	v_mul_f32_e32 v16, v21, v23
	v_mul_f32_e32 v6, 0xbfb8aa3b, v13
	v_exp_f32_e32 v6, v6
	v_mul_f32_e32 v2, v11, v2
	v_mul_f32_e32 v21, v10, v2
	v_mul_f32_e32 v17, v20, v16
	v_add_f32_e32 v6, 1.0, v6
	v_rcp_f32_e32 v11, v6
	v_cvt_f32_i32_e32 v6, v3
	v_pk_mul_f32 v[2:3], v[50:51], v[122:123] op_sel_hi:[1,0]
	v_mul_f32_e32 v13, v13, v11
	v_pk_mul_f32 v[2:3], v[2:3], v[6:7]
	v_cvt_f32_i32_e32 v7, v8
	v_mul_f32_e32 v6, 0xbfb8aa3b, v3
	v_exp_f32_e32 v10, v6
	v_cvt_f32_i32_e32 v6, v4
	v_cvt_f32_i32_e32 v8, v5
	v_mul_f32_e32 v23, v12, v13
	v_add_f32_e32 v4, 1.0, v10
	v_pk_mul_f32 v[10:11], v[126:127], v[122:123] op_sel_hi:[1,0]
	v_rcp_f32_e32 v25, v4
	v_pk_mul_f32 v[6:7], v[10:11], v[6:7]
	v_mul_f32_e32 v3, v3, v25
	v_mul_f32_e32 v4, 0xbfb8aa3b, v7
	v_exp_f32_e32 v10, v4
	v_pk_mul_f32 v[4:5], v[52:53], v[122:123] op_sel_hi:[1,0]
	v_mul_f32_e32 v11, v2, v3
	v_pk_mul_f32 v[4:5], v[4:5], v[8:9]
	v_add_f32_e32 v9, 1.0, v10
	v_mul_f32_e32 v8, 0xbfb8aa3b, v5
	v_exp_f32_e32 v8, v8
	v_rcp_f32_e32 v9, v9
	v_fma_f32 v3, v18, v19, -v22
	v_add_f32_e32 v10, v23, v11
	v_add_f32_e32 v8, 1.0, v8
	v_rcp_f32_e32 v8, v8
	v_mul_f32_e32 v7, v7, v9
	v_mul_f32_e32 v25, v6, v7
	v_fma_f32 v11, v12, v13, -v11
	v_mul_f32_e32 v2, v5, v8
	v_mul_f32_e32 v26, v4, v2
	v_add_f32_e32 v2, v24, v22
	v_add_f32_e32 v4, v17, v21
	v_fma_f32 v5, v20, v16, -v21
	v_add_f32_e32 v12, v25, v26
	v_fma_f32 v13, v6, v7, -v26
	v_pk_add_f32 v[6:7], v[2:3], v[4:5] neg_lo:[0,1] neg_hi:[0,1]
	v_pk_add_f32 v[2:3], v[2:3], v[4:5]
	v_pk_add_f32 v[4:5], v[10:11], v[12:13]
	v_lshl_add_u64 v[8:9], v[14:15], 0, v[124:125]
	v_pk_add_f32 v[14:15], v[10:11], v[12:13] neg_lo:[0,1] neg_hi:[0,1]
	v_pk_add_f32 v[10:11], v[2:3], v[4:5]
	v_pk_add_f32 v[2:3], v[2:3], v[4:5] neg_lo:[0,1] neg_hi:[0,1]
	v_mov_b32_e32 v4, v10
	v_mov_b32_e32 v5, v10
	s_nop 1
	v_permlane16_swap_b32_e32 v4, v5
	v_cndmask_b32_e64 v4, v4, v5, s[2:3]
	v_cndmask_b32_e64 v5, -v10, v10, s[2:3]
	v_add_f32_e32 v10, v5, v4
	v_mov_b32_e32 v4, v11
	v_mov_b32_e32 v5, v11
	s_nop 1
	v_permlane16_swap_b32_e32 v4, v5
	v_cndmask_b32_e64 v4, v4, v5, s[2:3]
	v_cndmask_b32_e64 v5, -v11, v11, s[2:3]
	v_add_f32_e32 v11, v5, v4
	v_mov_b32_e32 v4, v2
	v_mov_b32_e32 v12, v2
	v_mov_b32_e32 v5, v3
	v_mov_b32_e32 v13, v3
	v_permlane16_swap_b32_e32 v4, v12
	s_nop 0
	v_permlane16_swap_b32_e32 v5, v13
	v_pk_add_f32 v[16:17], v[6:7], v[14:15]
	v_cndmask_b32_e64 v5, v5, v13, s[2:3]
	v_cndmask_b32_e64 v4, v4, v12, s[2:3]
	v_cndmask_b32_e64 v3, -v3, v3, s[2:3]
	v_cndmask_b32_e64 v2, -v2, v2, s[2:3]
	v_pk_add_f32 v[6:7], v[6:7], v[14:15] neg_lo:[0,1] neg_hi:[0,1]
	v_mov_b32_e32 v14, v16
	v_mov_b32_e32 v15, v16
	v_pk_add_f32 v[2:3], v[2:3], v[4:5]
	v_mov_b32_e32 v4, v10
	v_mov_b32_e32 v5, v10
	v_permlane16_swap_b32_e32 v14, v15
	s_nop 0
	v_permlane32_swap_b32_e32 v4, v5
	v_cndmask_b32_e64 v14, v14, v15, s[2:3]
	v_cndmask_b32_e64 v15, -v16, v16, s[2:3]
	v_cndmask_b32_e64 v4, v4, v5, s[4:5]
	v_cndmask_b32_e64 v5, -v10, v10, s[4:5]
	v_add_f32_e32 v16, v15, v14
	v_mov_b32_e32 v14, v17
	v_mov_b32_e32 v15, v17
	v_add_f32_e32 v4, v5, v4
	s_nop 0
	v_permlane16_swap_b32_e32 v14, v15
	v_mul_f32_e32 v10, 0x3e3504f3, v4
	v_mov_b32_e32 v4, v11
	v_mov_b32_e32 v5, v11
	v_cndmask_b32_e64 v14, v14, v15, s[2:3]
	v_cndmask_b32_e64 v15, -v17, v17, s[2:3]
	v_permlane32_swap_b32_e32 v4, v5
	v_add_f32_e32 v17, v15, v14
	v_mov_b32_e32 v14, v6
	v_mov_b32_e32 v18, v6
	v_mov_b32_e32 v15, v7
	v_mov_b32_e32 v19, v7
	v_cndmask_b32_e64 v4, v4, v5, s[4:5]
	v_cndmask_b32_e64 v5, -v11, v11, s[4:5]
	v_permlane16_swap_b32_e32 v14, v18
	v_permlane16_swap_b32_e32 v15, v19
	v_add_f32_e32 v4, v5, v4
	v_cndmask_b32_e64 v15, v15, v19, s[2:3]
	v_cndmask_b32_e64 v14, v14, v18, s[2:3]
	v_cndmask_b32_e64 v7, -v7, v7, s[2:3]
	v_cndmask_b32_e64 v6, -v6, v6, s[2:3]
	v_mul_f32_e32 v11, 0x3e3504f3, v4
	v_mov_b32_e32 v4, v2
	v_mov_b32_e32 v12, v2
	v_mov_b32_e32 v5, v3
	v_mov_b32_e32 v13, v3
	v_pk_add_f32 v[6:7], v[6:7], v[14:15]
	v_mov_b32_e32 v14, v16
	v_mov_b32_e32 v15, v16
	v_permlane32_swap_b32_e32 v4, v12
	v_permlane32_swap_b32_e32 v5, v13
	v_permlane32_swap_b32_e32 v14, v15
	v_cndmask_b32_e64 v5, v5, v13, s[4:5]
	v_cndmask_b32_e64 v4, v4, v12, s[4:5]
	v_cndmask_b32_e64 v3, -v3, v3, s[4:5]
	v_cndmask_b32_e64 v2, -v2, v2, s[4:5]
	v_cndmask_b32_e64 v14, v14, v15, s[4:5]
	v_cndmask_b32_e64 v15, -v16, v16, s[4:5]
	v_pk_add_f32 v[2:3], v[2:3], v[4:5]
	v_add_f32_e32 v14, v15, v14
	v_mov_b32_e32 v15, v17
	v_mov_b32_e32 v16, v17
	v_pk_mul_f32 v[4:5], v[2:3], s[38:39] op_sel_hi:[1,0]
	v_mov_b32_e32 v2, v6
	v_mov_b32_e32 v12, v6
	v_mov_b32_e32 v3, v7
	v_mov_b32_e32 v13, v7
	v_permlane32_swap_b32_e32 v15, v16
	v_permlane32_swap_b32_e32 v2, v12
	v_permlane32_swap_b32_e32 v3, v13
	v_cndmask_b32_e64 v15, v15, v16, s[4:5]
	v_cndmask_b32_e64 v16, -v17, v17, s[4:5]
	v_cndmask_b32_e64 v3, v3, v13, s[4:5]
	v_cndmask_b32_e64 v2, v2, v12, s[4:5]
	v_cndmask_b32_e64 v7, -v7, v7, s[4:5]
	v_cndmask_b32_e64 v6, -v6, v6, s[4:5]
	v_add_f32_e32 v15, v16, v15
	v_pk_add_f32 v[2:3], v[6:7], v[2:3]
	v_mul_f32_e32 v14, 0x3e3504f3, v14
	v_mul_f32_e32 v15, 0x3e3504f3, v15
	v_pk_mul_f32 v[6:7], v[2:3], s[38:39] op_sel_hi:[1,0]
	v_cvt_pk_bf16_f32 v2, v10, v11
	v_cvt_pk_bf16_f32 v3, v14, v15
	v_cvt_pk_bf16_f32 v4, v4, v5
	v_cvt_pk_bf16_f32 v5, v6, v7
	global_store_dwordx4 v[8:9], v[2:5], off nt
	s_cbranch_vccnz .LBB0_907
	s_andn2_b64 vcc, exec, s[0:1]
	s_cbranch_vccnz .LBB0_906
	s_barrier
	s_branch .LBB0_906

.LBB0_918:
	s_cmpk_lg_i32 s94, 0x100
	s_cselect_b64 s[0:1], -1, 0
	s_cmpk_lt_i32 s62, 0xc0
	s_cselect_b64 s[2:3], -1, 0
	s_or_b64 s[0:1], s[2:3], s[0:1]
	s_and_b64 vcc, exec, s[0:1]
	s_cbranch_vccnz .LBB0_946
	s_add_i32 s100, s62, 0xffffff80
	s_waitcnt vmcnt(0) lgkmcnt(0)
	v_lshrrev_b32_e32 v1, 3, v178
	v_and_b32_e32 v2, 7, v178
	v_and_b32_e32 v3, 31, v178
	v_lshrrev_b32_e32 v175, 5, v178
	v_lshlrev_b32_e32 v176, 14, v1
	v_lshl_add_u32 v152, v2, 4, v176
	v_add_u32_e32 v153, 0x20000, v152
	v_add_u32_e32 v154, 0x40000, v152
	v_add_u32_e32 v155, 0x60000, v152
	v_add_u32_e32 v156, 0x80000, v152
	v_add_u32_e32 v157, 0xa0000, v152
	v_add_u32_e32 v158, 0xc0000, v152
	v_add_u32_e32 v159, 0xe0000, v152
	v_mul_u32_u24_e32 v172, 0x2b00, v3
	v_lshl_add_u32 v172, v175, 5, v172
	s_lshl_b32 s10, s92, 14
	v_mul_u32_u24_e32 v176, 0x84, v1
	v_lshl_add_u32 v176, v2, 4, v176
	v_add_u32_e32 v160, s10, v176
	v_add_u32_e32 v161, 0x420, v160
	v_add_u32_e32 v162, 0x840, v160
	v_add_u32_e32 v163, 0xc60, v160
	v_add_u32_e32 v164, 0x1080, v160
	v_add_u32_e32 v165, 0x14a0, v160
	v_add_u32_e32 v166, 0x18c0, v160
	v_add_u32_e32 v167, 0x1ce0, v160
	v_mul_u32_u24_e32 v176, 0x1080, v175
	v_lshl_add_u32 v176, v3, 2, v176
	v_add_u32_e32 v168, s10, v176
	v_add_u32_e32 v169, 0x420, v168
	v_add_u32_e32 v170, 0x840, v168
	v_add_u32_e32 v171, 0xc60, v168
	s_lshl_b32 s11, s92, 8
	v_lshl_add_u32 v177, v178, 2, s11
	v_add_u32_e32 v177, 0x3000, v177
	v_lshlrev_b32_e32 v176, 2, v3
	v_add_u32_e32 v1, 0x3000, v176
	s_lshl_b32 s10, s100, 7
	s_add_u32 s4, s48, s10
	s_addc_u32 s5, s49, 0
	s_mul_i32 s10, s100, 0x56000
	s_add_u32 s8, s54, s10
	s_addc_u32 s9, s55, 0
	s_add_u32 s8, s8, 0x13000000
	s_addc_u32 s9, s9, 0
	s_mov_b32 s12, 0x0c0c0400
	s_mov_b32 s13, 0x05040100
	s_lshl_b32 s99, s100, 7
	v_mov_b32_e32 v173, 0
	s_mov_b32 s0, s92
	s_add_i32 s1, s0, 0
	s_lshl_b32 s10, s1, 20
	s_add_u32 s2, s4, s10
	s_addc_u32 s3, s5, 0
	global_load_dwordx4 v[4:7], v152, s[2:3]
	global_load_dwordx4 v[8:11], v153, s[2:3]
	global_load_dwordx4 v[12:15], v154, s[2:3]
	global_load_dwordx4 v[16:19], v155, s[2:3]
	global_load_dwordx4 v[20:23], v156, s[2:3]
	global_load_dwordx4 v[24:27], v157, s[2:3]
	global_load_dwordx4 v[28:31], v158, s[2:3]
	global_load_dwordx4 v[32:35], v159, s[2:3]
	s_add_i32 s1, s0, 8
	s_lshl_b32 s10, s1, 20
	s_add_u32 s2, s4, s10
	s_addc_u32 s3, s5, 0
	global_load_dwordx4 v[36:39], v152, s[2:3]
	global_load_dwordx4 v[40:43], v153, s[2:3]
	global_load_dwordx4 v[44:47], v154, s[2:3]
	global_load_dwordx4 v[48:51], v155, s[2:3]
	global_load_dwordx4 v[52:55], v156, s[2:3]
	global_load_dwordx4 v[56:59], v157, s[2:3]
	global_load_dwordx4 v[60:63], v158, s[2:3]
	global_load_dwordx4 v[64:67], v159, s[2:3]
	s_add_i32 s1, s0, 16
	s_lshl_b32 s10, s1, 20
	s_add_u32 s2, s4, s10
	s_addc_u32 s3, s5, 0
	global_load_dwordx4 v[68:71], v152, s[2:3]
	global_load_dwordx4 v[72:75], v153, s[2:3]
	global_load_dwordx4 v[76:79], v154, s[2:3]
	global_load_dwordx4 v[80:83], v155, s[2:3]
	global_load_dwordx4 v[84:87], v156, s[2:3]
	global_load_dwordx4 v[88:91], v157, s[2:3]
	global_load_dwordx4 v[92:95], v158, s[2:3]
	global_load_dwordx4 v[96:99], v159, s[2:3]
.Lqa_loop1:
	s_waitcnt vmcnt(16)
	ds_write2_b32 v160, v4, v5 offset1:1
	ds_write2_b32 v160, v6, v7 offset0:2 offset1:3
	ds_write2_b32 v161, v8, v9 offset1:1
	ds_write2_b32 v161, v10, v11 offset0:2 offset1:3
	ds_write2_b32 v162, v12, v13 offset1:1
	ds_write2_b32 v162, v14, v15 offset0:2 offset1:3
	ds_write2_b32 v163, v16, v17 offset1:1
	ds_write2_b32 v163, v18, v19 offset0:2 offset1:3
	ds_write2_b32 v164, v20, v21 offset1:1
	ds_write2_b32 v164, v22, v23 offset0:2 offset1:3
	ds_write2_b32 v165, v24, v25 offset1:1
	ds_write2_b32 v165, v26, v27 offset0:2 offset1:3
	ds_write2_b32 v166, v28, v29 offset1:1
	ds_write2_b32 v166, v30, v31 offset0:2 offset1:3
	ds_write2_b32 v167, v32, v33 offset1:1
	ds_write2_b32 v167, v34, v35 offset0:2 offset1:3
	s_add_i32 s1, s0, 24
	s_cmp_lt_u32 s1, 172
	s_cselect_b32 s1, s1, s0
	s_lshl_b32 s10, s1, 20
	s_add_u32 s2, s4, s10
	s_addc_u32 s3, s5, 0
	global_load_dwordx4 v[4:7], v152, s[2:3]
	global_load_dwordx4 v[8:11], v153, s[2:3]
	global_load_dwordx4 v[12:15], v154, s[2:3]
	global_load_dwordx4 v[16:19], v155, s[2:3]
	global_load_dwordx4 v[20:23], v156, s[2:3]
	global_load_dwordx4 v[24:27], v157, s[2:3]
	global_load_dwordx4 v[28:31], v158, s[2:3]
	global_load_dwordx4 v[32:35], v159, s[2:3]
	ds_read2_b32 v[100:101], v168 offset1:33
	ds_read2_b32 v[102:103], v168 offset0:66 offset1:99
	ds_read2_b32 v[104:105], v168 offset0:132 offset1:165
	ds_read2_b32 v[106:107], v168 offset0:198 offset1:231
	ds_read2_b32 v[108:109], v169 offset1:33
	ds_read2_b32 v[110:111], v169 offset0:66 offset1:99
	ds_read2_b32 v[112:113], v169 offset0:132 offset1:165
	ds_read2_b32 v[114:115], v169 offset0:198 offset1:231
	ds_read2_b32 v[116:117], v170 offset1:33
	ds_read2_b32 v[118:119], v170 offset0:66 offset1:99
	ds_read2_b32 v[120:121], v170 offset0:132 offset1:165
	ds_read2_b32 v[122:123], v170 offset0:198 offset1:231
	ds_read2_b32 v[124:125], v171 offset1:33
	ds_read2_b32 v[126:127], v171 offset0:66 offset1:99
	ds_read2_b32 v[128:129], v171 offset0:132 offset1:165
	ds_read2_b32 v[130:131], v171 offset0:198 offset1:231
	s_waitcnt lgkmcnt(0)
	v_pk_add_f32 v[100:101], v[100:101], v[100:101] op_sel:[0,1] op_sel_hi:[0,1] neg_hi:[0,1]
	v_pk_add_f32 v[102:103], v[102:103], v[102:103] op_sel:[0,1] op_sel_hi:[0,1] neg_hi:[0,1]
	v_pk_add_f32 v[104:105], v[104:105], v[104:105] op_sel:[0,1] op_sel_hi:[0,1] neg_hi:[0,1]
	v_pk_add_f32 v[106:107], v[106:107], v[106:107] op_sel:[0,1] op_sel_hi:[0,1] neg_hi:[0,1]
	v_pk_add_f32 v[108:109], v[108:109], v[108:109] op_sel:[0,1] op_sel_hi:[0,1] neg_hi:[0,1]
	v_pk_add_f32 v[110:111], v[110:111], v[110:111] op_sel:[0,1] op_sel_hi:[0,1] neg_hi:[0,1]
	v_pk_add_f32 v[112:113], v[112:113], v[112:113] op_sel:[0,1] op_sel_hi:[0,1] neg_hi:[0,1]
	v_pk_add_f32 v[114:115], v[114:115], v[114:115] op_sel:[0,1] op_sel_hi:[0,1] neg_hi:[0,1]
	v_pk_add_f32 v[116:117], v[116:117], v[116:117] op_sel:[0,1] op_sel_hi:[0,1] neg_hi:[0,1]
	v_pk_add_f32 v[118:119], v[118:119], v[118:119] op_sel:[0,1] op_sel_hi:[0,1] neg_hi:[0,1]
	v_pk_add_f32 v[120:121], v[120:121], v[120:121] op_sel:[0,1] op_sel_hi:[0,1] neg_hi:[0,1]
	v_pk_add_f32 v[122:123], v[122:123], v[122:123] op_sel:[0,1] op_sel_hi:[0,1] neg_hi:[0,1]
	v_pk_add_f32 v[124:125], v[124:125], v[124:125] op_sel:[0,1] op_sel_hi:[0,1] neg_hi:[0,1]
	v_pk_add_f32 v[126:127], v[126:127], v[126:127] op_sel:[0,1] op_sel_hi:[0,1] neg_hi:[0,1]
	v_pk_add_f32 v[128:129], v[128:129], v[128:129] op_sel:[0,1] op_sel_hi:[0,1] neg_hi:[0,1]
	v_pk_add_f32 v[130:131], v[130:131], v[130:131] op_sel:[0,1] op_sel_hi:[0,1] neg_hi:[0,1]
	v_pk_add_f32 v[132:133], v[100:101], v[102:103] neg_lo:[0,1] neg_hi:[0,1]
	v_pk_add_f32 v[100:101], v[100:101], v[102:103]
	v_pk_add_f32 v[134:135], v[104:105], v[106:107] neg_lo:[0,1] neg_hi:[0,1]
	v_pk_add_f32 v[104:105], v[104:105], v[106:107]
	v_pk_add_f32 v[136:137], v[108:109], v[110:111] neg_lo:[0,1] neg_hi:[0,1]
	v_pk_add_f32 v[108:109], v[108:109], v[110:111]
	v_pk_add_f32 v[138:139], v[112:113], v[114:115] neg_lo:[0,1] neg_hi:[0,1]
	v_pk_add_f32 v[112:113], v[112:113], v[114:115]
	v_pk_add_f32 v[140:141], v[116:117], v[118:119] neg_lo:[0,1] neg_hi:[0,1]
	v_pk_add_f32 v[116:117], v[116:117], v[118:119]
	v_pk_add_f32 v[142:143], v[120:121], v[122:123] neg_lo:[0,1] neg_hi:[0,1]
	v_pk_add_f32 v[120:121], v[120:121], v[122:123]
	v_pk_add_f32 v[102:103], v[124:125], v[126:127] neg_lo:[0,1] neg_hi:[0,1]
	v_pk_add_f32 v[124:125], v[124:125], v[126:127]
	v_pk_add_f32 v[106:107], v[128:129], v[130:131] neg_lo:[0,1] neg_hi:[0,1]
	v_pk_add_f32 v[128:129], v[128:129], v[130:131]
	v_pk_add_f32 v[110:111], v[100:101], v[104:105] neg_lo:[0,1] neg_hi:[0,1]
	v_pk_add_f32 v[100:101], v[100:101], v[104:105]
	v_pk_add_f32 v[114:115], v[132:133], v[134:135] neg_lo:[0,1] neg_hi:[0,1]
	v_pk_add_f32 v[132:133], v[132:133], v[134:135]
	v_pk_add_f32 v[118:119], v[108:109], v[112:113] neg_lo:[0,1] neg_hi:[0,1]
	v_pk_add_f32 v[108:109], v[108:109], v[112:113]
	v_pk_add_f32 v[122:123], v[136:137], v[138:139] neg_lo:[0,1] neg_hi:[0,1]
	v_pk_add_f32 v[136:137], v[136:137], v[138:139]
	v_pk_add_f32 v[126:127], v[116:117], v[120:121] neg_lo:[0,1] neg_hi:[0,1]
	v_pk_add_f32 v[116:117], v[116:117], v[120:121]
	v_pk_add_f32 v[130:131], v[140:141], v[142:143] neg_lo:[0,1] neg_hi:[0,1]
	v_pk_add_f32 v[140:141], v[140:141], v[142:143]
	v_pk_add_f32 v[104:105], v[124:125], v[128:129] neg_lo:[0,1] neg_hi:[0,1]
	v_pk_add_f32 v[124:125], v[124:125], v[128:129]
	v_pk_add_f32 v[134:135], v[102:103], v[106:107] neg_lo:[0,1] neg_hi:[0,1]
	v_pk_add_f32 v[102:103], v[102:103], v[106:107]
	v_pk_add_f32 v[112:113], v[100:101], v[108:109] neg_lo:[0,1] neg_hi:[0,1]
	v_pk_add_f32 v[100:101], v[100:101], v[108:109]
	v_pk_add_f32 v[138:139], v[132:133], v[136:137] neg_lo:[0,1] neg_hi:[0,1]
	v_pk_add_f32 v[132:133], v[132:133], v[136:137]
	v_pk_add_f32 v[120:121], v[110:111], v[118:119] neg_lo:[0,1] neg_hi:[0,1]
	v_pk_add_f32 v[110:111], v[110:111], v[118:119]
	v_pk_add_f32 v[142:143], v[114:115], v[122:123] neg_lo:[0,1] neg_hi:[0,1]
	v_pk_add_f32 v[114:115], v[114:115], v[122:123]
	v_pk_add_f32 v[128:129], v[116:117], v[124:125] neg_lo:[0,1] neg_hi:[0,1]
	v_pk_add_f32 v[116:117], v[116:117], v[124:125]
	v_pk_add_f32 v[106:107], v[140:141], v[102:103] neg_lo:[0,1] neg_hi:[0,1]
	v_pk_add_f32 v[140:141], v[140:141], v[102:103]
	v_pk_add_f32 v[108:109], v[126:127], v[104:105] neg_lo:[0,1] neg_hi:[0,1]
	v_pk_add_f32 v[126:127], v[126:127], v[104:105]
	v_pk_add_f32 v[136:137], v[130:131], v[134:135] neg_lo:[0,1] neg_hi:[0,1]
	v_pk_add_f32 v[130:131], v[130:131], v[134:135]
	v_pk_add_f32 v[118:119], v[100:101], v[116:117] neg_lo:[0,1] neg_hi:[0,1]
	v_pk_add_f32 v[100:101], v[100:101], v[116:117]
	v_pk_add_f32 v[122:123], v[132:133], v[140:141] neg_lo:[0,1] neg_hi:[0,1]
	v_pk_add_f32 v[132:133], v[132:133], v[140:141]
	v_pk_add_f32 v[124:125], v[110:111], v[126:127] neg_lo:[0,1] neg_hi:[0,1]
	v_pk_add_f32 v[110:111], v[110:111], v[126:127]
	v_pk_add_f32 v[102:103], v[114:115], v[130:131] neg_lo:[0,1] neg_hi:[0,1]
	v_pk_add_f32 v[114:115], v[114:115], v[130:131]
	v_pk_add_f32 v[104:105], v[112:113], v[128:129] neg_lo:[0,1] neg_hi:[0,1]
	v_pk_add_f32 v[112:113], v[112:113], v[128:129]
	v_pk_add_f32 v[134:135], v[138:139], v[106:107] neg_lo:[0,1] neg_hi:[0,1]
	v_pk_add_f32 v[138:139], v[138:139], v[106:107]
	v_pk_add_f32 v[116:117], v[120:121], v[108:109] neg_lo:[0,1] neg_hi:[0,1]
	v_pk_add_f32 v[120:121], v[120:121], v[108:109]
	v_pk_add_f32 v[140:141], v[142:143], v[136:137] neg_lo:[0,1] neg_hi:[0,1]
	v_pk_add_f32 v[142:143], v[142:143], v[136:137]
	v_max3_f32 v173, v173, |v100|, |v101|
	v_max3_f32 v173, v173, |v132|, |v133|
	v_max3_f32 v173, v173, |v110|, |v111|
	v_max3_f32 v173, v173, |v114|, |v115|
	v_max3_f32 v173, v173, |v112|, |v113|
	v_max3_f32 v173, v173, |v138|, |v139|
	v_max3_f32 v173, v173, |v120|, |v121|
	v_max3_f32 v173, v173, |v142|, |v143|
	v_max3_f32 v173, v173, |v118|, |v119|
	v_max3_f32 v173, v173, |v122|, |v123|
	v_max3_f32 v173, v173, |v124|, |v125|
	v_max3_f32 v173, v173, |v102|, |v103|
	v_max3_f32 v173, v173, |v104|, |v105|
	v_max3_f32 v173, v173, |v134|, |v135|
	v_max3_f32 v173, v173, |v116|, |v117|
	v_max3_f32 v173, v173, |v140|, |v141|
	s_add_i32 s0, s0, 8
	s_cmp_ge_u32 s0, 172
	s_cbranch_scc1 .Lqa_done2
	s_waitcnt vmcnt(16)
	ds_write2_b32 v160, v36, v37 offset1:1
	ds_write2_b32 v160, v38, v39 offset0:2 offset1:3
	ds_write2_b32 v161, v40, v41 offset1:1
	ds_write2_b32 v161, v42, v43 offset0:2 offset1:3
	ds_write2_b32 v162, v44, v45 offset1:1
	ds_write2_b32 v162, v46, v47 offset0:2 offset1:3
	ds_write2_b32 v163, v48, v49 offset1:1
	ds_write2_b32 v163, v50, v51 offset0:2 offset1:3
	ds_write2_b32 v164, v52, v53 offset1:1
	ds_write2_b32 v164, v54, v55 offset0:2 offset1:3
	ds_write2_b32 v165, v56, v57 offset1:1
	ds_write2_b32 v165, v58, v59 offset0:2 offset1:3
	ds_write2_b32 v166, v60, v61 offset1:1
	ds_write2_b32 v166, v62, v63 offset0:2 offset1:3
	ds_write2_b32 v167, v64, v65 offset1:1
	ds_write2_b32 v167, v66, v67 offset0:2 offset1:3
	s_add_i32 s1, s0, 24
	s_cmp_lt_u32 s1, 172
	s_cselect_b32 s1, s1, s0
	s_lshl_b32 s10, s1, 20
	s_add_u32 s2, s4, s10
	s_addc_u32 s3, s5, 0
	global_load_dwordx4 v[36:39], v152, s[2:3]
	global_load_dwordx4 v[40:43], v153, s[2:3]
	global_load_dwordx4 v[44:47], v154, s[2:3]
	global_load_dwordx4 v[48:51], v155, s[2:3]
	global_load_dwordx4 v[52:55], v156, s[2:3]
	global_load_dwordx4 v[56:59], v157, s[2:3]
	global_load_dwordx4 v[60:63], v158, s[2:3]
	global_load_dwordx4 v[64:67], v159, s[2:3]
	ds_read2_b32 v[100:101], v168 offset1:33
	ds_read2_b32 v[102:103], v168 offset0:66 offset1:99
	ds_read2_b32 v[104:105], v168 offset0:132 offset1:165
	ds_read2_b32 v[106:107], v168 offset0:198 offset1:231
	ds_read2_b32 v[108:109], v169 offset1:33
	ds_read2_b32 v[110:111], v169 offset0:66 offset1:99
	ds_read2_b32 v[112:113], v169 offset0:132 offset1:165
	ds_read2_b32 v[114:115], v169 offset0:198 offset1:231
	ds_read2_b32 v[116:117], v170 offset1:33
	ds_read2_b32 v[118:119], v170 offset0:66 offset1:99
	ds_read2_b32 v[120:121], v170 offset0:132 offset1:165
	ds_read2_b32 v[122:123], v170 offset0:198 offset1:231
	ds_read2_b32 v[124:125], v171 offset1:33
	ds_read2_b32 v[126:127], v171 offset0:66 offset1:99
	ds_read2_b32 v[128:129], v171 offset0:132 offset1:165
	ds_read2_b32 v[130:131], v171 offset0:198 offset1:231
	s_waitcnt lgkmcnt(0)
	v_pk_add_f32 v[100:101], v[100:101], v[100:101] op_sel:[0,1] op_sel_hi:[0,1] neg_hi:[0,1]
	v_pk_add_f32 v[102:103], v[102:103], v[102:103] op_sel:[0,1] op_sel_hi:[0,1] neg_hi:[0,1]
	v_pk_add_f32 v[104:105], v[104:105], v[104:105] op_sel:[0,1] op_sel_hi:[0,1] neg_hi:[0,1]
	v_pk_add_f32 v[106:107], v[106:107], v[106:107] op_sel:[0,1] op_sel_hi:[0,1] neg_hi:[0,1]
	v_pk_add_f32 v[108:109], v[108:109], v[108:109] op_sel:[0,1] op_sel_hi:[0,1] neg_hi:[0,1]
	v_pk_add_f32 v[110:111], v[110:111], v[110:111] op_sel:[0,1] op_sel_hi:[0,1] neg_hi:[0,1]
	v_pk_add_f32 v[112:113], v[112:113], v[112:113] op_sel:[0,1] op_sel_hi:[0,1] neg_hi:[0,1]
	v_pk_add_f32 v[114:115], v[114:115], v[114:115] op_sel:[0,1] op_sel_hi:[0,1] neg_hi:[0,1]
	v_pk_add_f32 v[116:117], v[116:117], v[116:117] op_sel:[0,1] op_sel_hi:[0,1] neg_hi:[0,1]
	v_pk_add_f32 v[118:119], v[118:119], v[118:119] op_sel:[0,1] op_sel_hi:[0,1] neg_hi:[0,1]
	v_pk_add_f32 v[120:121], v[120:121], v[120:121] op_sel:[0,1] op_sel_hi:[0,1] neg_hi:[0,1]
	v_pk_add_f32 v[122:123], v[122:123], v[122:123] op_sel:[0,1] op_sel_hi:[0,1] neg_hi:[0,1]
	v_pk_add_f32 v[124:125], v[124:125], v[124:125] op_sel:[0,1] op_sel_hi:[0,1] neg_hi:[0,1]
	v_pk_add_f32 v[126:127], v[126:127], v[126:127] op_sel:[0,1] op_sel_hi:[0,1] neg_hi:[0,1]
	v_pk_add_f32 v[128:129], v[128:129], v[128:129] op_sel:[0,1] op_sel_hi:[0,1] neg_hi:[0,1]
	v_pk_add_f32 v[130:131], v[130:131], v[130:131] op_sel:[0,1] op_sel_hi:[0,1] neg_hi:[0,1]
	v_pk_add_f32 v[132:133], v[100:101], v[102:103] neg_lo:[0,1] neg_hi:[0,1]
	v_pk_add_f32 v[100:101], v[100:101], v[102:103]
	v_pk_add_f32 v[134:135], v[104:105], v[106:107] neg_lo:[0,1] neg_hi:[0,1]
	v_pk_add_f32 v[104:105], v[104:105], v[106:107]
	v_pk_add_f32 v[136:137], v[108:109], v[110:111] neg_lo:[0,1] neg_hi:[0,1]
	v_pk_add_f32 v[108:109], v[108:109], v[110:111]
	v_pk_add_f32 v[138:139], v[112:113], v[114:115] neg_lo:[0,1] neg_hi:[0,1]
	v_pk_add_f32 v[112:113], v[112:113], v[114:115]
	v_pk_add_f32 v[140:141], v[116:117], v[118:119] neg_lo:[0,1] neg_hi:[0,1]
	v_pk_add_f32 v[116:117], v[116:117], v[118:119]
	v_pk_add_f32 v[142:143], v[120:121], v[122:123] neg_lo:[0,1] neg_hi:[0,1]
	v_pk_add_f32 v[120:121], v[120:121], v[122:123]
	v_pk_add_f32 v[102:103], v[124:125], v[126:127] neg_lo:[0,1] neg_hi:[0,1]
	v_pk_add_f32 v[124:125], v[124:125], v[126:127]
	v_pk_add_f32 v[106:107], v[128:129], v[130:131] neg_lo:[0,1] neg_hi:[0,1]
	v_pk_add_f32 v[128:129], v[128:129], v[130:131]
	v_pk_add_f32 v[110:111], v[100:101], v[104:105] neg_lo:[0,1] neg_hi:[0,1]
	v_pk_add_f32 v[100:101], v[100:101], v[104:105]
	v_pk_add_f32 v[114:115], v[132:133], v[134:135] neg_lo:[0,1] neg_hi:[0,1]
	v_pk_add_f32 v[132:133], v[132:133], v[134:135]
	v_pk_add_f32 v[118:119], v[108:109], v[112:113] neg_lo:[0,1] neg_hi:[0,1]
	v_pk_add_f32 v[108:109], v[108:109], v[112:113]
	v_pk_add_f32 v[122:123], v[136:137], v[138:139] neg_lo:[0,1] neg_hi:[0,1]
	v_pk_add_f32 v[136:137], v[136:137], v[138:139]
	v_pk_add_f32 v[126:127], v[116:117], v[120:121] neg_lo:[0,1] neg_hi:[0,1]
	v_pk_add_f32 v[116:117], v[116:117], v[120:121]
	v_pk_add_f32 v[130:131], v[140:141], v[142:143] neg_lo:[0,1] neg_hi:[0,1]
	v_pk_add_f32 v[140:141], v[140:141], v[142:143]
	v_pk_add_f32 v[104:105], v[124:125], v[128:129] neg_lo:[0,1] neg_hi:[0,1]
	v_pk_add_f32 v[124:125], v[124:125], v[128:129]
	v_pk_add_f32 v[134:135], v[102:103], v[106:107] neg_lo:[0,1] neg_hi:[0,1]
	v_pk_add_f32 v[102:103], v[102:103], v[106:107]
	v_pk_add_f32 v[112:113], v[100:101], v[108:109] neg_lo:[0,1] neg_hi:[0,1]
	v_pk_add_f32 v[100:101], v[100:101], v[108:109]
	v_pk_add_f32 v[138:139], v[132:133], v[136:137] neg_lo:[0,1] neg_hi:[0,1]
	v_pk_add_f32 v[132:133], v[132:133], v[136:137]
	v_pk_add_f32 v[120:121], v[110:111], v[118:119] neg_lo:[0,1] neg_hi:[0,1]
	v_pk_add_f32 v[110:111], v[110:111], v[118:119]
	v_pk_add_f32 v[142:143], v[114:115], v[122:123] neg_lo:[0,1] neg_hi:[0,1]
	v_pk_add_f32 v[114:115], v[114:115], v[122:123]
	v_pk_add_f32 v[128:129], v[116:117], v[124:125] neg_lo:[0,1] neg_hi:[0,1]
	v_pk_add_f32 v[116:117], v[116:117], v[124:125]
	v_pk_add_f32 v[106:107], v[140:141], v[102:103] neg_lo:[0,1] neg_hi:[0,1]
	v_pk_add_f32 v[140:141], v[140:141], v[102:103]
	v_pk_add_f32 v[108:109], v[126:127], v[104:105] neg_lo:[0,1] neg_hi:[0,1]
	v_pk_add_f32 v[126:127], v[126:127], v[104:105]
	v_pk_add_f32 v[136:137], v[130:131], v[134:135] neg_lo:[0,1] neg_hi:[0,1]
	v_pk_add_f32 v[130:131], v[130:131], v[134:135]
	v_pk_add_f32 v[118:119], v[100:101], v[116:117] neg_lo:[0,1] neg_hi:[0,1]
	v_pk_add_f32 v[100:101], v[100:101], v[116:117]
	v_pk_add_f32 v[122:123], v[132:133], v[140:141] neg_lo:[0,1] neg_hi:[0,1]
	v_pk_add_f32 v[132:133], v[132:133], v[140:141]
	v_pk_add_f32 v[124:125], v[110:111], v[126:127] neg_lo:[0,1] neg_hi:[0,1]
	v_pk_add_f32 v[110:111], v[110:111], v[126:127]
	v_pk_add_f32 v[102:103], v[114:115], v[130:131] neg_lo:[0,1] neg_hi:[0,1]
	v_pk_add_f32 v[114:115], v[114:115], v[130:131]
	v_pk_add_f32 v[104:105], v[112:113], v[128:129] neg_lo:[0,1] neg_hi:[0,1]
	v_pk_add_f32 v[112:113], v[112:113], v[128:129]
	v_pk_add_f32 v[134:135], v[138:139], v[106:107] neg_lo:[0,1] neg_hi:[0,1]
	v_pk_add_f32 v[138:139], v[138:139], v[106:107]
	v_pk_add_f32 v[116:117], v[120:121], v[108:109] neg_lo:[0,1] neg_hi:[0,1]
	v_pk_add_f32 v[120:121], v[120:121], v[108:109]
	v_pk_add_f32 v[140:141], v[142:143], v[136:137] neg_lo:[0,1] neg_hi:[0,1]
	v_pk_add_f32 v[142:143], v[142:143], v[136:137]
	v_max3_f32 v173, v173, |v100|, |v101|
	v_max3_f32 v173, v173, |v132|, |v133|
	v_max3_f32 v173, v173, |v110|, |v111|
	v_max3_f32 v173, v173, |v114|, |v115|
	v_max3_f32 v173, v173, |v112|, |v113|
	v_max3_f32 v173, v173, |v138|, |v139|
	v_max3_f32 v173, v173, |v120|, |v121|
	v_max3_f32 v173, v173, |v142|, |v143|
	v_max3_f32 v173, v173, |v118|, |v119|
	v_max3_f32 v173, v173, |v122|, |v123|
	v_max3_f32 v173, v173, |v124|, |v125|
	v_max3_f32 v173, v173, |v102|, |v103|
	v_max3_f32 v173, v173, |v104|, |v105|
	v_max3_f32 v173, v173, |v134|, |v135|
	v_max3_f32 v173, v173, |v116|, |v117|
	v_max3_f32 v173, v173, |v140|, |v141|
	s_add_i32 s0, s0, 8
	s_cmp_ge_u32 s0, 172
	s_cbranch_scc1 .Lqa_done2
	s_waitcnt vmcnt(16)
	ds_write2_b32 v160, v68, v69 offset1:1
	ds_write2_b32 v160, v70, v71 offset0:2 offset1:3
	ds_write2_b32 v161, v72, v73 offset1:1
	ds_write2_b32 v161, v74, v75 offset0:2 offset1:3
	ds_write2_b32 v162, v76, v77 offset1:1
	ds_write2_b32 v162, v78, v79 offset0:2 offset1:3
	ds_write2_b32 v163, v80, v81 offset1:1
	ds_write2_b32 v163, v82, v83 offset0:2 offset1:3
	ds_write2_b32 v164, v84, v85 offset1:1
	ds_write2_b32 v164, v86, v87 offset0:2 offset1:3
	ds_write2_b32 v165, v88, v89 offset1:1
	ds_write2_b32 v165, v90, v91 offset0:2 offset1:3
	ds_write2_b32 v166, v92, v93 offset1:1
	ds_write2_b32 v166, v94, v95 offset0:2 offset1:3
	ds_write2_b32 v167, v96, v97 offset1:1
	ds_write2_b32 v167, v98, v99 offset0:2 offset1:3
	s_add_i32 s1, s0, 24
	s_cmp_lt_u32 s1, 172
	s_cselect_b32 s1, s1, s0
	s_lshl_b32 s10, s1, 20
	s_add_u32 s2, s4, s10
	s_addc_u32 s3, s5, 0
	global_load_dwordx4 v[68:71], v152, s[2:3]
	global_load_dwordx4 v[72:75], v153, s[2:3]
	global_load_dwordx4 v[76:79], v154, s[2:3]
	global_load_dwordx4 v[80:83], v155, s[2:3]
	global_load_dwordx4 v[84:87], v156, s[2:3]
	global_load_dwordx4 v[88:91], v157, s[2:3]
	global_load_dwordx4 v[92:95], v158, s[2:3]
	global_load_dwordx4 v[96:99], v159, s[2:3]
	ds_read2_b32 v[100:101], v168 offset1:33
	ds_read2_b32 v[102:103], v168 offset0:66 offset1:99
	ds_read2_b32 v[104:105], v168 offset0:132 offset1:165
	ds_read2_b32 v[106:107], v168 offset0:198 offset1:231
	ds_read2_b32 v[108:109], v169 offset1:33
	ds_read2_b32 v[110:111], v169 offset0:66 offset1:99
	ds_read2_b32 v[112:113], v169 offset0:132 offset1:165
	ds_read2_b32 v[114:115], v169 offset0:198 offset1:231
	ds_read2_b32 v[116:117], v170 offset1:33
	ds_read2_b32 v[118:119], v170 offset0:66 offset1:99
	ds_read2_b32 v[120:121], v170 offset0:132 offset1:165
	ds_read2_b32 v[122:123], v170 offset0:198 offset1:231
	ds_read2_b32 v[124:125], v171 offset1:33
	ds_read2_b32 v[126:127], v171 offset0:66 offset1:99
	ds_read2_b32 v[128:129], v171 offset0:132 offset1:165
	ds_read2_b32 v[130:131], v171 offset0:198 offset1:231
	s_waitcnt lgkmcnt(0)
	v_pk_add_f32 v[100:101], v[100:101], v[100:101] op_sel:[0,1] op_sel_hi:[0,1] neg_hi:[0,1]
	v_pk_add_f32 v[102:103], v[102:103], v[102:103] op_sel:[0,1] op_sel_hi:[0,1] neg_hi:[0,1]
	v_pk_add_f32 v[104:105], v[104:105], v[104:105] op_sel:[0,1] op_sel_hi:[0,1] neg_hi:[0,1]
	v_pk_add_f32 v[106:107], v[106:107], v[106:107] op_sel:[0,1] op_sel_hi:[0,1] neg_hi:[0,1]
	v_pk_add_f32 v[108:109], v[108:109], v[108:109] op_sel:[0,1] op_sel_hi:[0,1] neg_hi:[0,1]
	v_pk_add_f32 v[110:111], v[110:111], v[110:111] op_sel:[0,1] op_sel_hi:[0,1] neg_hi:[0,1]
	v_pk_add_f32 v[112:113], v[112:113], v[112:113] op_sel:[0,1] op_sel_hi:[0,1] neg_hi:[0,1]
	v_pk_add_f32 v[114:115], v[114:115], v[114:115] op_sel:[0,1] op_sel_hi:[0,1] neg_hi:[0,1]
	v_pk_add_f32 v[116:117], v[116:117], v[116:117] op_sel:[0,1] op_sel_hi:[0,1] neg_hi:[0,1]
	v_pk_add_f32 v[118:119], v[118:119], v[118:119] op_sel:[0,1] op_sel_hi:[0,1] neg_hi:[0,1]
	v_pk_add_f32 v[120:121], v[120:121], v[120:121] op_sel:[0,1] op_sel_hi:[0,1] neg_hi:[0,1]
	v_pk_add_f32 v[122:123], v[122:123], v[122:123] op_sel:[0,1] op_sel_hi:[0,1] neg_hi:[0,1]
	v_pk_add_f32 v[124:125], v[124:125], v[124:125] op_sel:[0,1] op_sel_hi:[0,1] neg_hi:[0,1]
	v_pk_add_f32 v[126:127], v[126:127], v[126:127] op_sel:[0,1] op_sel_hi:[0,1] neg_hi:[0,1]
	v_pk_add_f32 v[128:129], v[128:129], v[128:129] op_sel:[0,1] op_sel_hi:[0,1] neg_hi:[0,1]
	v_pk_add_f32 v[130:131], v[130:131], v[130:131] op_sel:[0,1] op_sel_hi:[0,1] neg_hi:[0,1]
	v_pk_add_f32 v[132:133], v[100:101], v[102:103] neg_lo:[0,1] neg_hi:[0,1]
	v_pk_add_f32 v[100:101], v[100:101], v[102:103]
	v_pk_add_f32 v[134:135], v[104:105], v[106:107] neg_lo:[0,1] neg_hi:[0,1]
	v_pk_add_f32 v[104:105], v[104:105], v[106:107]
	v_pk_add_f32 v[136:137], v[108:109], v[110:111] neg_lo:[0,1] neg_hi:[0,1]
	v_pk_add_f32 v[108:109], v[108:109], v[110:111]
	v_pk_add_f32 v[138:139], v[112:113], v[114:115] neg_lo:[0,1] neg_hi:[0,1]
	v_pk_add_f32 v[112:113], v[112:113], v[114:115]
	v_pk_add_f32 v[140:141], v[116:117], v[118:119] neg_lo:[0,1] neg_hi:[0,1]
	v_pk_add_f32 v[116:117], v[116:117], v[118:119]
	v_pk_add_f32 v[142:143], v[120:121], v[122:123] neg_lo:[0,1] neg_hi:[0,1]
	v_pk_add_f32 v[120:121], v[120:121], v[122:123]
	v_pk_add_f32 v[102:103], v[124:125], v[126:127] neg_lo:[0,1] neg_hi:[0,1]
	v_pk_add_f32 v[124:125], v[124:125], v[126:127]
	v_pk_add_f32 v[106:107], v[128:129], v[130:131] neg_lo:[0,1] neg_hi:[0,1]
	v_pk_add_f32 v[128:129], v[128:129], v[130:131]
	v_pk_add_f32 v[110:111], v[100:101], v[104:105] neg_lo:[0,1] neg_hi:[0,1]
	v_pk_add_f32 v[100:101], v[100:101], v[104:105]
	v_pk_add_f32 v[114:115], v[132:133], v[134:135] neg_lo:[0,1] neg_hi:[0,1]
	v_pk_add_f32 v[132:133], v[132:133], v[134:135]
	v_pk_add_f32 v[118:119], v[108:109], v[112:113] neg_lo:[0,1] neg_hi:[0,1]
	v_pk_add_f32 v[108:109], v[108:109], v[112:113]
	v_pk_add_f32 v[122:123], v[136:137], v[138:139] neg_lo:[0,1] neg_hi:[0,1]
	v_pk_add_f32 v[136:137], v[136:137], v[138:139]
	v_pk_add_f32 v[126:127], v[116:117], v[120:121] neg_lo:[0,1] neg_hi:[0,1]
	v_pk_add_f32 v[116:117], v[116:117], v[120:121]
	v_pk_add_f32 v[130:131], v[140:141], v[142:143] neg_lo:[0,1] neg_hi:[0,1]
	v_pk_add_f32 v[140:141], v[140:141], v[142:143]
	v_pk_add_f32 v[104:105], v[124:125], v[128:129] neg_lo:[0,1] neg_hi:[0,1]
	v_pk_add_f32 v[124:125], v[124:125], v[128:129]
	v_pk_add_f32 v[134:135], v[102:103], v[106:107] neg_lo:[0,1] neg_hi:[0,1]
	v_pk_add_f32 v[102:103], v[102:103], v[106:107]
	v_pk_add_f32 v[112:113], v[100:101], v[108:109] neg_lo:[0,1] neg_hi:[0,1]
	v_pk_add_f32 v[100:101], v[100:101], v[108:109]
	v_pk_add_f32 v[138:139], v[132:133], v[136:137] neg_lo:[0,1] neg_hi:[0,1]
	v_pk_add_f32 v[132:133], v[132:133], v[136:137]
	v_pk_add_f32 v[120:121], v[110:111], v[118:119] neg_lo:[0,1] neg_hi:[0,1]
	v_pk_add_f32 v[110:111], v[110:111], v[118:119]
	v_pk_add_f32 v[142:143], v[114:115], v[122:123] neg_lo:[0,1] neg_hi:[0,1]
	v_pk_add_f32 v[114:115], v[114:115], v[122:123]
	v_pk_add_f32 v[128:129], v[116:117], v[124:125] neg_lo:[0,1] neg_hi:[0,1]
	v_pk_add_f32 v[116:117], v[116:117], v[124:125]
	v_pk_add_f32 v[106:107], v[140:141], v[102:103] neg_lo:[0,1] neg_hi:[0,1]
	v_pk_add_f32 v[140:141], v[140:141], v[102:103]
	v_pk_add_f32 v[108:109], v[126:127], v[104:105] neg_lo:[0,1] neg_hi:[0,1]
	v_pk_add_f32 v[126:127], v[126:127], v[104:105]
	v_pk_add_f32 v[136:137], v[130:131], v[134:135] neg_lo:[0,1] neg_hi:[0,1]
	v_pk_add_f32 v[130:131], v[130:131], v[134:135]
	v_pk_add_f32 v[118:119], v[100:101], v[116:117] neg_lo:[0,1] neg_hi:[0,1]
	v_pk_add_f32 v[100:101], v[100:101], v[116:117]
	v_pk_add_f32 v[122:123], v[132:133], v[140:141] neg_lo:[0,1] neg_hi:[0,1]
	v_pk_add_f32 v[132:133], v[132:133], v[140:141]
	v_pk_add_f32 v[124:125], v[110:111], v[126:127] neg_lo:[0,1] neg_hi:[0,1]
	v_pk_add_f32 v[110:111], v[110:111], v[126:127]
	v_pk_add_f32 v[102:103], v[114:115], v[130:131] neg_lo:[0,1] neg_hi:[0,1]
	v_pk_add_f32 v[114:115], v[114:115], v[130:131]
	v_pk_add_f32 v[104:105], v[112:113], v[128:129] neg_lo:[0,1] neg_hi:[0,1]
	v_pk_add_f32 v[112:113], v[112:113], v[128:129]
	v_pk_add_f32 v[134:135], v[138:139], v[106:107] neg_lo:[0,1] neg_hi:[0,1]
	v_pk_add_f32 v[138:139], v[138:139], v[106:107]
	v_pk_add_f32 v[116:117], v[120:121], v[108:109] neg_lo:[0,1] neg_hi:[0,1]
	v_pk_add_f32 v[120:121], v[120:121], v[108:109]
	v_pk_add_f32 v[140:141], v[142:143], v[136:137] neg_lo:[0,1] neg_hi:[0,1]
	v_pk_add_f32 v[142:143], v[142:143], v[136:137]
	v_max3_f32 v173, v173, |v100|, |v101|
	v_max3_f32 v173, v173, |v132|, |v133|
	v_max3_f32 v173, v173, |v110|, |v111|
	v_max3_f32 v173, v173, |v114|, |v115|
	v_max3_f32 v173, v173, |v112|, |v113|
	v_max3_f32 v173, v173, |v138|, |v139|
	v_max3_f32 v173, v173, |v120|, |v121|
	v_max3_f32 v173, v173, |v142|, |v143|
	v_max3_f32 v173, v173, |v118|, |v119|
	v_max3_f32 v173, v173, |v122|, |v123|
	v_max3_f32 v173, v173, |v124|, |v125|
	v_max3_f32 v173, v173, |v102|, |v103|
	v_max3_f32 v173, v173, |v104|, |v105|
	v_max3_f32 v173, v173, |v134|, |v135|
	v_max3_f32 v173, v173, |v116|, |v117|
	v_max3_f32 v173, v173, |v140|, |v141|
	s_add_i32 s0, s0, 8
	s_cmp_ge_u32 s0, 172
	s_cbranch_scc1 .Lqa_done2
	s_branch .Lqa_loop1
.Lqa_done2:
	s_waitcnt vmcnt(0)
	ds_write_b32 v177, v173
	s_waitcnt lgkmcnt(0)
	s_barrier
	ds_read2_b32 v[100:101], v1 offset0:0 offset1:32
	ds_read2_b32 v[102:103], v1 offset0:64 offset1:96
	ds_read2_b32 v[104:105], v1 offset0:128 offset1:160
	ds_read2_b32 v[106:107], v1 offset0:192 offset1:224
	v_add_u32_e32 v176, 0x400, v1
	ds_read2_b32 v[108:109], v176 offset0:0 offset1:32
	ds_read2_b32 v[110:111], v176 offset0:64 offset1:96
	ds_read2_b32 v[112:113], v176 offset0:128 offset1:160
	ds_read2_b32 v[114:115], v176 offset0:192 offset1:224
	s_waitcnt lgkmcnt(0)
	v_max3_f32 v2, v100, v101, v102
	v_max3_f32 v2, v2, v103, v104
	v_max3_f32 v2, v2, v105, v106
	v_max3_f32 v2, v2, v107, v108
	v_max3_f32 v2, v2, v109, v110
	v_max3_f32 v2, v2, v111, v112
	v_max3_f32 v2, v2, v113, v114
	v_max_f32_e32 v2, v2, v115
	v_mul_f32_e32 v2, 0x3e3504f3, v2
	s_mov_b32 s98, 0x42fe0000
	v_mul_f32_e32 v176, 0x3c010204, v2
	v_div_scale_f32 v116, s[100:101], v2, v2, s98
	v_rcp_f32_e32 v117, v116
	v_div_scale_f32 v118, vcc, s98, v2, s98
	v_fma_f32 v119, -v116, v117, 1.0
	v_fmac_f32_e32 v117, v119, v117
	v_mul_f32_e32 v119, v118, v117
	v_fma_f32 v174, -v116, v119, v118
	v_fmac_f32_e32 v119, v174, v117
	v_fma_f32 v116, -v116, v119, v118
	s_nop 1
	v_div_fmas_f32 v116, v116, v117, v119
	v_div_fixup_f32 v116, v116, v2, s98
	v_cmp_lt_f32_e32 vcc, 0, v2
	s_nop 1
	v_cndmask_b32_e32 v174, 0, v116, vcc
	s_cmp_lg_u32 s92, 0
	s_cbranch_scc1 .Lqa_nosc3
	v_cmp_gt_u32_e32 vcc, 32, v178
	s_and_saveexec_b64 s[100:101], vcc
	s_add_u32 s6, s54, s99
	s_addc_u32 s7, s55, 0
	s_add_u32 s6, s6, 0x194000
	s_addc_u32 s7, s7, 0
	v_lshlrev_b32_e32 v116, 2, v3
	global_store_dword v116, v176, s[6:7]
	s_mov_b64 exec, s[100:101]
.Lqa_nosc3:
	s_mov_b32 s98, 0x3e3504f3
	s_mov_b32 s99, 0x3e3504f3
	s_mov_b32 s100, 0x4b400000
	s_mov_b32 s101, 0x4b400000
	s_mov_b32 s0, s92
	s_add_i32 s1, s0, 0
	s_lshl_b32 s10, s1, 20
	s_add_u32 s2, s4, s10
	s_addc_u32 s3, s5, 0
	global_load_dwordx4 v[4:7], v152, s[2:3]
	global_load_dwordx4 v[8:11], v153, s[2:3]
	global_load_dwordx4 v[12:15], v154, s[2:3]
	global_load_dwordx4 v[16:19], v155, s[2:3]
	global_load_dwordx4 v[20:23], v156, s[2:3]
	global_load_dwordx4 v[24:27], v157, s[2:3]
	global_load_dwordx4 v[28:31], v158, s[2:3]
	global_load_dwordx4 v[32:35], v159, s[2:3]
	s_add_i32 s1, s0, 8
	s_lshl_b32 s10, s1, 20
	s_add_u32 s2, s4, s10
	s_addc_u32 s3, s5, 0
	global_load_dwordx4 v[36:39], v152, s[2:3]
	global_load_dwordx4 v[40:43], v153, s[2:3]
	global_load_dwordx4 v[44:47], v154, s[2:3]
	global_load_dwordx4 v[48:51], v155, s[2:3]
	global_load_dwordx4 v[52:55], v156, s[2:3]
	global_load_dwordx4 v[56:59], v157, s[2:3]
	global_load_dwordx4 v[60:63], v158, s[2:3]
	global_load_dwordx4 v[64:67], v159, s[2:3]
	s_add_i32 s1, s0, 16
	s_lshl_b32 s10, s1, 20
	s_add_u32 s2, s4, s10
	s_addc_u32 s3, s5, 0
	global_load_dwordx4 v[68:71], v152, s[2:3]
	global_load_dwordx4 v[72:75], v153, s[2:3]
	global_load_dwordx4 v[76:79], v154, s[2:3]
	global_load_dwordx4 v[80:83], v155, s[2:3]
	global_load_dwordx4 v[84:87], v156, s[2:3]
	global_load_dwordx4 v[88:91], v157, s[2:3]
	global_load_dwordx4 v[92:95], v158, s[2:3]
	global_load_dwordx4 v[96:99], v159, s[2:3]
.Lqa_loop4:
	s_waitcnt vmcnt(16)
	ds_write2_b32 v160, v4, v5 offset1:1
	ds_write2_b32 v160, v6, v7 offset0:2 offset1:3
	ds_write2_b32 v161, v8, v9 offset1:1
	ds_write2_b32 v161, v10, v11 offset0:2 offset1:3
	ds_write2_b32 v162, v12, v13 offset1:1
	ds_write2_b32 v162, v14, v15 offset0:2 offset1:3
	ds_write2_b32 v163, v16, v17 offset1:1
	ds_write2_b32 v163, v18, v19 offset0:2 offset1:3
	ds_write2_b32 v164, v20, v21 offset1:1
	ds_write2_b32 v164, v22, v23 offset0:2 offset1:3
	ds_write2_b32 v165, v24, v25 offset1:1
	ds_write2_b32 v165, v26, v27 offset0:2 offset1:3
	ds_write2_b32 v166, v28, v29 offset1:1
	ds_write2_b32 v166, v30, v31 offset0:2 offset1:3
	ds_write2_b32 v167, v32, v33 offset1:1
	ds_write2_b32 v167, v34, v35 offset0:2 offset1:3
	s_add_i32 s1, s0, 24
	s_cmp_lt_u32 s1, 172
	s_cselect_b32 s1, s1, s0
	s_lshl_b32 s10, s1, 20
	s_add_u32 s2, s4, s10
	s_addc_u32 s3, s5, 0
	global_load_dwordx4 v[4:7], v152, s[2:3]
	global_load_dwordx4 v[8:11], v153, s[2:3]
	global_load_dwordx4 v[12:15], v154, s[2:3]
	global_load_dwordx4 v[16:19], v155, s[2:3]
	global_load_dwordx4 v[20:23], v156, s[2:3]
	global_load_dwordx4 v[24:27], v157, s[2:3]
	global_load_dwordx4 v[28:31], v158, s[2:3]
	global_load_dwordx4 v[32:35], v159, s[2:3]
	ds_read2_b32 v[100:101], v168 offset1:33
	ds_read2_b32 v[102:103], v168 offset0:66 offset1:99
	ds_read2_b32 v[104:105], v168 offset0:132 offset1:165
	ds_read2_b32 v[106:107], v168 offset0:198 offset1:231
	ds_read2_b32 v[108:109], v169 offset1:33
	ds_read2_b32 v[110:111], v169 offset0:66 offset1:99
	ds_read2_b32 v[112:113], v169 offset0:132 offset1:165
	ds_read2_b32 v[114:115], v169 offset0:198 offset1:231
	ds_read2_b32 v[116:117], v170 offset1:33
	ds_read2_b32 v[118:119], v170 offset0:66 offset1:99
	ds_read2_b32 v[120:121], v170 offset0:132 offset1:165
	ds_read2_b32 v[122:123], v170 offset0:198 offset1:231
	ds_read2_b32 v[124:125], v171 offset1:33
	ds_read2_b32 v[126:127], v171 offset0:66 offset1:99
	ds_read2_b32 v[128:129], v171 offset0:132 offset1:165
	ds_read2_b32 v[130:131], v171 offset0:198 offset1:231
	s_lshl_b32 s10, s0, 6
	s_add_u32 s6, s8, s10
	s_addc_u32 s7, s9, 0
	s_waitcnt lgkmcnt(0)
	v_pk_add_f32 v[100:101], v[100:101], v[100:101] op_sel:[0,1] op_sel_hi:[0,1] neg_hi:[0,1]
	v_pk_add_f32 v[102:103], v[102:103], v[102:103] op_sel:[0,1] op_sel_hi:[0,1] neg_hi:[0,1]
	v_pk_add_f32 v[104:105], v[104:105], v[104:105] op_sel:[0,1] op_sel_hi:[0,1] neg_hi:[0,1]
	v_pk_add_f32 v[106:107], v[106:107], v[106:107] op_sel:[0,1] op_sel_hi:[0,1] neg_hi:[0,1]
	v_pk_add_f32 v[108:109], v[108:109], v[108:109] op_sel:[0,1] op_sel_hi:[0,1] neg_hi:[0,1]
	v_pk_add_f32 v[110:111], v[110:111], v[110:111] op_sel:[0,1] op_sel_hi:[0,1] neg_hi:[0,1]
	v_pk_add_f32 v[112:113], v[112:113], v[112:113] op_sel:[0,1] op_sel_hi:[0,1] neg_hi:[0,1]
	v_pk_add_f32 v[114:115], v[114:115], v[114:115] op_sel:[0,1] op_sel_hi:[0,1] neg_hi:[0,1]
	v_pk_add_f32 v[116:117], v[116:117], v[116:117] op_sel:[0,1] op_sel_hi:[0,1] neg_hi:[0,1]
	v_pk_add_f32 v[118:119], v[118:119], v[118:119] op_sel:[0,1] op_sel_hi:[0,1] neg_hi:[0,1]
	v_pk_add_f32 v[120:121], v[120:121], v[120:121] op_sel:[0,1] op_sel_hi:[0,1] neg_hi:[0,1]
	v_pk_add_f32 v[122:123], v[122:123], v[122:123] op_sel:[0,1] op_sel_hi:[0,1] neg_hi:[0,1]
	v_pk_add_f32 v[124:125], v[124:125], v[124:125] op_sel:[0,1] op_sel_hi:[0,1] neg_hi:[0,1]
	v_pk_add_f32 v[126:127], v[126:127], v[126:127] op_sel:[0,1] op_sel_hi:[0,1] neg_hi:[0,1]
	v_pk_add_f32 v[128:129], v[128:129], v[128:129] op_sel:[0,1] op_sel_hi:[0,1] neg_hi:[0,1]
	v_pk_add_f32 v[130:131], v[130:131], v[130:131] op_sel:[0,1] op_sel_hi:[0,1] neg_hi:[0,1]
	v_pk_add_f32 v[132:133], v[100:101], v[102:103] neg_lo:[0,1] neg_hi:[0,1]
	v_pk_add_f32 v[100:101], v[100:101], v[102:103]
	v_pk_add_f32 v[134:135], v[104:105], v[106:107] neg_lo:[0,1] neg_hi:[0,1]
	v_pk_add_f32 v[104:105], v[104:105], v[106:107]
	v_pk_add_f32 v[136:137], v[108:109], v[110:111] neg_lo:[0,1] neg_hi:[0,1]
	v_pk_add_f32 v[108:109], v[108:109], v[110:111]
	v_pk_add_f32 v[138:139], v[112:113], v[114:115] neg_lo:[0,1] neg_hi:[0,1]
	v_pk_add_f32 v[112:113], v[112:113], v[114:115]
	v_pk_add_f32 v[140:141], v[116:117], v[118:119] neg_lo:[0,1] neg_hi:[0,1]
	v_pk_add_f32 v[116:117], v[116:117], v[118:119]
	v_pk_add_f32 v[142:143], v[120:121], v[122:123] neg_lo:[0,1] neg_hi:[0,1]
	v_pk_add_f32 v[120:121], v[120:121], v[122:123]
	v_pk_add_f32 v[102:103], v[124:125], v[126:127] neg_lo:[0,1] neg_hi:[0,1]
	v_pk_add_f32 v[124:125], v[124:125], v[126:127]
	v_pk_add_f32 v[106:107], v[128:129], v[130:131] neg_lo:[0,1] neg_hi:[0,1]
	v_pk_add_f32 v[128:129], v[128:129], v[130:131]
	v_pk_add_f32 v[110:111], v[100:101], v[104:105] neg_lo:[0,1] neg_hi:[0,1]
	v_pk_add_f32 v[100:101], v[100:101], v[104:105]
	v_pk_add_f32 v[114:115], v[132:133], v[134:135] neg_lo:[0,1] neg_hi:[0,1]
	v_pk_add_f32 v[132:133], v[132:133], v[134:135]
	v_pk_add_f32 v[118:119], v[108:109], v[112:113] neg_lo:[0,1] neg_hi:[0,1]
	v_pk_add_f32 v[108:109], v[108:109], v[112:113]
	v_pk_add_f32 v[122:123], v[136:137], v[138:139] neg_lo:[0,1] neg_hi:[0,1]
	v_pk_add_f32 v[136:137], v[136:137], v[138:139]
	v_pk_add_f32 v[126:127], v[116:117], v[120:121] neg_lo:[0,1] neg_hi:[0,1]
	v_pk_add_f32 v[116:117], v[116:117], v[120:121]
	v_pk_add_f32 v[130:131], v[140:141], v[142:143] neg_lo:[0,1] neg_hi:[0,1]
	v_pk_add_f32 v[140:141], v[140:141], v[142:143]
	v_pk_add_f32 v[104:105], v[124:125], v[128:129] neg_lo:[0,1] neg_hi:[0,1]
	v_pk_add_f32 v[124:125], v[124:125], v[128:129]
	v_pk_add_f32 v[134:135], v[102:103], v[106:107] neg_lo:[0,1] neg_hi:[0,1]
	v_pk_add_f32 v[102:103], v[102:103], v[106:107]
	v_pk_add_f32 v[112:113], v[100:101], v[108:109] neg_lo:[0,1] neg_hi:[0,1]
	v_pk_add_f32 v[100:101], v[100:101], v[108:109]
	v_pk_add_f32 v[138:139], v[132:133], v[136:137] neg_lo:[0,1] neg_hi:[0,1]
	v_pk_add_f32 v[132:133], v[132:133], v[136:137]
	v_pk_add_f32 v[120:121], v[110:111], v[118:119] neg_lo:[0,1] neg_hi:[0,1]
	v_pk_add_f32 v[110:111], v[110:111], v[118:119]
	v_pk_add_f32 v[142:143], v[114:115], v[122:123] neg_lo:[0,1] neg_hi:[0,1]
	v_pk_add_f32 v[114:115], v[114:115], v[122:123]
	v_pk_add_f32 v[128:129], v[116:117], v[124:125] neg_lo:[0,1] neg_hi:[0,1]
	v_pk_add_f32 v[116:117], v[116:117], v[124:125]
	v_pk_add_f32 v[106:107], v[140:141], v[102:103] neg_lo:[0,1] neg_hi:[0,1]
	v_pk_add_f32 v[140:141], v[140:141], v[102:103]
	v_pk_add_f32 v[108:109], v[126:127], v[104:105] neg_lo:[0,1] neg_hi:[0,1]
	v_pk_add_f32 v[126:127], v[126:127], v[104:105]
	v_pk_add_f32 v[136:137], v[130:131], v[134:135] neg_lo:[0,1] neg_hi:[0,1]
	v_pk_add_f32 v[130:131], v[130:131], v[134:135]
	v_pk_add_f32 v[118:119], v[100:101], v[116:117] neg_lo:[0,1] neg_hi:[0,1]
	v_pk_add_f32 v[100:101], v[100:101], v[116:117]
	v_pk_add_f32 v[122:123], v[132:133], v[140:141] neg_lo:[0,1] neg_hi:[0,1]
	v_pk_add_f32 v[132:133], v[132:133], v[140:141]
	v_pk_add_f32 v[124:125], v[110:111], v[126:127] neg_lo:[0,1] neg_hi:[0,1]
	v_pk_add_f32 v[110:111], v[110:111], v[126:127]
	v_pk_add_f32 v[102:103], v[114:115], v[130:131] neg_lo:[0,1] neg_hi:[0,1]
	v_pk_add_f32 v[114:115], v[114:115], v[130:131]
	v_pk_add_f32 v[104:105], v[112:113], v[128:129] neg_lo:[0,1] neg_hi:[0,1]
	v_pk_add_f32 v[112:113], v[112:113], v[128:129]
	v_pk_add_f32 v[134:135], v[138:139], v[106:107] neg_lo:[0,1] neg_hi:[0,1]
	v_pk_add_f32 v[138:139], v[138:139], v[106:107]
	v_pk_add_f32 v[116:117], v[120:121], v[108:109] neg_lo:[0,1] neg_hi:[0,1]
	v_pk_add_f32 v[120:121], v[120:121], v[108:109]
	v_pk_add_f32 v[140:141], v[142:143], v[136:137] neg_lo:[0,1] neg_hi:[0,1]
	v_pk_add_f32 v[142:143], v[142:143], v[136:137]
	v_pk_mul_f32 v[100:101], v[100:101], s[98:99]
	v_pk_mul_f32 v[100:101], v[100:101], v[174:175] op_sel_hi:[1,0]
	v_pk_add_f32 v[100:101], v[100:101], s[100:101]
	v_pk_mul_f32 v[132:133], v[132:133], s[98:99]
	v_pk_mul_f32 v[132:133], v[132:133], v[174:175] op_sel_hi:[1,0]
	v_pk_add_f32 v[132:133], v[132:133], s[100:101]
	v_pk_mul_f32 v[110:111], v[110:111], s[98:99]
	v_pk_mul_f32 v[110:111], v[110:111], v[174:175] op_sel_hi:[1,0]
	v_pk_add_f32 v[110:111], v[110:111], s[100:101]
	v_pk_mul_f32 v[114:115], v[114:115], s[98:99]
	v_pk_mul_f32 v[114:115], v[114:115], v[174:175] op_sel_hi:[1,0]
	v_pk_add_f32 v[114:115], v[114:115], s[100:101]
	v_pk_mul_f32 v[112:113], v[112:113], s[98:99]
	v_pk_mul_f32 v[112:113], v[112:113], v[174:175] op_sel_hi:[1,0]
	v_pk_add_f32 v[112:113], v[112:113], s[100:101]
	v_pk_mul_f32 v[138:139], v[138:139], s[98:99]
	v_pk_mul_f32 v[138:139], v[138:139], v[174:175] op_sel_hi:[1,0]
	v_pk_add_f32 v[138:139], v[138:139], s[100:101]
	v_pk_mul_f32 v[120:121], v[120:121], s[98:99]
	v_pk_mul_f32 v[120:121], v[120:121], v[174:175] op_sel_hi:[1,0]
	v_pk_add_f32 v[120:121], v[120:121], s[100:101]
	v_pk_mul_f32 v[142:143], v[142:143], s[98:99]
	v_pk_mul_f32 v[142:143], v[142:143], v[174:175] op_sel_hi:[1,0]
	v_pk_add_f32 v[142:143], v[142:143], s[100:101]
	v_pk_mul_f32 v[118:119], v[118:119], s[98:99]
	v_pk_mul_f32 v[118:119], v[118:119], v[174:175] op_sel_hi:[1,0]
	v_pk_add_f32 v[118:119], v[118:119], s[100:101]
	v_pk_mul_f32 v[122:123], v[122:123], s[98:99]
	v_pk_mul_f32 v[122:123], v[122:123], v[174:175] op_sel_hi:[1,0]
	v_pk_add_f32 v[122:123], v[122:123], s[100:101]
	v_pk_mul_f32 v[124:125], v[124:125], s[98:99]
	v_pk_mul_f32 v[124:125], v[124:125], v[174:175] op_sel_hi:[1,0]
	v_pk_add_f32 v[124:125], v[124:125], s[100:101]
	v_pk_mul_f32 v[102:103], v[102:103], s[98:99]
	v_pk_mul_f32 v[102:103], v[102:103], v[174:175] op_sel_hi:[1,0]
	v_pk_add_f32 v[102:103], v[102:103], s[100:101]
	v_pk_mul_f32 v[104:105], v[104:105], s[98:99]
	v_pk_mul_f32 v[104:105], v[104:105], v[174:175] op_sel_hi:[1,0]
	v_pk_add_f32 v[104:105], v[104:105], s[100:101]
	v_pk_mul_f32 v[134:135], v[134:135], s[98:99]
	v_pk_mul_f32 v[134:135], v[134:135], v[174:175] op_sel_hi:[1,0]
	v_pk_add_f32 v[134:135], v[134:135], s[100:101]
	v_pk_mul_f32 v[116:117], v[116:117], s[98:99]
	v_pk_mul_f32 v[116:117], v[116:117], v[174:175] op_sel_hi:[1,0]
	v_pk_add_f32 v[116:117], v[116:117], s[100:101]
	v_pk_mul_f32 v[140:141], v[140:141], s[98:99]
	v_pk_mul_f32 v[140:141], v[140:141], v[174:175] op_sel_hi:[1,0]
	v_pk_add_f32 v[140:141], v[140:141], s[100:101]
	v_perm_b32 v100, v101, v100, s12
	v_perm_b32 v132, v133, v132, s12
	v_perm_b32 v144, v132, v100, s13
	v_perm_b32 v110, v111, v110, s12
	v_perm_b32 v114, v115, v114, s12
	v_perm_b32 v145, v114, v110, s13
	v_perm_b32 v112, v113, v112, s12
	v_perm_b32 v138, v139, v138, s12
	v_perm_b32 v146, v138, v112, s13
	v_perm_b32 v120, v121, v120, s12
	v_perm_b32 v142, v143, v142, s12
	v_perm_b32 v147, v142, v120, s13
	v_perm_b32 v118, v119, v118, s12
	v_perm_b32 v122, v123, v122, s12
	v_perm_b32 v148, v122, v118, s13
	v_perm_b32 v124, v125, v124, s12
	v_perm_b32 v102, v103, v102, s12
	v_perm_b32 v149, v102, v124, s13
	v_perm_b32 v104, v105, v104, s12
	v_perm_b32 v134, v135, v134, s12
	v_perm_b32 v150, v134, v104, s13
	v_perm_b32 v116, v117, v116, s12
	v_perm_b32 v140, v141, v140, s12
	v_perm_b32 v151, v140, v116, s13
	global_store_dwordx4 v172, v[144:147], s[6:7] nt
	global_store_dwordx4 v172, v[148:151], s[6:7] offset:16 nt
	s_add_i32 s0, s0, 8
	s_cmp_ge_u32 s0, 172
	s_cbranch_scc1 .Lqa_done5
	s_waitcnt vmcnt(16)
	ds_write2_b32 v160, v36, v37 offset1:1
	ds_write2_b32 v160, v38, v39 offset0:2 offset1:3
	ds_write2_b32 v161, v40, v41 offset1:1
	ds_write2_b32 v161, v42, v43 offset0:2 offset1:3
	ds_write2_b32 v162, v44, v45 offset1:1
	ds_write2_b32 v162, v46, v47 offset0:2 offset1:3
	ds_write2_b32 v163, v48, v49 offset1:1
	ds_write2_b32 v163, v50, v51 offset0:2 offset1:3
	ds_write2_b32 v164, v52, v53 offset1:1
	ds_write2_b32 v164, v54, v55 offset0:2 offset1:3
	ds_write2_b32 v165, v56, v57 offset1:1
	ds_write2_b32 v165, v58, v59 offset0:2 offset1:3
	ds_write2_b32 v166, v60, v61 offset1:1
	ds_write2_b32 v166, v62, v63 offset0:2 offset1:3
	ds_write2_b32 v167, v64, v65 offset1:1
	ds_write2_b32 v167, v66, v67 offset0:2 offset1:3
	s_add_i32 s1, s0, 24
	s_cmp_lt_u32 s1, 172
	s_cselect_b32 s1, s1, s0
	s_lshl_b32 s10, s1, 20
	s_add_u32 s2, s4, s10
	s_addc_u32 s3, s5, 0
	global_load_dwordx4 v[36:39], v152, s[2:3]
	global_load_dwordx4 v[40:43], v153, s[2:3]
	global_load_dwordx4 v[44:47], v154, s[2:3]
	global_load_dwordx4 v[48:51], v155, s[2:3]
	global_load_dwordx4 v[52:55], v156, s[2:3]
	global_load_dwordx4 v[56:59], v157, s[2:3]
	global_load_dwordx4 v[60:63], v158, s[2:3]
	global_load_dwordx4 v[64:67], v159, s[2:3]
	ds_read2_b32 v[100:101], v168 offset1:33
	ds_read2_b32 v[102:103], v168 offset0:66 offset1:99
	ds_read2_b32 v[104:105], v168 offset0:132 offset1:165
	ds_read2_b32 v[106:107], v168 offset0:198 offset1:231
	ds_read2_b32 v[108:109], v169 offset1:33
	ds_read2_b32 v[110:111], v169 offset0:66 offset1:99
	ds_read2_b32 v[112:113], v169 offset0:132 offset1:165
	ds_read2_b32 v[114:115], v169 offset0:198 offset1:231
	ds_read2_b32 v[116:117], v170 offset1:33
	ds_read2_b32 v[118:119], v170 offset0:66 offset1:99
	ds_read2_b32 v[120:121], v170 offset0:132 offset1:165
	ds_read2_b32 v[122:123], v170 offset0:198 offset1:231
	ds_read2_b32 v[124:125], v171 offset1:33
	ds_read2_b32 v[126:127], v171 offset0:66 offset1:99
	ds_read2_b32 v[128:129], v171 offset0:132 offset1:165
	ds_read2_b32 v[130:131], v171 offset0:198 offset1:231
	s_lshl_b32 s10, s0, 6
	s_add_u32 s6, s8, s10
	s_addc_u32 s7, s9, 0
	s_waitcnt lgkmcnt(0)
	v_pk_add_f32 v[100:101], v[100:101], v[100:101] op_sel:[0,1] op_sel_hi:[0,1] neg_hi:[0,1]
	v_pk_add_f32 v[102:103], v[102:103], v[102:103] op_sel:[0,1] op_sel_hi:[0,1] neg_hi:[0,1]
	v_pk_add_f32 v[104:105], v[104:105], v[104:105] op_sel:[0,1] op_sel_hi:[0,1] neg_hi:[0,1]
	v_pk_add_f32 v[106:107], v[106:107], v[106:107] op_sel:[0,1] op_sel_hi:[0,1] neg_hi:[0,1]
	v_pk_add_f32 v[108:109], v[108:109], v[108:109] op_sel:[0,1] op_sel_hi:[0,1] neg_hi:[0,1]
	v_pk_add_f32 v[110:111], v[110:111], v[110:111] op_sel:[0,1] op_sel_hi:[0,1] neg_hi:[0,1]
	v_pk_add_f32 v[112:113], v[112:113], v[112:113] op_sel:[0,1] op_sel_hi:[0,1] neg_hi:[0,1]
	v_pk_add_f32 v[114:115], v[114:115], v[114:115] op_sel:[0,1] op_sel_hi:[0,1] neg_hi:[0,1]
	v_pk_add_f32 v[116:117], v[116:117], v[116:117] op_sel:[0,1] op_sel_hi:[0,1] neg_hi:[0,1]
	v_pk_add_f32 v[118:119], v[118:119], v[118:119] op_sel:[0,1] op_sel_hi:[0,1] neg_hi:[0,1]
	v_pk_add_f32 v[120:121], v[120:121], v[120:121] op_sel:[0,1] op_sel_hi:[0,1] neg_hi:[0,1]
	v_pk_add_f32 v[122:123], v[122:123], v[122:123] op_sel:[0,1] op_sel_hi:[0,1] neg_hi:[0,1]
	v_pk_add_f32 v[124:125], v[124:125], v[124:125] op_sel:[0,1] op_sel_hi:[0,1] neg_hi:[0,1]
	v_pk_add_f32 v[126:127], v[126:127], v[126:127] op_sel:[0,1] op_sel_hi:[0,1] neg_hi:[0,1]
	v_pk_add_f32 v[128:129], v[128:129], v[128:129] op_sel:[0,1] op_sel_hi:[0,1] neg_hi:[0,1]
	v_pk_add_f32 v[130:131], v[130:131], v[130:131] op_sel:[0,1] op_sel_hi:[0,1] neg_hi:[0,1]
	v_pk_add_f32 v[132:133], v[100:101], v[102:103] neg_lo:[0,1] neg_hi:[0,1]
	v_pk_add_f32 v[100:101], v[100:101], v[102:103]
	v_pk_add_f32 v[134:135], v[104:105], v[106:107] neg_lo:[0,1] neg_hi:[0,1]
	v_pk_add_f32 v[104:105], v[104:105], v[106:107]
	v_pk_add_f32 v[136:137], v[108:109], v[110:111] neg_lo:[0,1] neg_hi:[0,1]
	v_pk_add_f32 v[108:109], v[108:109], v[110:111]
	v_pk_add_f32 v[138:139], v[112:113], v[114:115] neg_lo:[0,1] neg_hi:[0,1]
	v_pk_add_f32 v[112:113], v[112:113], v[114:115]
	v_pk_add_f32 v[140:141], v[116:117], v[118:119] neg_lo:[0,1] neg_hi:[0,1]
	v_pk_add_f32 v[116:117], v[116:117], v[118:119]
	v_pk_add_f32 v[142:143], v[120:121], v[122:123] neg_lo:[0,1] neg_hi:[0,1]
	v_pk_add_f32 v[120:121], v[120:121], v[122:123]
	v_pk_add_f32 v[102:103], v[124:125], v[126:127] neg_lo:[0,1] neg_hi:[0,1]
	v_pk_add_f32 v[124:125], v[124:125], v[126:127]
	v_pk_add_f32 v[106:107], v[128:129], v[130:131] neg_lo:[0,1] neg_hi:[0,1]
	v_pk_add_f32 v[128:129], v[128:129], v[130:131]
	v_pk_add_f32 v[110:111], v[100:101], v[104:105] neg_lo:[0,1] neg_hi:[0,1]
	v_pk_add_f32 v[100:101], v[100:101], v[104:105]
	v_pk_add_f32 v[114:115], v[132:133], v[134:135] neg_lo:[0,1] neg_hi:[0,1]
	v_pk_add_f32 v[132:133], v[132:133], v[134:135]
	v_pk_add_f32 v[118:119], v[108:109], v[112:113] neg_lo:[0,1] neg_hi:[0,1]
	v_pk_add_f32 v[108:109], v[108:109], v[112:113]
	v_pk_add_f32 v[122:123], v[136:137], v[138:139] neg_lo:[0,1] neg_hi:[0,1]
	v_pk_add_f32 v[136:137], v[136:137], v[138:139]
	v_pk_add_f32 v[126:127], v[116:117], v[120:121] neg_lo:[0,1] neg_hi:[0,1]
	v_pk_add_f32 v[116:117], v[116:117], v[120:121]
	v_pk_add_f32 v[130:131], v[140:141], v[142:143] neg_lo:[0,1] neg_hi:[0,1]
	v_pk_add_f32 v[140:141], v[140:141], v[142:143]
	v_pk_add_f32 v[104:105], v[124:125], v[128:129] neg_lo:[0,1] neg_hi:[0,1]
	v_pk_add_f32 v[124:125], v[124:125], v[128:129]
	v_pk_add_f32 v[134:135], v[102:103], v[106:107] neg_lo:[0,1] neg_hi:[0,1]
	v_pk_add_f32 v[102:103], v[102:103], v[106:107]
	v_pk_add_f32 v[112:113], v[100:101], v[108:109] neg_lo:[0,1] neg_hi:[0,1]
	v_pk_add_f32 v[100:101], v[100:101], v[108:109]
	v_pk_add_f32 v[138:139], v[132:133], v[136:137] neg_lo:[0,1] neg_hi:[0,1]
	v_pk_add_f32 v[132:133], v[132:133], v[136:137]
	v_pk_add_f32 v[120:121], v[110:111], v[118:119] neg_lo:[0,1] neg_hi:[0,1]
	v_pk_add_f32 v[110:111], v[110:111], v[118:119]
	v_pk_add_f32 v[142:143], v[114:115], v[122:123] neg_lo:[0,1] neg_hi:[0,1]
	v_pk_add_f32 v[114:115], v[114:115], v[122:123]
	v_pk_add_f32 v[128:129], v[116:117], v[124:125] neg_lo:[0,1] neg_hi:[0,1]
	v_pk_add_f32 v[116:117], v[116:117], v[124:125]
	v_pk_add_f32 v[106:107], v[140:141], v[102:103] neg_lo:[0,1] neg_hi:[0,1]
	v_pk_add_f32 v[140:141], v[140:141], v[102:103]
	v_pk_add_f32 v[108:109], v[126:127], v[104:105] neg_lo:[0,1] neg_hi:[0,1]
	v_pk_add_f32 v[126:127], v[126:127], v[104:105]
	v_pk_add_f32 v[136:137], v[130:131], v[134:135] neg_lo:[0,1] neg_hi:[0,1]
	v_pk_add_f32 v[130:131], v[130:131], v[134:135]
	v_pk_add_f32 v[118:119], v[100:101], v[116:117] neg_lo:[0,1] neg_hi:[0,1]
	v_pk_add_f32 v[100:101], v[100:101], v[116:117]
	v_pk_add_f32 v[122:123], v[132:133], v[140:141] neg_lo:[0,1] neg_hi:[0,1]
	v_pk_add_f32 v[132:133], v[132:133], v[140:141]
	v_pk_add_f32 v[124:125], v[110:111], v[126:127] neg_lo:[0,1] neg_hi:[0,1]
	v_pk_add_f32 v[110:111], v[110:111], v[126:127]
	v_pk_add_f32 v[102:103], v[114:115], v[130:131] neg_lo:[0,1] neg_hi:[0,1]
	v_pk_add_f32 v[114:115], v[114:115], v[130:131]
	v_pk_add_f32 v[104:105], v[112:113], v[128:129] neg_lo:[0,1] neg_hi:[0,1]
	v_pk_add_f32 v[112:113], v[112:113], v[128:129]
	v_pk_add_f32 v[134:135], v[138:139], v[106:107] neg_lo:[0,1] neg_hi:[0,1]
	v_pk_add_f32 v[138:139], v[138:139], v[106:107]
	v_pk_add_f32 v[116:117], v[120:121], v[108:109] neg_lo:[0,1] neg_hi:[0,1]
	v_pk_add_f32 v[120:121], v[120:121], v[108:109]
	v_pk_add_f32 v[140:141], v[142:143], v[136:137] neg_lo:[0,1] neg_hi:[0,1]
	v_pk_add_f32 v[142:143], v[142:143], v[136:137]
	v_pk_mul_f32 v[100:101], v[100:101], s[98:99]
	v_pk_mul_f32 v[100:101], v[100:101], v[174:175] op_sel_hi:[1,0]
	v_pk_add_f32 v[100:101], v[100:101], s[100:101]
	v_pk_mul_f32 v[132:133], v[132:133], s[98:99]
	v_pk_mul_f32 v[132:133], v[132:133], v[174:175] op_sel_hi:[1,0]
	v_pk_add_f32 v[132:133], v[132:133], s[100:101]
	v_pk_mul_f32 v[110:111], v[110:111], s[98:99]
	v_pk_mul_f32 v[110:111], v[110:111], v[174:175] op_sel_hi:[1,0]
	v_pk_add_f32 v[110:111], v[110:111], s[100:101]
	v_pk_mul_f32 v[114:115], v[114:115], s[98:99]
	v_pk_mul_f32 v[114:115], v[114:115], v[174:175] op_sel_hi:[1,0]
	v_pk_add_f32 v[114:115], v[114:115], s[100:101]
	v_pk_mul_f32 v[112:113], v[112:113], s[98:99]
	v_pk_mul_f32 v[112:113], v[112:113], v[174:175] op_sel_hi:[1,0]
	v_pk_add_f32 v[112:113], v[112:113], s[100:101]
	v_pk_mul_f32 v[138:139], v[138:139], s[98:99]
	v_pk_mul_f32 v[138:139], v[138:139], v[174:175] op_sel_hi:[1,0]
	v_pk_add_f32 v[138:139], v[138:139], s[100:101]
	v_pk_mul_f32 v[120:121], v[120:121], s[98:99]
	v_pk_mul_f32 v[120:121], v[120:121], v[174:175] op_sel_hi:[1,0]
	v_pk_add_f32 v[120:121], v[120:121], s[100:101]
	v_pk_mul_f32 v[142:143], v[142:143], s[98:99]
	v_pk_mul_f32 v[142:143], v[142:143], v[174:175] op_sel_hi:[1,0]
	v_pk_add_f32 v[142:143], v[142:143], s[100:101]
	v_pk_mul_f32 v[118:119], v[118:119], s[98:99]
	v_pk_mul_f32 v[118:119], v[118:119], v[174:175] op_sel_hi:[1,0]
	v_pk_add_f32 v[118:119], v[118:119], s[100:101]
	v_pk_mul_f32 v[122:123], v[122:123], s[98:99]
	v_pk_mul_f32 v[122:123], v[122:123], v[174:175] op_sel_hi:[1,0]
	v_pk_add_f32 v[122:123], v[122:123], s[100:101]
	v_pk_mul_f32 v[124:125], v[124:125], s[98:99]
	v_pk_mul_f32 v[124:125], v[124:125], v[174:175] op_sel_hi:[1,0]
	v_pk_add_f32 v[124:125], v[124:125], s[100:101]
	v_pk_mul_f32 v[102:103], v[102:103], s[98:99]
	v_pk_mul_f32 v[102:103], v[102:103], v[174:175] op_sel_hi:[1,0]
	v_pk_add_f32 v[102:103], v[102:103], s[100:101]
	v_pk_mul_f32 v[104:105], v[104:105], s[98:99]
	v_pk_mul_f32 v[104:105], v[104:105], v[174:175] op_sel_hi:[1,0]
	v_pk_add_f32 v[104:105], v[104:105], s[100:101]
	v_pk_mul_f32 v[134:135], v[134:135], s[98:99]
	v_pk_mul_f32 v[134:135], v[134:135], v[174:175] op_sel_hi:[1,0]
	v_pk_add_f32 v[134:135], v[134:135], s[100:101]
	v_pk_mul_f32 v[116:117], v[116:117], s[98:99]
	v_pk_mul_f32 v[116:117], v[116:117], v[174:175] op_sel_hi:[1,0]
	v_pk_add_f32 v[116:117], v[116:117], s[100:101]
	v_pk_mul_f32 v[140:141], v[140:141], s[98:99]
	v_pk_mul_f32 v[140:141], v[140:141], v[174:175] op_sel_hi:[1,0]
	v_pk_add_f32 v[140:141], v[140:141], s[100:101]
	v_perm_b32 v100, v101, v100, s12
	v_perm_b32 v132, v133, v132, s12
	v_perm_b32 v144, v132, v100, s13
	v_perm_b32 v110, v111, v110, s12
	v_perm_b32 v114, v115, v114, s12
	v_perm_b32 v145, v114, v110, s13
	v_perm_b32 v112, v113, v112, s12
	v_perm_b32 v138, v139, v138, s12
	v_perm_b32 v146, v138, v112, s13
	v_perm_b32 v120, v121, v120, s12
	v_perm_b32 v142, v143, v142, s12
	v_perm_b32 v147, v142, v120, s13
	v_perm_b32 v118, v119, v118, s12
	v_perm_b32 v122, v123, v122, s12
	v_perm_b32 v148, v122, v118, s13
	v_perm_b32 v124, v125, v124, s12
	v_perm_b32 v102, v103, v102, s12
	v_perm_b32 v149, v102, v124, s13
	v_perm_b32 v104, v105, v104, s12
	v_perm_b32 v134, v135, v134, s12
	v_perm_b32 v150, v134, v104, s13
	v_perm_b32 v116, v117, v116, s12
	v_perm_b32 v140, v141, v140, s12
	v_perm_b32 v151, v140, v116, s13
	global_store_dwordx4 v172, v[144:147], s[6:7] nt
	global_store_dwordx4 v172, v[148:151], s[6:7] offset:16 nt
	s_add_i32 s0, s0, 8
	s_cmp_ge_u32 s0, 172
	s_cbranch_scc1 .Lqa_done5
	s_waitcnt vmcnt(16)
	ds_write2_b32 v160, v68, v69 offset1:1
	ds_write2_b32 v160, v70, v71 offset0:2 offset1:3
	ds_write2_b32 v161, v72, v73 offset1:1
	ds_write2_b32 v161, v74, v75 offset0:2 offset1:3
	ds_write2_b32 v162, v76, v77 offset1:1
	ds_write2_b32 v162, v78, v79 offset0:2 offset1:3
	ds_write2_b32 v163, v80, v81 offset1:1
	ds_write2_b32 v163, v82, v83 offset0:2 offset1:3
	ds_write2_b32 v164, v84, v85 offset1:1
	ds_write2_b32 v164, v86, v87 offset0:2 offset1:3
	ds_write2_b32 v165, v88, v89 offset1:1
	ds_write2_b32 v165, v90, v91 offset0:2 offset1:3
	ds_write2_b32 v166, v92, v93 offset1:1
	ds_write2_b32 v166, v94, v95 offset0:2 offset1:3
	ds_write2_b32 v167, v96, v97 offset1:1
	ds_write2_b32 v167, v98, v99 offset0:2 offset1:3
	s_add_i32 s1, s0, 24
	s_cmp_lt_u32 s1, 172
	s_cselect_b32 s1, s1, s0
	s_lshl_b32 s10, s1, 20
	s_add_u32 s2, s4, s10
	s_addc_u32 s3, s5, 0
	global_load_dwordx4 v[68:71], v152, s[2:3]
	global_load_dwordx4 v[72:75], v153, s[2:3]
	global_load_dwordx4 v[76:79], v154, s[2:3]
	global_load_dwordx4 v[80:83], v155, s[2:3]
	global_load_dwordx4 v[84:87], v156, s[2:3]
	global_load_dwordx4 v[88:91], v157, s[2:3]
	global_load_dwordx4 v[92:95], v158, s[2:3]
	global_load_dwordx4 v[96:99], v159, s[2:3]
	ds_read2_b32 v[100:101], v168 offset1:33
	ds_read2_b32 v[102:103], v168 offset0:66 offset1:99
	ds_read2_b32 v[104:105], v168 offset0:132 offset1:165
	ds_read2_b32 v[106:107], v168 offset0:198 offset1:231
	ds_read2_b32 v[108:109], v169 offset1:33
	ds_read2_b32 v[110:111], v169 offset0:66 offset1:99
	ds_read2_b32 v[112:113], v169 offset0:132 offset1:165
	ds_read2_b32 v[114:115], v169 offset0:198 offset1:231
	ds_read2_b32 v[116:117], v170 offset1:33
	ds_read2_b32 v[118:119], v170 offset0:66 offset1:99
	ds_read2_b32 v[120:121], v170 offset0:132 offset1:165
	ds_read2_b32 v[122:123], v170 offset0:198 offset1:231
	ds_read2_b32 v[124:125], v171 offset1:33
	ds_read2_b32 v[126:127], v171 offset0:66 offset1:99
	ds_read2_b32 v[128:129], v171 offset0:132 offset1:165
	ds_read2_b32 v[130:131], v171 offset0:198 offset1:231
	s_lshl_b32 s10, s0, 6
	s_add_u32 s6, s8, s10
	s_addc_u32 s7, s9, 0
	s_waitcnt lgkmcnt(0)
	v_pk_add_f32 v[100:101], v[100:101], v[100:101] op_sel:[0,1] op_sel_hi:[0,1] neg_hi:[0,1]
	v_pk_add_f32 v[102:103], v[102:103], v[102:103] op_sel:[0,1] op_sel_hi:[0,1] neg_hi:[0,1]
	v_pk_add_f32 v[104:105], v[104:105], v[104:105] op_sel:[0,1] op_sel_hi:[0,1] neg_hi:[0,1]
	v_pk_add_f32 v[106:107], v[106:107], v[106:107] op_sel:[0,1] op_sel_hi:[0,1] neg_hi:[0,1]
	v_pk_add_f32 v[108:109], v[108:109], v[108:109] op_sel:[0,1] op_sel_hi:[0,1] neg_hi:[0,1]
	v_pk_add_f32 v[110:111], v[110:111], v[110:111] op_sel:[0,1] op_sel_hi:[0,1] neg_hi:[0,1]
	v_pk_add_f32 v[112:113], v[112:113], v[112:113] op_sel:[0,1] op_sel_hi:[0,1] neg_hi:[0,1]
	v_pk_add_f32 v[114:115], v[114:115], v[114:115] op_sel:[0,1] op_sel_hi:[0,1] neg_hi:[0,1]
	v_pk_add_f32 v[116:117], v[116:117], v[116:117] op_sel:[0,1] op_sel_hi:[0,1] neg_hi:[0,1]
	v_pk_add_f32 v[118:119], v[118:119], v[118:119] op_sel:[0,1] op_sel_hi:[0,1] neg_hi:[0,1]
	v_pk_add_f32 v[120:121], v[120:121], v[120:121] op_sel:[0,1] op_sel_hi:[0,1] neg_hi:[0,1]
	v_pk_add_f32 v[122:123], v[122:123], v[122:123] op_sel:[0,1] op_sel_hi:[0,1] neg_hi:[0,1]
	v_pk_add_f32 v[124:125], v[124:125], v[124:125] op_sel:[0,1] op_sel_hi:[0,1] neg_hi:[0,1]
	v_pk_add_f32 v[126:127], v[126:127], v[126:127] op_sel:[0,1] op_sel_hi:[0,1] neg_hi:[0,1]
	v_pk_add_f32 v[128:129], v[128:129], v[128:129] op_sel:[0,1] op_sel_hi:[0,1] neg_hi:[0,1]
	v_pk_add_f32 v[130:131], v[130:131], v[130:131] op_sel:[0,1] op_sel_hi:[0,1] neg_hi:[0,1]
	v_pk_add_f32 v[132:133], v[100:101], v[102:103] neg_lo:[0,1] neg_hi:[0,1]
	v_pk_add_f32 v[100:101], v[100:101], v[102:103]
	v_pk_add_f32 v[134:135], v[104:105], v[106:107] neg_lo:[0,1] neg_hi:[0,1]
	v_pk_add_f32 v[104:105], v[104:105], v[106:107]
	v_pk_add_f32 v[136:137], v[108:109], v[110:111] neg_lo:[0,1] neg_hi:[0,1]
	v_pk_add_f32 v[108:109], v[108:109], v[110:111]
	v_pk_add_f32 v[138:139], v[112:113], v[114:115] neg_lo:[0,1] neg_hi:[0,1]
	v_pk_add_f32 v[112:113], v[112:113], v[114:115]
	v_pk_add_f32 v[140:141], v[116:117], v[118:119] neg_lo:[0,1] neg_hi:[0,1]
	v_pk_add_f32 v[116:117], v[116:117], v[118:119]
	v_pk_add_f32 v[142:143], v[120:121], v[122:123] neg_lo:[0,1] neg_hi:[0,1]
	v_pk_add_f32 v[120:121], v[120:121], v[122:123]
	v_pk_add_f32 v[102:103], v[124:125], v[126:127] neg_lo:[0,1] neg_hi:[0,1]
	v_pk_add_f32 v[124:125], v[124:125], v[126:127]
	v_pk_add_f32 v[106:107], v[128:129], v[130:131] neg_lo:[0,1] neg_hi:[0,1]
	v_pk_add_f32 v[128:129], v[128:129], v[130:131]
	v_pk_add_f32 v[110:111], v[100:101], v[104:105] neg_lo:[0,1] neg_hi:[0,1]
	v_pk_add_f32 v[100:101], v[100:101], v[104:105]
	v_pk_add_f32 v[114:115], v[132:133], v[134:135] neg_lo:[0,1] neg_hi:[0,1]
	v_pk_add_f32 v[132:133], v[132:133], v[134:135]
	v_pk_add_f32 v[118:119], v[108:109], v[112:113] neg_lo:[0,1] neg_hi:[0,1]
	v_pk_add_f32 v[108:109], v[108:109], v[112:113]
	v_pk_add_f32 v[122:123], v[136:137], v[138:139] neg_lo:[0,1] neg_hi:[0,1]
	v_pk_add_f32 v[136:137], v[136:137], v[138:139]
	v_pk_add_f32 v[126:127], v[116:117], v[120:121] neg_lo:[0,1] neg_hi:[0,1]
	v_pk_add_f32 v[116:117], v[116:117], v[120:121]
	v_pk_add_f32 v[130:131], v[140:141], v[142:143] neg_lo:[0,1] neg_hi:[0,1]
	v_pk_add_f32 v[140:141], v[140:141], v[142:143]
	v_pk_add_f32 v[104:105], v[124:125], v[128:129] neg_lo:[0,1] neg_hi:[0,1]
	v_pk_add_f32 v[124:125], v[124:125], v[128:129]
	v_pk_add_f32 v[134:135], v[102:103], v[106:107] neg_lo:[0,1] neg_hi:[0,1]
	v_pk_add_f32 v[102:103], v[102:103], v[106:107]
	v_pk_add_f32 v[112:113], v[100:101], v[108:109] neg_lo:[0,1] neg_hi:[0,1]
	v_pk_add_f32 v[100:101], v[100:101], v[108:109]
	v_pk_add_f32 v[138:139], v[132:133], v[136:137] neg_lo:[0,1] neg_hi:[0,1]
	v_pk_add_f32 v[132:133], v[132:133], v[136:137]
	v_pk_add_f32 v[120:121], v[110:111], v[118:119] neg_lo:[0,1] neg_hi:[0,1]
	v_pk_add_f32 v[110:111], v[110:111], v[118:119]
	v_pk_add_f32 v[142:143], v[114:115], v[122:123] neg_lo:[0,1] neg_hi:[0,1]
	v_pk_add_f32 v[114:115], v[114:115], v[122:123]
	v_pk_add_f32 v[128:129], v[116:117], v[124:125] neg_lo:[0,1] neg_hi:[0,1]
	v_pk_add_f32 v[116:117], v[116:117], v[124:125]
	v_pk_add_f32 v[106:107], v[140:141], v[102:103] neg_lo:[0,1] neg_hi:[0,1]
	v_pk_add_f32 v[140:141], v[140:141], v[102:103]
	v_pk_add_f32 v[108:109], v[126:127], v[104:105] neg_lo:[0,1] neg_hi:[0,1]
	v_pk_add_f32 v[126:127], v[126:127], v[104:105]
	v_pk_add_f32 v[136:137], v[130:131], v[134:135] neg_lo:[0,1] neg_hi:[0,1]
	v_pk_add_f32 v[130:131], v[130:131], v[134:135]
	v_pk_add_f32 v[118:119], v[100:101], v[116:117] neg_lo:[0,1] neg_hi:[0,1]
	v_pk_add_f32 v[100:101], v[100:101], v[116:117]
	v_pk_add_f32 v[122:123], v[132:133], v[140:141] neg_lo:[0,1] neg_hi:[0,1]
	v_pk_add_f32 v[132:133], v[132:133], v[140:141]
	v_pk_add_f32 v[124:125], v[110:111], v[126:127] neg_lo:[0,1] neg_hi:[0,1]
	v_pk_add_f32 v[110:111], v[110:111], v[126:127]
	v_pk_add_f32 v[102:103], v[114:115], v[130:131] neg_lo:[0,1] neg_hi:[0,1]
	v_pk_add_f32 v[114:115], v[114:115], v[130:131]
	v_pk_add_f32 v[104:105], v[112:113], v[128:129] neg_lo:[0,1] neg_hi:[0,1]
	v_pk_add_f32 v[112:113], v[112:113], v[128:129]
	v_pk_add_f32 v[134:135], v[138:139], v[106:107] neg_lo:[0,1] neg_hi:[0,1]
	v_pk_add_f32 v[138:139], v[138:139], v[106:107]
	v_pk_add_f32 v[116:117], v[120:121], v[108:109] neg_lo:[0,1] neg_hi:[0,1]
	v_pk_add_f32 v[120:121], v[120:121], v[108:109]
	v_pk_add_f32 v[140:141], v[142:143], v[136:137] neg_lo:[0,1] neg_hi:[0,1]
	v_pk_add_f32 v[142:143], v[142:143], v[136:137]
	v_pk_mul_f32 v[100:101], v[100:101], s[98:99]
	v_pk_mul_f32 v[100:101], v[100:101], v[174:175] op_sel_hi:[1,0]
	v_pk_add_f32 v[100:101], v[100:101], s[100:101]
	v_pk_mul_f32 v[132:133], v[132:133], s[98:99]
	v_pk_mul_f32 v[132:133], v[132:133], v[174:175] op_sel_hi:[1,0]
	v_pk_add_f32 v[132:133], v[132:133], s[100:101]
	v_pk_mul_f32 v[110:111], v[110:111], s[98:99]
	v_pk_mul_f32 v[110:111], v[110:111], v[174:175] op_sel_hi:[1,0]
	v_pk_add_f32 v[110:111], v[110:111], s[100:101]
	v_pk_mul_f32 v[114:115], v[114:115], s[98:99]
	v_pk_mul_f32 v[114:115], v[114:115], v[174:175] op_sel_hi:[1,0]
	v_pk_add_f32 v[114:115], v[114:115], s[100:101]
	v_pk_mul_f32 v[112:113], v[112:113], s[98:99]
	v_pk_mul_f32 v[112:113], v[112:113], v[174:175] op_sel_hi:[1,0]
	v_pk_add_f32 v[112:113], v[112:113], s[100:101]
	v_pk_mul_f32 v[138:139], v[138:139], s[98:99]
	v_pk_mul_f32 v[138:139], v[138:139], v[174:175] op_sel_hi:[1,0]
	v_pk_add_f32 v[138:139], v[138:139], s[100:101]
	v_pk_mul_f32 v[120:121], v[120:121], s[98:99]
	v_pk_mul_f32 v[120:121], v[120:121], v[174:175] op_sel_hi:[1,0]
	v_pk_add_f32 v[120:121], v[120:121], s[100:101]
	v_pk_mul_f32 v[142:143], v[142:143], s[98:99]
	v_pk_mul_f32 v[142:143], v[142:143], v[174:175] op_sel_hi:[1,0]
	v_pk_add_f32 v[142:143], v[142:143], s[100:101]
	v_pk_mul_f32 v[118:119], v[118:119], s[98:99]
	v_pk_mul_f32 v[118:119], v[118:119], v[174:175] op_sel_hi:[1,0]
	v_pk_add_f32 v[118:119], v[118:119], s[100:101]
	v_pk_mul_f32 v[122:123], v[122:123], s[98:99]
	v_pk_mul_f32 v[122:123], v[122:123], v[174:175] op_sel_hi:[1,0]
	v_pk_add_f32 v[122:123], v[122:123], s[100:101]
	v_pk_mul_f32 v[124:125], v[124:125], s[98:99]
	v_pk_mul_f32 v[124:125], v[124:125], v[174:175] op_sel_hi:[1,0]
	v_pk_add_f32 v[124:125], v[124:125], s[100:101]
	v_pk_mul_f32 v[102:103], v[102:103], s[98:99]
	v_pk_mul_f32 v[102:103], v[102:103], v[174:175] op_sel_hi:[1,0]
	v_pk_add_f32 v[102:103], v[102:103], s[100:101]
	v_pk_mul_f32 v[104:105], v[104:105], s[98:99]
	v_pk_mul_f32 v[104:105], v[104:105], v[174:175] op_sel_hi:[1,0]
	v_pk_add_f32 v[104:105], v[104:105], s[100:101]
	v_pk_mul_f32 v[134:135], v[134:135], s[98:99]
	v_pk_mul_f32 v[134:135], v[134:135], v[174:175] op_sel_hi:[1,0]
	v_pk_add_f32 v[134:135], v[134:135], s[100:101]
	v_pk_mul_f32 v[116:117], v[116:117], s[98:99]
	v_pk_mul_f32 v[116:117], v[116:117], v[174:175] op_sel_hi:[1,0]
	v_pk_add_f32 v[116:117], v[116:117], s[100:101]
	v_pk_mul_f32 v[140:141], v[140:141], s[98:99]
	v_pk_mul_f32 v[140:141], v[140:141], v[174:175] op_sel_hi:[1,0]
	v_pk_add_f32 v[140:141], v[140:141], s[100:101]
	v_perm_b32 v100, v101, v100, s12
	v_perm_b32 v132, v133, v132, s12
	v_perm_b32 v144, v132, v100, s13
	v_perm_b32 v110, v111, v110, s12
	v_perm_b32 v114, v115, v114, s12
	v_perm_b32 v145, v114, v110, s13
	v_perm_b32 v112, v113, v112, s12
	v_perm_b32 v138, v139, v138, s12
	v_perm_b32 v146, v138, v112, s13
	v_perm_b32 v120, v121, v120, s12
	v_perm_b32 v142, v143, v142, s12
	v_perm_b32 v147, v142, v120, s13
	v_perm_b32 v118, v119, v118, s12
	v_perm_b32 v122, v123, v122, s12
	v_perm_b32 v148, v122, v118, s13
	v_perm_b32 v124, v125, v124, s12
	v_perm_b32 v102, v103, v102, s12
	v_perm_b32 v149, v102, v124, s13
	v_perm_b32 v104, v105, v104, s12
	v_perm_b32 v134, v135, v134, s12
	v_perm_b32 v150, v134, v104, s13
	v_perm_b32 v116, v117, v116, s12
	v_perm_b32 v140, v141, v140, s12
	v_perm_b32 v151, v140, v116, s13
	global_store_dwordx4 v172, v[144:147], s[6:7] nt
	global_store_dwordx4 v172, v[148:151], s[6:7] offset:16 nt
	s_add_i32 s0, s0, 8
	s_cmp_ge_u32 s0, 172
	s_cbranch_scc1 .Lqa_done5
	s_branch .Lqa_loop4
.Lqa_done5:
	s_waitcnt vmcnt(0)
	s_barrier
.LBB0_946:
	s_cmp_lt_i32 s59, 9
	s_cbranch_scc1 .LBB0_1000
	s_waitcnt vmcnt(0)
	s_waitcnt vmcnt(0) lgkmcnt(0)
	s_barrier
	s_mov_b64 s[0:1], exec
	v_readlane_b32 s2, v254, 4
	v_readlane_b32 s3, v254, 5
	s_and_b64 s[2:3], s[0:1], s[2:3]
	s_mov_b64 exec, s[2:3]
	s_cbranch_execz .LBB0_999
	s_add_i32 s2, 0, 0x20160
	v_mov_b32_e32 v1, s2
	s_waitcnt vmcnt(0) expcnt(0) lgkmcnt(0)
	ds_read_b32 v3, v1
	s_add_i32 s2, 0, 0x20164
	v_mov_b32_e32 v1, s2
	ds_read_b32 v1, v1
	s_waitcnt lgkmcnt(1)
	v_cmp_ne_u32_e32 vcc, 0, v3
	s_cbranch_vccnz .LBB0_963
	v_readlane_b32 s2, v254, 0
	v_readlane_b32 s3, v254, 1
	s_load_dwordx2 s[6:7], s[2:3], 0x4
	s_add_u32 s2, s54, 0x4200
	s_addc_u32 s3, s55, 0
	s_add_u32 s4, s54, 0x4400
	s_addc_u32 s5, s55, 0
	s_waitcnt lgkmcnt(0)
	s_mul_i32 s12, s6, s94
	s_add_u32 s6, s54, 0x4500
	s_mul_i32 s12, s12, s7
	s_addc_u32 s7, s55, 0
	s_add_u32 s8, s54, 0x4600
	s_addc_u32 s9, s55, 0
	s_add_u32 s10, s54, 0x4700
	s_addc_u32 s11, s55, 0
	s_add_u32 s22, s54, 0x4800
	s_addc_u32 s23, s55, 0
	s_add_u32 s24, s54, 0x4900
	s_addc_u32 s25, s55, 0
	s_add_u32 s26, s54, 0x4a00
	s_addc_u32 s27, s55, 0
	s_add_u32 s28, s54, 0x4b00
	s_addc_u32 s29, s55, 0
	s_add_u32 s30, s54, 0x4c00
	s_addc_u32 s31, s55, 0
	s_add_u32 s36, s54, 0x4d00
	s_addc_u32 s37, s55, 0
	s_add_u32 s38, s54, 0x4e00
	s_addc_u32 s39, s55, 0
	s_add_u32 s40, s54, 0x4f00
	s_addc_u32 s41, s55, 0
	s_add_u32 s42, s54, 0x5000
	s_addc_u32 s43, s55, 0
	s_add_u32 s44, s54, 0x5100
	s_addc_u32 s45, s55, 0
	s_add_u32 s46, s54, 0x5200
	s_addc_u32 s47, s55, 0
	s_add_u32 s48, s54, 0x5300
	s_addc_u32 s49, s55, 0
	s_mov_b32 s13, 1
	v_mov_b32_e32 v17, 0
	s_branch .LBB0_951

	.amdhsa_kernel _Z10fwd_kernel4Args
		.amdhsa_group_segment_fixed_size 0
		.amdhsa_private_segment_fixed_size 0
		.amdhsa_kernarg_size 408
		.amdhsa_user_sgpr_count 2
		.amdhsa_user_sgpr_dispatch_ptr 0
		.amdhsa_user_sgpr_queue_ptr 0
		.amdhsa_user_sgpr_kernarg_segment_ptr 1
		.amdhsa_user_sgpr_dispatch_id 0
		.amdhsa_user_sgpr_kernarg_preload_length 0
		.amdhsa_user_sgpr_kernarg_preload_offset 0
		.amdhsa_user_sgpr_private_segment_size 0
		.amdhsa_uses_dynamic_stack 0
		.amdhsa_enable_private_segment 0
		.amdhsa_system_sgpr_workgroup_id_x 1
		.amdhsa_system_sgpr_workgroup_id_y 0
		.amdhsa_system_sgpr_workgroup_id_z 0
		.amdhsa_system_sgpr_workgroup_info 0
		.amdhsa_system_vgpr_workitem_id 0
		.amdhsa_next_free_vgpr 255
		.amdhsa_next_free_sgpr 102
		.amdhsa_accum_offset 256
		.amdhsa_reserve_vcc 1
		.amdhsa_float_round_mode_32 0
		.amdhsa_float_round_mode_16_64 0
		.amdhsa_float_denorm_mode_32 3
		.amdhsa_float_denorm_mode_16_64 3
		.amdhsa_dx10_clamp 1
		.amdhsa_ieee_mode 1
		.amdhsa_fp16_overflow 0
		.amdhsa_tg_split 0
		.amdhsa_exception_fp_ieee_invalid_op 0
		.amdhsa_exception_fp_denorm_src 0
		.amdhsa_exception_fp_ieee_div_zero 0
		.amdhsa_exception_fp_ieee_overflow 0
		.amdhsa_exception_fp_ieee_underflow 0
		.amdhsa_exception_fp_ieee_inexact 0
		.amdhsa_exception_int_div_zero 0
	.end_amdhsa_kernel

.Lfunc_end0:
	.size	_Z10fwd_kernel4Args, .Lfunc_end0-_Z10fwd_kernel4Args
	.set _Z10fwd_kernel4Args.num_vgpr, 255
	.set _Z10fwd_kernel4Args.num_agpr, 0
	.set _Z10fwd_kernel4Args.numbered_sgpr, 102
	.set _Z10fwd_kernel4Args.num_named_barrier, 0
	.set _Z10fwd_kernel4Args.private_seg_size, 0
	.set _Z10fwd_kernel4Args.uses_vcc, 1
	.set _Z10fwd_kernel4Args.uses_flat_scratch, 0
	.set _Z10fwd_kernel4Args.has_dyn_sized_stack, 0
	.set _Z10fwd_kernel4Args.has_recursion, 0
	.set _Z10fwd_kernel4Args.has_indirect_call, 0

amdhsa.kernels:
  - .agpr_count:     0
    .args:
      - .offset:         0
        .size:           152
        .value_kind:     by_value
      - .offset:         152
        .size:           4
        .value_kind:     hidden_block_count_x
      - .offset:         156
        .size:           4
        .value_kind:     hidden_block_count_y
      - .offset:         160
        .size:           4
        .value_kind:     hidden_block_count_z
      - .offset:         164
        .size:           2
        .value_kind:     hidden_group_size_x
      - .offset:         166
        .size:           2
        .value_kind:     hidden_group_size_y
      - .offset:         168
        .size:           2
        .value_kind:     hidden_group_size_z
      - .offset:         170
        .size:           2
        .value_kind:     hidden_remainder_x
      - .offset:         172
        .size:           2
        .value_kind:     hidden_remainder_y
      - .offset:         174
        .size:           2
        .value_kind:     hidden_remainder_z
      - .offset:         192
        .size:           8
        .value_kind:     hidden_global_offset_x
      - .offset:         200
        .size:           8
        .value_kind:     hidden_global_offset_y
      - .offset:         208
        .size:           8
        .value_kind:     hidden_global_offset_z
      - .offset:         216
        .size:           2
        .value_kind:     hidden_grid_dims
      - .offset:         272
        .size:           4
        .value_kind:     hidden_dynamic_lds_size
    .group_segment_fixed_size: 0
    .kernarg_segment_align: 8
    .kernarg_segment_size: 408
    .language:       OpenCL C
    .language_version:
      - 2
      - 0
    .max_flat_workgroup_size: 512
    .name:           _Z10fwd_kernel4Args
    .private_segment_fixed_size: 0
    .sgpr_count:     108
    .sgpr_spill_count: 13
    .symbol:         _Z10fwd_kernel4Args.kd
    .uniform_work_group_size: 1
    .uses_dynamic_stack: false
    .vgpr_count:     255
    .vgpr_spill_count: 0
    .wavefront_size: 64
